# K-loops: redundant second lgkmcnt(0) (after barrier+setprio) removed from every MFMA segment (56 sites), on top of previous edits
# speedup vs baseline: 1.0043x; 1.0043x over previous
.LBB0_153:
	ds_read_b128 v[0:3], v145
	ds_read_b128 v[4:7], v145 offset:1024
	ds_read_b128 v[8:11], v145 offset:2048
	ds_read_b128 v[12:15], v145 offset:3072
	ds_read_b128 v[16:19], v146
	ds_read_b128 v[20:23], v146 offset:1024
	ds_read_b128 v[24:27], v146 offset:2048
	ds_read_b128 v[28:31], v146 offset:3072
	s_ashr_i32 s37, s36, 31
	s_lshl_b64 s[46:47], s[36:37], 17
	s_add_u32 s46, s44, s46
	s_addc_u32 s47, s45, s47
	s_and_b64 s[48:49], s[4:5], exec
	s_cselect_b32 s59, s47, s53
	s_cselect_b32 s58, s46, s52
	s_ashr_i32 s35, s34, 31
	s_lshl_b64 s[48:49], s[34:35], 17
	s_add_u32 s48, s60, s48
	s_addc_u32 s49, s61, s49
	s_and_b64 s[56:57], s[4:5], exec
	s_cselect_b32 s57, s49, s55
	s_cselect_b32 s56, s48, s54
	s_add_u32 s80, s52, 0x10080
	s_addc_u32 s81, s53, 0
	s_add_i32 s83, s51, 0xc000
	v_lshl_add_u64 v[64:65], s[80:81], 0, v[128:129]
	s_mov_b32 m0, s83
	s_add_i32 s35, s51, 0xe000
	ds_read_b128 v[32:35], v147
	ds_read_b128 v[36:39], v147 offset:1024
	ds_read_b128 v[40:43], v147 offset:2048
	ds_read_b128 v[44:47], v147 offset:3072
	ds_read_b128 v[48:51], v147 offset:4096
	ds_read_b128 v[52:55], v147 offset:5120
	ds_read_b128 v[56:59], v147 offset:6144
	ds_read_b128 v[60:63], v147 offset:7168
	global_load_lds_dwordx4 v[64:65], off
	v_lshl_add_u64 v[64:65], s[80:81], 0, v[132:133]
	s_mov_b32 m0, s35
	s_nop 0
	global_load_lds_dwordx4 v[64:65], off
	s_waitcnt vmcnt(8)
	s_waitcnt lgkmcnt(0)
	s_barrier
	s_setprio 1
	v_mfma_f32_16x16x32_bf16 v[64:67], v[0:3], v[32:35], 0
	v_mfma_f32_16x16x32_bf16 v[68:71], v[8:11], v[32:35], 0
	v_mfma_f32_16x16x32_bf16 v[72:75], v[0:3], v[40:43], 0
	v_mfma_f32_16x16x32_bf16 v[76:79], v[8:11], v[40:43], 0
	v_mfma_f32_16x16x32_bf16 v[80:83], v[0:3], v[48:51], 0
	v_mfma_f32_16x16x32_bf16 v[84:87], v[8:11], v[48:51], 0
	v_mfma_f32_16x16x32_bf16 v[88:91], v[0:3], v[56:59], 0
	v_mfma_f32_16x16x32_bf16 v[92:95], v[8:11], v[56:59], 0
	v_mfma_f32_16x16x32_bf16 v[64:67], v[4:7], v[36:39], v[64:67]
	v_mfma_f32_16x16x32_bf16 v[68:71], v[12:15], v[36:39], v[68:71]
	v_mfma_f32_16x16x32_bf16 v[72:75], v[4:7], v[44:47], v[72:75]
	v_mfma_f32_16x16x32_bf16 v[76:79], v[12:15], v[44:47], v[76:79]
	v_mfma_f32_16x16x32_bf16 v[80:83], v[4:7], v[52:55], v[80:83]
	v_mfma_f32_16x16x32_bf16 v[84:87], v[12:15], v[52:55], v[84:87]
	v_mfma_f32_16x16x32_bf16 v[88:91], v[4:7], v[60:63], v[88:91]
	v_mfma_f32_16x16x32_bf16 v[92:95], v[12:15], v[60:63], v[92:95]
	s_setprio 0
	s_setprio 1
	v_mfma_f32_16x16x32_bf16 v[96:99], v[16:19], v[32:35], 0
	v_mfma_f32_16x16x32_bf16 v[32:35], v[24:27], v[32:35], 0
	v_mfma_f32_16x16x32_bf16 v[96:99], v[20:23], v[36:39], v[96:99]
	v_mfma_f32_16x16x32_bf16 v[32:35], v[28:31], v[36:39], v[32:35]
	v_mfma_f32_16x16x32_bf16 v[36:39], v[16:19], v[40:43], 0
	v_mfma_f32_16x16x32_bf16 v[40:43], v[24:27], v[40:43], 0
	v_mfma_f32_16x16x32_bf16 v[36:39], v[20:23], v[44:47], v[36:39]
	v_mfma_f32_16x16x32_bf16 v[40:43], v[28:31], v[44:47], v[40:43]
	v_mfma_f32_16x16x32_bf16 v[44:47], v[16:19], v[48:51], 0
	v_mfma_f32_16x16x32_bf16 v[48:51], v[24:27], v[48:51], 0
	v_mfma_f32_16x16x32_bf16 v[44:47], v[20:23], v[52:55], v[44:47]
	v_mfma_f32_16x16x32_bf16 v[48:51], v[28:31], v[52:55], v[48:51]
	v_mfma_f32_16x16x32_bf16 v[52:55], v[16:19], v[56:59], 0
	v_mfma_f32_16x16x32_bf16 v[56:59], v[24:27], v[56:59], 0
	v_mfma_f32_16x16x32_bf16 v[52:55], v[20:23], v[60:63], v[52:55]
	v_mfma_f32_16x16x32_bf16 v[56:59], v[28:31], v[60:63], v[56:59]
	s_setprio 0
	s_barrier
	s_add_i32 s81, s72, s62
	v_lshl_add_u64 v[140:141], s[54:55], 0, v[130:131]
	s_add_i32 s37, s81, 0x2000
	v_lshl_add_u64 v[148:149], v[140:141], 0, s[18:19]
	s_mov_b32 m0, s81
	v_lshl_add_u64 v[212:213], s[54:55], 0, v[134:135]
	s_add_u32 s84, s54, 0x10100
	ds_read_b128 v[60:63], v147 offset:16384
	ds_read_b128 v[100:103], v147 offset:17408
	ds_read_b128 v[104:107], v147 offset:18432
	ds_read_b128 v[108:111], v147 offset:19456
	ds_read_b128 v[112:115], v147 offset:20480
	ds_read_b128 v[116:119], v147 offset:21504
	ds_read_b128 v[120:123], v147 offset:22528
	ds_read_b128 v[124:127], v147 offset:23552
	global_load_lds_dwordx4 v[148:149], off
	v_lshl_add_u64 v[148:149], v[212:213], 0, s[18:19]
	s_mov_b32 m0, s37
	s_addc_u32 s85, s55, 0
	s_add_i32 s79, s73, s62
	global_load_lds_dwordx4 v[148:149], off
	v_lshl_add_u64 v[148:149], s[84:85], 0, v[130:131]
	s_mov_b32 m0, s79
	s_add_i32 s80, s79, 0x2000
	global_load_lds_dwordx4 v[148:149], off
	v_lshl_add_u64 v[148:149], s[84:85], 0, v[134:135]
	s_mov_b32 m0, s80
	v_lshl_add_u64 v[214:215], s[52:53], 0, v[128:129]
	global_load_lds_dwordx4 v[148:149], off
	v_lshl_add_u64 v[148:149], v[214:215], 0, s[18:19]
	s_mov_b32 m0, s51
	v_lshl_add_u64 v[216:217], s[52:53], 0, v[132:133]
	global_load_lds_dwordx4 v[148:149], off
	v_lshl_add_u64 v[148:149], v[216:217], 0, s[18:19]
	s_mov_b32 m0, s63
	s_nop 0
	global_load_lds_dwordx4 v[148:149], off
	s_waitcnt vmcnt(8)
	s_waitcnt lgkmcnt(0)
	s_barrier
	s_setprio 1
	v_mfma_f32_16x16x32_bf16 v[148:151], v[0:3], v[60:63], 0
	v_mfma_f32_16x16x32_bf16 v[156:159], v[0:3], v[104:107], 0
	v_mfma_f32_16x16x32_bf16 v[164:167], v[0:3], v[112:115], 0
	v_mfma_f32_16x16x32_bf16 v[0:3], v[0:3], v[120:123], 0
	v_mfma_f32_16x16x32_bf16 v[148:151], v[4:7], v[100:103], v[148:151]
	v_mfma_f32_16x16x32_bf16 v[156:159], v[4:7], v[108:111], v[156:159]
	v_mfma_f32_16x16x32_bf16 v[164:167], v[4:7], v[116:119], v[164:167]
	v_mfma_f32_16x16x32_bf16 v[0:3], v[4:7], v[124:127], v[0:3]
	v_mfma_f32_16x16x32_bf16 v[4:7], v[8:11], v[120:123], 0
	v_mfma_f32_16x16x32_bf16 v[152:155], v[8:11], v[60:63], 0
	v_mfma_f32_16x16x32_bf16 v[160:163], v[8:11], v[104:107], 0
	v_mfma_f32_16x16x32_bf16 v[168:171], v[8:11], v[112:115], 0
	v_mfma_f32_16x16x32_bf16 v[4:7], v[12:15], v[124:127], v[4:7]
	v_mfma_f32_16x16x32_bf16 v[152:155], v[12:15], v[100:103], v[152:155]
	v_mfma_f32_16x16x32_bf16 v[160:163], v[12:15], v[108:111], v[160:163]
	v_mfma_f32_16x16x32_bf16 v[168:171], v[12:15], v[116:119], v[168:171]
	s_setprio 0
	s_setprio 1
	v_mfma_f32_16x16x32_bf16 v[8:11], v[16:19], v[60:63], 0
	v_mfma_f32_16x16x32_bf16 v[12:15], v[24:27], v[60:63], 0
	v_mfma_f32_16x16x32_bf16 v[8:11], v[20:23], v[100:103], v[8:11]
	v_mfma_f32_16x16x32_bf16 v[12:15], v[28:31], v[100:103], v[12:15]
	v_mfma_f32_16x16x32_bf16 v[60:63], v[16:19], v[104:107], 0
	v_mfma_f32_16x16x32_bf16 v[100:103], v[24:27], v[104:107], 0
	v_mfma_f32_16x16x32_bf16 v[104:107], v[16:19], v[112:115], 0
	v_mfma_f32_16x16x32_bf16 v[16:19], v[16:19], v[120:123], 0
	v_mfma_f32_16x16x32_bf16 v[60:63], v[20:23], v[108:111], v[60:63]
	v_mfma_f32_16x16x32_bf16 v[100:103], v[28:31], v[108:111], v[100:103]
	v_mfma_f32_16x16x32_bf16 v[104:107], v[20:23], v[116:119], v[104:107]
	v_mfma_f32_16x16x32_bf16 v[108:111], v[24:27], v[112:115], 0
	v_mfma_f32_16x16x32_bf16 v[16:19], v[20:23], v[124:127], v[16:19]
	v_mfma_f32_16x16x32_bf16 v[20:23], v[24:27], v[120:123], 0
	v_mfma_f32_16x16x32_bf16 v[108:111], v[28:31], v[116:119], v[108:111]
	v_mfma_f32_16x16x32_bf16 v[20:23], v[28:31], v[124:127], v[20:23]
	s_setprio 0
	s_barrier
	s_add_i32 s82, 0, 0x18000
	s_add_i32 s88, 0, 0x1c000
	v_add_u32_e32 v228, s82, v143
	v_add_u32_e32 v236, s88, v143
	ds_read_b128 v[24:27], v228
	ds_read_b128 v[28:31], v228 offset:1024
	ds_read_b128 v[112:115], v228 offset:2048
	ds_read_b128 v[116:119], v228 offset:3072
	ds_read_b128 v[120:123], v236
	ds_read_b128 v[124:127], v236 offset:1024
	ds_read_b128 v[172:175], v236 offset:2048
	ds_read_b128 v[176:179], v236 offset:3072
	s_add_u32 s84, s52, 0x10100
	s_addc_u32 s85, s53, 0
	s_mov_b32 m0, s64
	v_lshl_add_u64 v[218:219], s[84:85], 0, v[128:129]
	ds_read_b128 v[180:183], v147 offset:32768
	ds_read_b128 v[184:187], v147 offset:33792
	ds_read_b128 v[188:191], v147 offset:34816
	ds_read_b128 v[192:195], v147 offset:35840
	ds_read_b128 v[196:199], v147 offset:36864
	ds_read_b128 v[200:203], v147 offset:37888
	ds_read_b128 v[204:207], v147 offset:38912
	ds_read_b128 v[208:211], v147 offset:39936
	global_load_lds_dwordx4 v[218:219], off
	v_lshl_add_u64 v[218:219], s[84:85], 0, v[132:133]
	s_mov_b32 m0, s65
	s_nop 0
	global_load_lds_dwordx4 v[218:219], off
	s_waitcnt vmcnt(8)
	s_waitcnt lgkmcnt(0)
	s_barrier
	s_setprio 1
	v_mfma_f32_16x16x32_bf16 v[64:67], v[24:27], v[180:183], v[64:67]
	v_mfma_f32_16x16x32_bf16 v[68:71], v[112:115], v[180:183], v[68:71]
	v_mfma_f32_16x16x32_bf16 v[72:75], v[24:27], v[188:191], v[72:75]
	v_mfma_f32_16x16x32_bf16 v[76:79], v[112:115], v[188:191], v[76:79]
	v_mfma_f32_16x16x32_bf16 v[80:83], v[24:27], v[196:199], v[80:83]
	v_mfma_f32_16x16x32_bf16 v[84:87], v[112:115], v[196:199], v[84:87]
	v_mfma_f32_16x16x32_bf16 v[88:91], v[24:27], v[204:207], v[88:91]
	v_mfma_f32_16x16x32_bf16 v[92:95], v[112:115], v[204:207], v[92:95]
	v_mfma_f32_16x16x32_bf16 v[64:67], v[28:31], v[184:187], v[64:67]
	v_mfma_f32_16x16x32_bf16 v[68:71], v[116:119], v[184:187], v[68:71]
	v_mfma_f32_16x16x32_bf16 v[72:75], v[28:31], v[192:195], v[72:75]
	v_mfma_f32_16x16x32_bf16 v[76:79], v[116:119], v[192:195], v[76:79]
	v_mfma_f32_16x16x32_bf16 v[80:83], v[28:31], v[200:203], v[80:83]
	v_mfma_f32_16x16x32_bf16 v[84:87], v[116:119], v[200:203], v[84:87]
	v_mfma_f32_16x16x32_bf16 v[88:91], v[28:31], v[208:211], v[88:91]
	v_mfma_f32_16x16x32_bf16 v[92:95], v[116:119], v[208:211], v[92:95]
	s_setprio 0
	s_setprio 1
	v_mfma_f32_16x16x32_bf16 v[96:99], v[120:123], v[180:183], v[96:99]
	v_mfma_f32_16x16x32_bf16 v[32:35], v[172:175], v[180:183], v[32:35]
	v_mfma_f32_16x16x32_bf16 v[36:39], v[120:123], v[188:191], v[36:39]
	v_mfma_f32_16x16x32_bf16 v[40:43], v[172:175], v[188:191], v[40:43]
	v_mfma_f32_16x16x32_bf16 v[44:47], v[120:123], v[196:199], v[44:47]
	v_mfma_f32_16x16x32_bf16 v[48:51], v[172:175], v[196:199], v[48:51]
	v_mfma_f32_16x16x32_bf16 v[52:55], v[120:123], v[204:207], v[52:55]
	v_mfma_f32_16x16x32_bf16 v[56:59], v[172:175], v[204:207], v[56:59]
	v_mfma_f32_16x16x32_bf16 v[96:99], v[124:127], v[184:187], v[96:99]
	v_mfma_f32_16x16x32_bf16 v[32:35], v[176:179], v[184:187], v[32:35]
	v_mfma_f32_16x16x32_bf16 v[36:39], v[124:127], v[192:195], v[36:39]
	v_mfma_f32_16x16x32_bf16 v[40:43], v[176:179], v[192:195], v[40:43]
	v_mfma_f32_16x16x32_bf16 v[44:47], v[124:127], v[200:203], v[44:47]
	v_mfma_f32_16x16x32_bf16 v[48:51], v[176:179], v[200:203], v[48:51]
	v_mfma_f32_16x16x32_bf16 v[52:55], v[124:127], v[208:211], v[52:55]
	v_mfma_f32_16x16x32_bf16 v[56:59], v[176:179], v[208:211], v[56:59]
	s_setprio 0
	s_barrier
	s_add_i32 s84, s82, s62
	s_add_i32 s82, s84, 0x2000
	v_lshl_add_u64 v[140:141], v[140:141], 0, s[20:21]
	s_mov_b32 m0, s84
	s_add_u32 s86, s54, 0x10180
	ds_read_b128 v[180:183], v147 offset:49152
	ds_read_b128 v[184:187], v147 offset:50176
	ds_read_b128 v[188:191], v147 offset:51200
	ds_read_b128 v[192:195], v147 offset:52224
	ds_read_b128 v[196:199], v147 offset:53248
	ds_read_b128 v[200:203], v147 offset:54272
	ds_read_b128 v[204:207], v147 offset:55296
	ds_read_b128 v[208:211], v147 offset:56320
	global_load_lds_dwordx4 v[140:141], off
	v_lshl_add_u64 v[140:141], v[212:213], 0, s[20:21]
	s_mov_b32 m0, s82
	s_addc_u32 s87, s55, 0
	s_add_i32 s54, s88, s62
	global_load_lds_dwordx4 v[140:141], off
	v_lshl_add_u64 v[140:141], s[86:87], 0, v[130:131]
	s_mov_b32 m0, s54
	s_add_i32 s55, s54, 0x2000
	global_load_lds_dwordx4 v[140:141], off
	v_lshl_add_u64 v[140:141], s[86:87], 0, v[134:135]
	s_mov_b32 m0, s55
	s_nop 0
	global_load_lds_dwordx4 v[140:141], off
	v_lshl_add_u64 v[140:141], v[214:215], 0, s[20:21]
	s_mov_b32 m0, s66
	s_nop 0
	global_load_lds_dwordx4 v[140:141], off
	v_lshl_add_u64 v[140:141], v[216:217], 0, s[20:21]
	s_mov_b32 m0, s67
	s_nop 0
	global_load_lds_dwordx4 v[140:141], off
	s_waitcnt vmcnt(8)
	s_waitcnt lgkmcnt(0)
	s_barrier
	s_setprio 1
	v_mfma_f32_16x16x32_bf16 v[0:3], v[24:27], v[204:207], v[0:3]
	v_mfma_f32_16x16x32_bf16 v[4:7], v[112:115], v[204:207], v[4:7]
	v_mfma_f32_16x16x32_bf16 v[148:151], v[24:27], v[180:183], v[148:151]
	v_mfma_f32_16x16x32_bf16 v[152:155], v[112:115], v[180:183], v[152:155]
	v_mfma_f32_16x16x32_bf16 v[156:159], v[24:27], v[188:191], v[156:159]
	v_mfma_f32_16x16x32_bf16 v[160:163], v[112:115], v[188:191], v[160:163]
	v_mfma_f32_16x16x32_bf16 v[164:167], v[24:27], v[196:199], v[164:167]
	v_mfma_f32_16x16x32_bf16 v[168:171], v[112:115], v[196:199], v[168:171]
	v_mfma_f32_16x16x32_bf16 v[0:3], v[28:31], v[208:211], v[0:3]
	v_mfma_f32_16x16x32_bf16 v[4:7], v[116:119], v[208:211], v[4:7]
	v_mfma_f32_16x16x32_bf16 v[148:151], v[28:31], v[184:187], v[148:151]
	v_mfma_f32_16x16x32_bf16 v[152:155], v[116:119], v[184:187], v[152:155]
	v_mfma_f32_16x16x32_bf16 v[156:159], v[28:31], v[192:195], v[156:159]
	v_mfma_f32_16x16x32_bf16 v[160:163], v[116:119], v[192:195], v[160:163]
	v_mfma_f32_16x16x32_bf16 v[164:167], v[28:31], v[200:203], v[164:167]
	v_mfma_f32_16x16x32_bf16 v[168:171], v[116:119], v[200:203], v[168:171]
	s_setprio 0
	s_setprio 1
	v_mfma_f32_16x16x32_bf16 v[8:11], v[120:123], v[180:183], v[8:11]
	v_mfma_f32_16x16x32_bf16 v[12:15], v[172:175], v[180:183], v[12:15]
	v_mfma_f32_16x16x32_bf16 v[24:27], v[120:123], v[188:191], v[60:63]
	v_mfma_f32_16x16x32_bf16 v[28:31], v[172:175], v[188:191], v[100:103]
	v_mfma_f32_16x16x32_bf16 v[60:63], v[120:123], v[196:199], v[104:107]
	v_mfma_f32_16x16x32_bf16 v[100:103], v[172:175], v[196:199], v[108:111]
	v_mfma_f32_16x16x32_bf16 v[16:19], v[120:123], v[204:207], v[16:19]
	v_mfma_f32_16x16x32_bf16 v[20:23], v[172:175], v[204:207], v[20:23]
	v_mfma_f32_16x16x32_bf16 v[8:11], v[124:127], v[184:187], v[8:11]
	v_mfma_f32_16x16x32_bf16 v[12:15], v[176:179], v[184:187], v[12:15]
	v_mfma_f32_16x16x32_bf16 v[24:27], v[124:127], v[192:195], v[24:27]
	v_mfma_f32_16x16x32_bf16 v[28:31], v[176:179], v[192:195], v[28:31]
	v_mfma_f32_16x16x32_bf16 v[60:63], v[124:127], v[200:203], v[60:63]
	v_mfma_f32_16x16x32_bf16 v[100:103], v[176:179], v[200:203], v[100:103]
	v_mfma_f32_16x16x32_bf16 v[16:19], v[124:127], v[208:211], v[16:19]
	v_mfma_f32_16x16x32_bf16 v[20:23], v[176:179], v[208:211], v[20:23]
	s_setprio 0
	s_barrier
	ds_read_b128 v[104:107], v145
	ds_read_b128 v[108:111], v145 offset:1024
	ds_read_b128 v[112:115], v145 offset:2048
	ds_read_b128 v[116:119], v145 offset:3072
	ds_read_b128 v[120:123], v146
	ds_read_b128 v[124:127], v146 offset:1024
	ds_read_b128 v[172:175], v146 offset:2048
	ds_read_b128 v[176:179], v146 offset:3072
	s_add_u32 s52, s52, 0x10180
	s_addc_u32 s53, s53, 0
	s_mov_b32 m0, s83
	v_lshl_add_u64 v[140:141], s[52:53], 0, v[128:129]
	ds_read_b128 v[180:183], v147
	ds_read_b128 v[184:187], v147 offset:1024
	ds_read_b128 v[188:191], v147 offset:2048
	ds_read_b128 v[192:195], v147 offset:3072
	ds_read_b128 v[196:199], v147 offset:4096
	ds_read_b128 v[200:203], v147 offset:5120
	ds_read_b128 v[204:207], v147 offset:6144
	ds_read_b128 v[208:211], v147 offset:7168
	global_load_lds_dwordx4 v[140:141], off
	v_lshl_add_u64 v[140:141], s[52:53], 0, v[132:133]
	s_mov_b32 m0, s35
	s_nop 0
	global_load_lds_dwordx4 v[140:141], off
	s_waitcnt vmcnt(8)
	s_waitcnt lgkmcnt(0)
	s_barrier
	s_setprio 1
	v_mfma_f32_16x16x32_bf16 v[88:91], v[104:107], v[204:207], v[88:91]
	v_mfma_f32_16x16x32_bf16 v[64:67], v[104:107], v[180:183], v[64:67]
	v_mfma_f32_16x16x32_bf16 v[68:71], v[112:115], v[180:183], v[68:71]
	v_mfma_f32_16x16x32_bf16 v[72:75], v[104:107], v[188:191], v[72:75]
	v_mfma_f32_16x16x32_bf16 v[76:79], v[112:115], v[188:191], v[76:79]
	v_mfma_f32_16x16x32_bf16 v[80:83], v[104:107], v[196:199], v[80:83]
	v_mfma_f32_16x16x32_bf16 v[84:87], v[112:115], v[196:199], v[84:87]
	v_mfma_f32_16x16x32_bf16 v[212:215], v[108:111], v[208:211], v[88:91]
	v_mfma_f32_16x16x32_bf16 v[88:91], v[112:115], v[204:207], v[92:95]
	v_mfma_f32_16x16x32_bf16 v[64:67], v[108:111], v[184:187], v[64:67]
	v_mfma_f32_16x16x32_bf16 v[68:71], v[116:119], v[184:187], v[68:71]
	v_mfma_f32_16x16x32_bf16 v[72:75], v[108:111], v[192:195], v[72:75]
	v_mfma_f32_16x16x32_bf16 v[76:79], v[116:119], v[192:195], v[76:79]
	v_mfma_f32_16x16x32_bf16 v[80:83], v[108:111], v[200:203], v[80:83]
	v_mfma_f32_16x16x32_bf16 v[84:87], v[116:119], v[200:203], v[84:87]
	v_mfma_f32_16x16x32_bf16 v[92:95], v[116:119], v[208:211], v[88:91]
	s_setprio 0
	s_setprio 1
	v_mfma_f32_16x16x32_bf16 v[48:51], v[172:175], v[196:199], v[48:51]
	v_mfma_f32_16x16x32_bf16 v[88:91], v[120:123], v[180:183], v[96:99]
	v_mfma_f32_16x16x32_bf16 v[32:35], v[172:175], v[180:183], v[32:35]
	v_mfma_f32_16x16x32_bf16 v[36:39], v[120:123], v[188:191], v[36:39]
	v_mfma_f32_16x16x32_bf16 v[40:43], v[172:175], v[188:191], v[40:43]
	v_mfma_f32_16x16x32_bf16 v[44:47], v[120:123], v[196:199], v[44:47]
	v_mfma_f32_16x16x32_bf16 v[180:183], v[176:179], v[200:203], v[48:51]
	v_mfma_f32_16x16x32_bf16 v[48:51], v[120:123], v[204:207], v[52:55]
	v_mfma_f32_16x16x32_bf16 v[32:35], v[176:179], v[184:187], v[32:35]
	v_mfma_f32_16x16x32_bf16 v[36:39], v[124:127], v[192:195], v[36:39]
	v_mfma_f32_16x16x32_bf16 v[40:43], v[176:179], v[192:195], v[40:43]
	v_mfma_f32_16x16x32_bf16 v[44:47], v[124:127], v[200:203], v[44:47]
	v_mfma_f32_16x16x32_bf16 v[52:55], v[124:127], v[208:211], v[48:51]
	v_mfma_f32_16x16x32_bf16 v[48:51], v[172:175], v[204:207], v[56:59]
	v_mfma_f32_16x16x32_bf16 v[220:223], v[124:127], v[184:187], v[88:91]
	v_mfma_f32_16x16x32_bf16 v[184:187], v[176:179], v[208:211], v[48:51]
	s_setprio 0
	s_barrier
	s_mov_b32 m0, s81
	v_lshl_add_u64 v[140:141], s[56:57], 0, v[130:131]
	s_add_u32 s52, s56, 0x10000
	s_nop 0
	ds_read_b128 v[48:51], v147 offset:16384
	ds_read_b128 v[56:59], v147 offset:17408
	ds_read_b128 v[88:91], v147 offset:18432
	ds_read_b128 v[96:99], v147 offset:19456
	ds_read_b128 v[188:191], v147 offset:20480
	ds_read_b128 v[192:195], v147 offset:21504
	ds_read_b128 v[196:199], v147 offset:22528
	ds_read_b128 v[200:203], v147 offset:23552
	global_load_lds_dwordx4 v[140:141], off
	v_lshl_add_u64 v[252:253], s[56:57], 0, v[134:135]
	s_mov_b32 m0, s37
	s_addc_u32 s53, s57, 0
	global_load_lds_dwordx4 v[252:253], off
	v_lshl_add_u64 v[204:205], s[52:53], 0, v[130:131]
	s_mov_b32 m0, s79
	v_lshl_add_u64 v[136:137], s[58:59], 0, v[128:129]
	global_load_lds_dwordx4 v[204:205], off
	v_lshl_add_u64 v[204:205], s[52:53], 0, v[134:135]
	s_mov_b32 m0, s80
	v_lshl_add_u64 v[138:139], s[58:59], 0, v[132:133]
	global_load_lds_dwordx4 v[204:205], off
	s_mov_b32 m0, s51
	s_nop 0
	global_load_lds_dwordx4 v[136:137], off
	s_mov_b32 m0, s63
	s_nop 0
	global_load_lds_dwordx4 v[138:139], off
	s_waitcnt vmcnt(8)
	s_waitcnt lgkmcnt(0)
	s_barrier
	s_setprio 1
	v_mfma_f32_16x16x32_bf16 v[0:3], v[104:107], v[196:199], v[0:3]
	v_mfma_f32_16x16x32_bf16 v[4:7], v[112:115], v[196:199], v[4:7]
	v_mfma_f32_16x16x32_bf16 v[148:151], v[104:107], v[48:51], v[148:151]
	v_mfma_f32_16x16x32_bf16 v[152:155], v[112:115], v[48:51], v[152:155]
	v_mfma_f32_16x16x32_bf16 v[156:159], v[104:107], v[88:91], v[156:159]
	v_mfma_f32_16x16x32_bf16 v[160:163], v[112:115], v[88:91], v[160:163]
	v_mfma_f32_16x16x32_bf16 v[164:167], v[104:107], v[188:191], v[164:167]
	v_mfma_f32_16x16x32_bf16 v[168:171], v[112:115], v[188:191], v[168:171]
	v_mfma_f32_16x16x32_bf16 v[0:3], v[108:111], v[200:203], v[0:3]
	v_mfma_f32_16x16x32_bf16 v[4:7], v[116:119], v[200:203], v[4:7]
	v_mfma_f32_16x16x32_bf16 v[148:151], v[108:111], v[56:59], v[148:151]
	v_mfma_f32_16x16x32_bf16 v[152:155], v[116:119], v[56:59], v[152:155]
	v_mfma_f32_16x16x32_bf16 v[156:159], v[108:111], v[96:99], v[156:159]
	v_mfma_f32_16x16x32_bf16 v[160:163], v[116:119], v[96:99], v[160:163]
	v_mfma_f32_16x16x32_bf16 v[164:167], v[108:111], v[192:195], v[164:167]
	v_mfma_f32_16x16x32_bf16 v[168:171], v[116:119], v[192:195], v[168:171]
	s_setprio 0
	s_setprio 1
	v_mfma_f32_16x16x32_bf16 v[12:15], v[172:175], v[48:51], v[12:15]
	v_mfma_f32_16x16x32_bf16 v[204:207], v[176:179], v[56:59], v[12:15]
	v_mfma_f32_16x16x32_bf16 v[12:15], v[120:123], v[88:91], v[24:27]
	v_mfma_f32_16x16x32_bf16 v[24:27], v[124:127], v[96:99], v[12:15]
	v_mfma_f32_16x16x32_bf16 v[12:15], v[172:175], v[88:91], v[28:31]
	v_mfma_f32_16x16x32_bf16 v[208:211], v[176:179], v[96:99], v[12:15]
	v_mfma_f32_16x16x32_bf16 v[12:15], v[120:123], v[188:191], v[60:63]
	v_mfma_f32_16x16x32_bf16 v[224:227], v[124:127], v[192:195], v[12:15]
	v_mfma_f32_16x16x32_bf16 v[12:15], v[172:175], v[188:191], v[100:103]
	v_mfma_f32_16x16x32_bf16 v[8:11], v[120:123], v[48:51], v[8:11]
	v_mfma_f32_16x16x32_bf16 v[188:191], v[176:179], v[192:195], v[12:15]
	v_mfma_f32_16x16x32_bf16 v[12:15], v[120:123], v[196:199], v[16:19]
	v_mfma_f32_16x16x32_bf16 v[8:11], v[124:127], v[56:59], v[8:11]
	v_mfma_f32_16x16x32_bf16 v[192:195], v[124:127], v[200:203], v[12:15]
	v_mfma_f32_16x16x32_bf16 v[12:15], v[172:175], v[196:199], v[20:23]
	v_mfma_f32_16x16x32_bf16 v[172:175], v[176:179], v[200:203], v[12:15]
	s_setprio 0
	s_barrier
	s_nop 4
	ds_read_b128 v[12:15], v228
	ds_read_b128 v[16:19], v228 offset:1024
	ds_read_b128 v[176:179], v228 offset:2048
	ds_read_b128 v[196:199], v228 offset:3072
	ds_read_b128 v[200:203], v236
	ds_read_b128 v[228:231], v236 offset:1024
	ds_read_b128 v[232:235], v236 offset:2048
	ds_read_b128 v[236:239], v236 offset:3072
	s_add_u32 s52, s58, 0x10000
	s_addc_u32 s53, s59, 0
	s_mov_b32 m0, s64
	v_lshl_add_u64 v[48:49], s[52:53], 0, v[128:129]
	ds_read_b128 v[20:23], v147 offset:32768
	ds_read_b128 v[28:31], v147 offset:33792
	ds_read_b128 v[60:63], v147 offset:34816
	ds_read_b128 v[100:103], v147 offset:35840
	ds_read_b128 v[240:243], v147 offset:36864
	ds_read_b128 v[244:247], v147 offset:37888
	ds_read_b128 v[248:251], v147 offset:38912
	ds_read_b128 v[216:219], v147 offset:39936
	global_load_lds_dwordx4 v[48:49], off
	v_lshl_add_u64 v[48:49], s[52:53], 0, v[132:133]
	s_mov_b32 m0, s65
	s_nop 0
	global_load_lds_dwordx4 v[48:49], off
	s_waitcnt vmcnt(8)
	s_waitcnt lgkmcnt(0)
	s_barrier
	s_setprio 1
	v_mfma_f32_16x16x32_bf16 v[48:51], v[12:15], v[20:23], v[64:67]
	v_mfma_f32_16x16x32_bf16 v[120:123], v[16:19], v[28:31], v[48:51]
	v_mfma_f32_16x16x32_bf16 v[48:51], v[176:179], v[20:23], v[68:71]
	v_mfma_f32_16x16x32_bf16 v[112:115], v[196:199], v[28:31], v[48:51]
	v_mfma_f32_16x16x32_bf16 v[48:51], v[12:15], v[60:63], v[72:75]
	v_mfma_f32_16x16x32_bf16 v[104:107], v[16:19], v[100:103], v[48:51]
	v_mfma_f32_16x16x32_bf16 v[48:51], v[176:179], v[60:63], v[76:79]
	v_mfma_f32_16x16x32_bf16 v[96:99], v[196:199], v[100:103], v[48:51]
	v_mfma_f32_16x16x32_bf16 v[48:51], v[12:15], v[240:243], v[80:83]
	v_mfma_f32_16x16x32_bf16 v[88:91], v[16:19], v[244:247], v[48:51]
	v_mfma_f32_16x16x32_bf16 v[48:51], v[176:179], v[240:243], v[84:87]
	v_mfma_f32_16x16x32_bf16 v[80:83], v[196:199], v[244:247], v[48:51]
	v_mfma_f32_16x16x32_bf16 v[48:51], v[12:15], v[248:251], v[212:215]
	v_mfma_f32_16x16x32_bf16 v[56:59], v[16:19], v[216:219], v[48:51]
	v_mfma_f32_16x16x32_bf16 v[48:51], v[176:179], v[248:251], v[92:95]
	v_mfma_f32_16x16x32_bf16 v[48:51], v[196:199], v[216:219], v[48:51]
	s_setprio 0
	s_setprio 1
	v_mfma_f32_16x16x32_bf16 v[64:67], v[200:203], v[20:23], v[220:223]
	v_mfma_f32_16x16x32_bf16 v[20:23], v[232:235], v[20:23], v[32:35]
	v_mfma_f32_16x16x32_bf16 v[116:119], v[236:239], v[28:31], v[20:23]
	v_mfma_f32_16x16x32_bf16 v[20:23], v[200:203], v[60:63], v[36:39]
	v_mfma_f32_16x16x32_bf16 v[108:111], v[228:231], v[100:103], v[20:23]
	v_mfma_f32_16x16x32_bf16 v[20:23], v[232:235], v[60:63], v[40:43]
	v_mfma_f32_16x16x32_bf16 v[100:103], v[236:239], v[100:103], v[20:23]
	v_mfma_f32_16x16x32_bf16 v[20:23], v[200:203], v[240:243], v[44:47]
	v_mfma_f32_16x16x32_bf16 v[92:95], v[228:231], v[244:247], v[20:23]
	v_mfma_f32_16x16x32_bf16 v[20:23], v[232:235], v[240:243], v[180:183]
	v_mfma_f32_16x16x32_bf16 v[84:87], v[236:239], v[244:247], v[20:23]
	v_mfma_f32_16x16x32_bf16 v[20:23], v[200:203], v[248:251], v[52:55]
	v_mfma_f32_16x16x32_bf16 v[60:63], v[228:231], v[216:219], v[20:23]
	v_mfma_f32_16x16x32_bf16 v[20:23], v[232:235], v[248:251], v[184:187]
	v_mfma_f32_16x16x32_bf16 v[124:127], v[228:231], v[28:31], v[64:67]
	v_mfma_f32_16x16x32_bf16 v[52:55], v[236:239], v[216:219], v[20:23]
	s_setprio 0
	s_barrier
	s_mov_b32 m0, s84
	s_nop 2
	v_lshl_add_u64 v[20:21], v[140:141], 0, s[12:13]
	s_add_u32 s52, s56, 0x10080
	ds_read_b128 v[32:35], v147 offset:49152
	ds_read_b128 v[40:43], v147 offset:50176
	ds_read_b128 v[180:183], v147 offset:51200
	ds_read_b128 v[184:187], v147 offset:52224
	ds_read_b128 v[212:215], v147 offset:53248
	ds_read_b128 v[216:219], v147 offset:54272
	ds_read_b128 v[220:223], v147 offset:55296
	ds_read_b128 v[240:243], v147 offset:56320
	global_load_lds_dwordx4 v[20:21], off
	v_lshl_add_u64 v[20:21], v[252:253], 0, s[12:13]
	s_mov_b32 m0, s82
	s_addc_u32 s53, s57, 0
	global_load_lds_dwordx4 v[20:21], off
	v_lshl_add_u64 v[20:21], s[52:53], 0, v[130:131]
	s_mov_b32 m0, s54
	s_nop 0
	global_load_lds_dwordx4 v[20:21], off
	v_lshl_add_u64 v[20:21], s[52:53], 0, v[134:135]
	s_mov_b32 m0, s55
	s_nop 0
	global_load_lds_dwordx4 v[20:21], off
	v_lshl_add_u64 v[20:21], v[136:137], 0, s[12:13]
	s_mov_b32 m0, s66
	s_nop 0
	global_load_lds_dwordx4 v[20:21], off
	v_lshl_add_u64 v[20:21], v[138:139], 0, s[12:13]
	s_mov_b32 m0, s67
	s_nop 0
	global_load_lds_dwordx4 v[20:21], off
	s_waitcnt vmcnt(8)
	s_waitcnt lgkmcnt(0)
	s_barrier
	s_setprio 1
	v_mfma_f32_16x16x32_bf16 v[20:23], v[12:15], v[32:35], v[148:151]
	v_mfma_f32_16x16x32_bf16 v[76:79], v[16:19], v[40:43], v[20:23]
	v_mfma_f32_16x16x32_bf16 v[20:23], v[176:179], v[32:35], v[152:155]
	v_mfma_f32_16x16x32_bf16 v[68:71], v[196:199], v[40:43], v[20:23]
	v_mfma_f32_16x16x32_bf16 v[20:23], v[12:15], v[180:183], v[156:159]
	v_mfma_f32_16x16x32_bf16 v[44:47], v[16:19], v[184:187], v[20:23]
	v_mfma_f32_16x16x32_bf16 v[20:23], v[176:179], v[180:183], v[160:163]
	v_mfma_f32_16x16x32_bf16 v[36:39], v[196:199], v[184:187], v[20:23]
	v_mfma_f32_16x16x32_bf16 v[20:23], v[12:15], v[212:215], v[164:167]
	v_mfma_f32_16x16x32_bf16 v[0:3], v[12:15], v[220:223], v[0:3]
	v_mfma_f32_16x16x32_bf16 v[28:31], v[16:19], v[216:219], v[20:23]
	v_mfma_f32_16x16x32_bf16 v[20:23], v[176:179], v[212:215], v[168:171]
	v_mfma_f32_16x16x32_bf16 v[12:15], v[16:19], v[240:243], v[0:3]
	v_mfma_f32_16x16x32_bf16 v[0:3], v[176:179], v[220:223], v[4:7]
	v_mfma_f32_16x16x32_bf16 v[20:23], v[196:199], v[216:219], v[20:23]
	v_mfma_f32_16x16x32_bf16 v[4:7], v[196:199], v[240:243], v[0:3]
	s_setprio 0
	s_setprio 1
	v_mfma_f32_16x16x32_bf16 v[0:3], v[200:203], v[32:35], v[8:11]
	v_mfma_f32_16x16x32_bf16 v[72:75], v[228:231], v[40:43], v[0:3]
	v_mfma_f32_16x16x32_bf16 v[0:3], v[232:235], v[32:35], v[204:207]
	v_mfma_f32_16x16x32_bf16 v[64:67], v[236:239], v[40:43], v[0:3]
	v_mfma_f32_16x16x32_bf16 v[0:3], v[200:203], v[180:183], v[24:27]
	v_mfma_f32_16x16x32_bf16 v[40:43], v[228:231], v[184:187], v[0:3]
	v_mfma_f32_16x16x32_bf16 v[0:3], v[232:235], v[180:183], v[208:211]
	v_mfma_f32_16x16x32_bf16 v[32:35], v[236:239], v[184:187], v[0:3]
	v_mfma_f32_16x16x32_bf16 v[0:3], v[200:203], v[212:215], v[224:227]
	v_mfma_f32_16x16x32_bf16 v[24:27], v[228:231], v[216:219], v[0:3]
	v_mfma_f32_16x16x32_bf16 v[0:3], v[232:235], v[212:215], v[188:191]
	v_mfma_f32_16x16x32_bf16 v[16:19], v[236:239], v[216:219], v[0:3]
	v_mfma_f32_16x16x32_bf16 v[0:3], v[200:203], v[220:223], v[192:195]
	v_mfma_f32_16x16x32_bf16 v[8:11], v[228:231], v[240:243], v[0:3]
	v_mfma_f32_16x16x32_bf16 v[0:3], v[232:235], v[220:223], v[172:175]
	v_mfma_f32_16x16x32_bf16 v[0:3], v[236:239], v[240:243], v[0:3]
	s_setprio 0
	s_barrier
	s_andn2_b64 vcc, exec, s[14:15]
	s_cbranch_vccnz .LBB0_155
	s_barrier

.LBB0_178:
	ds_read_b128 v[148:151], v157
	ds_read_b128 v[162:165], v157 offset:1024
	ds_read_b128 v[166:169], v157 offset:2048
	ds_read_b128 v[170:173], v157 offset:3072
	ds_read_b128 v[174:177], v158
	ds_read_b128 v[178:181], v158 offset:1024
	ds_read_b128 v[182:185], v158 offset:2048
	ds_read_b128 v[186:189], v158 offset:3072
	s_add_u32 s48, s46, 0xfff80080
	s_addc_u32 s49, s47, -1
	s_cmp_eq_u32 s72, 28
	s_cselect_b32 s51, s31, s49
	s_cselect_b32 s50, s66, s48
	s_cselect_b32 s49, s27, s71
	s_cselect_b32 s48, s67, s70
	v_lshl_add_u64 v[152:153], s[46:47], 0, v[142:143]
	s_add_i32 m0, s13, 0xc000
	ds_read_b128 v[190:193], v159
	ds_read_b128 v[194:197], v159 offset:1024
	ds_read_b128 v[198:201], v159 offset:2048
	ds_read_b128 v[202:205], v159 offset:3072
	ds_read_b128 v[206:209], v159 offset:4096
	ds_read_b128 v[210:213], v159 offset:5120
	ds_read_b128 v[214:217], v159 offset:6144
	ds_read_b128 v[218:221], v159 offset:7168
	global_load_lds_dwordx4 v[152:153], off
	v_lshl_add_u64 v[152:153], s[46:47], 0, v[140:141]
	s_add_i32 m0, s13, 0xe000
	s_nop 0
	global_load_lds_dwordx4 v[152:153], off
	s_waitcnt vmcnt(8)
	s_waitcnt lgkmcnt(0)
	s_barrier
	s_setprio 1
	v_mfma_f32_16x16x32_bf16 v[124:127], v[148:151], v[190:193], v[124:127]
	v_mfma_f32_16x16x32_bf16 v[120:123], v[166:169], v[190:193], v[120:123]
	v_mfma_f32_16x16x32_bf16 v[108:111], v[148:151], v[198:201], v[108:111]
	v_mfma_f32_16x16x32_bf16 v[104:107], v[166:169], v[198:201], v[104:107]
	v_mfma_f32_16x16x32_bf16 v[92:95], v[148:151], v[206:209], v[92:95]
	v_mfma_f32_16x16x32_bf16 v[88:91], v[166:169], v[206:209], v[88:91]
	v_mfma_f32_16x16x32_bf16 v[76:79], v[148:151], v[214:217], v[76:79]
	v_mfma_f32_16x16x32_bf16 v[72:75], v[166:169], v[214:217], v[72:75]
	v_mfma_f32_16x16x32_bf16 v[124:127], v[162:165], v[194:197], v[124:127]
	v_mfma_f32_16x16x32_bf16 v[120:123], v[170:173], v[194:197], v[120:123]
	v_mfma_f32_16x16x32_bf16 v[108:111], v[162:165], v[202:205], v[108:111]
	v_mfma_f32_16x16x32_bf16 v[104:107], v[170:173], v[202:205], v[104:107]
	v_mfma_f32_16x16x32_bf16 v[92:95], v[162:165], v[210:213], v[92:95]
	v_mfma_f32_16x16x32_bf16 v[88:91], v[170:173], v[210:213], v[88:91]
	v_mfma_f32_16x16x32_bf16 v[76:79], v[162:165], v[218:221], v[76:79]
	v_mfma_f32_16x16x32_bf16 v[72:75], v[170:173], v[218:221], v[72:75]
	s_setprio 0
	s_setprio 1
	v_mfma_f32_16x16x32_bf16 v[116:119], v[174:177], v[190:193], v[116:119]
	v_mfma_f32_16x16x32_bf16 v[112:115], v[182:185], v[190:193], v[112:115]
	v_mfma_f32_16x16x32_bf16 v[100:103], v[174:177], v[198:201], v[100:103]
	v_mfma_f32_16x16x32_bf16 v[96:99], v[182:185], v[198:201], v[96:99]
	v_mfma_f32_16x16x32_bf16 v[84:87], v[174:177], v[206:209], v[84:87]
	v_mfma_f32_16x16x32_bf16 v[80:83], v[182:185], v[206:209], v[80:83]
	v_mfma_f32_16x16x32_bf16 v[68:71], v[174:177], v[214:217], v[68:71]
	v_mfma_f32_16x16x32_bf16 v[64:67], v[182:185], v[214:217], v[64:67]
	v_mfma_f32_16x16x32_bf16 v[116:119], v[178:181], v[194:197], v[116:119]
	v_mfma_f32_16x16x32_bf16 v[112:115], v[186:189], v[194:197], v[112:115]
	v_mfma_f32_16x16x32_bf16 v[100:103], v[178:181], v[202:205], v[100:103]
	v_mfma_f32_16x16x32_bf16 v[96:99], v[186:189], v[202:205], v[96:99]
	v_mfma_f32_16x16x32_bf16 v[84:87], v[178:181], v[210:213], v[84:87]
	v_mfma_f32_16x16x32_bf16 v[80:83], v[186:189], v[210:213], v[80:83]
	v_mfma_f32_16x16x32_bf16 v[68:71], v[178:181], v[218:221], v[68:71]
	v_mfma_f32_16x16x32_bf16 v[64:67], v[186:189], v[218:221], v[64:67]
	s_setprio 0
	s_barrier
	s_add_i32 s73, s62, s52
	v_lshl_add_u64 v[152:153], s[48:49], 0, v[130:131]
	s_mov_b32 m0, s73
	ds_read_b128 v[190:193], v159 offset:16384
	ds_read_b128 v[194:197], v159 offset:17408
	ds_read_b128 v[198:201], v159 offset:18432
	ds_read_b128 v[202:205], v159 offset:19456
	ds_read_b128 v[206:209], v159 offset:20480
	ds_read_b128 v[210:213], v159 offset:21504
	ds_read_b128 v[214:217], v159 offset:22528
	ds_read_b128 v[218:221], v159 offset:23552
	global_load_lds_dwordx4 v[152:153], off
	s_add_i32 m0, s73, 0x2000
	s_add_u32 s74, s48, 0x80000
	v_lshl_add_u64 v[222:223], s[48:49], 0, v[134:135]
	s_addc_u32 s75, s49, 0
	s_add_i32 s73, s63, s52
	global_load_lds_dwordx4 v[222:223], off
	v_lshl_add_u64 v[224:225], s[74:75], 0, v[130:131]
	s_mov_b32 m0, s73
	v_lshl_add_u64 v[226:227], s[50:51], 0, v[132:133]
	global_load_lds_dwordx4 v[224:225], off
	v_lshl_add_u64 v[224:225], s[74:75], 0, v[134:135]
	s_add_i32 m0, s73, 0x2000
	s_nop 0
	global_load_lds_dwordx4 v[224:225], off
	v_lshl_add_u64 v[224:225], s[50:51], 0, v[128:129]
	s_mov_b32 m0, s13
	s_nop 0
	global_load_lds_dwordx4 v[224:225], off
	s_mov_b32 m0, s53
	s_nop 0
	global_load_lds_dwordx4 v[226:227], off
	s_waitcnt vmcnt(8)
	s_waitcnt lgkmcnt(0)
	s_barrier
	s_setprio 1
	v_mfma_f32_16x16x32_bf16 v[60:63], v[148:151], v[190:193], v[60:63]
	v_mfma_f32_16x16x32_bf16 v[56:59], v[166:169], v[190:193], v[56:59]
	v_mfma_f32_16x16x32_bf16 v[44:47], v[148:151], v[198:201], v[44:47]
	v_mfma_f32_16x16x32_bf16 v[40:43], v[166:169], v[198:201], v[40:43]
	v_mfma_f32_16x16x32_bf16 v[28:31], v[148:151], v[206:209], v[28:31]
	v_mfma_f32_16x16x32_bf16 v[24:27], v[166:169], v[206:209], v[24:27]
	v_mfma_f32_16x16x32_bf16 v[12:15], v[148:151], v[214:217], v[12:15]
	v_mfma_f32_16x16x32_bf16 v[8:11], v[166:169], v[214:217], v[8:11]
	v_mfma_f32_16x16x32_bf16 v[60:63], v[162:165], v[194:197], v[60:63]
	v_mfma_f32_16x16x32_bf16 v[56:59], v[170:173], v[194:197], v[56:59]
	v_mfma_f32_16x16x32_bf16 v[44:47], v[162:165], v[202:205], v[44:47]
	v_mfma_f32_16x16x32_bf16 v[40:43], v[170:173], v[202:205], v[40:43]
	v_mfma_f32_16x16x32_bf16 v[28:31], v[162:165], v[210:213], v[28:31]
	v_mfma_f32_16x16x32_bf16 v[24:27], v[170:173], v[210:213], v[24:27]
	v_mfma_f32_16x16x32_bf16 v[12:15], v[162:165], v[218:221], v[12:15]
	v_mfma_f32_16x16x32_bf16 v[8:11], v[170:173], v[218:221], v[8:11]
	s_setprio 0
	s_setprio 1
	v_mfma_f32_16x16x32_bf16 v[52:55], v[174:177], v[190:193], v[52:55]
	v_mfma_f32_16x16x32_bf16 v[48:51], v[182:185], v[190:193], v[48:51]
	v_mfma_f32_16x16x32_bf16 v[36:39], v[174:177], v[198:201], v[36:39]
	v_mfma_f32_16x16x32_bf16 v[32:35], v[182:185], v[198:201], v[32:35]
	v_mfma_f32_16x16x32_bf16 v[20:23], v[174:177], v[206:209], v[20:23]
	v_mfma_f32_16x16x32_bf16 v[16:19], v[182:185], v[206:209], v[16:19]
	v_mfma_f32_16x16x32_bf16 v[4:7], v[174:177], v[214:217], v[4:7]
	v_mfma_f32_16x16x32_bf16 v[0:3], v[182:185], v[214:217], v[0:3]
	v_mfma_f32_16x16x32_bf16 v[52:55], v[178:181], v[194:197], v[52:55]
	v_mfma_f32_16x16x32_bf16 v[48:51], v[186:189], v[194:197], v[48:51]
	v_mfma_f32_16x16x32_bf16 v[36:39], v[178:181], v[202:205], v[36:39]
	v_mfma_f32_16x16x32_bf16 v[32:35], v[186:189], v[202:205], v[32:35]
	v_mfma_f32_16x16x32_bf16 v[20:23], v[178:181], v[210:213], v[20:23]
	v_mfma_f32_16x16x32_bf16 v[16:19], v[186:189], v[210:213], v[16:19]
	v_mfma_f32_16x16x32_bf16 v[4:7], v[178:181], v[218:221], v[4:7]
	v_mfma_f32_16x16x32_bf16 v[0:3], v[186:189], v[218:221], v[0:3]
	s_setprio 0
	s_barrier
	s_add_i32 s73, 0, 0x18000
	v_add_u32_e32 v137, s73, v155
	s_add_i32 s74, 0, 0x1c000
	ds_read_b128 v[148:151], v137
	ds_read_b128 v[162:165], v137 offset:1024
	ds_read_b128 v[166:169], v137 offset:2048
	ds_read_b128 v[170:173], v137 offset:3072
	v_add_u32_e32 v137, s74, v155
	ds_read_b128 v[174:177], v137
	ds_read_b128 v[178:181], v137 offset:1024
	ds_read_b128 v[182:185], v137 offset:2048
	ds_read_b128 v[186:189], v137 offset:3072
	s_add_u32 s50, s50, 0x80000
	s_addc_u32 s51, s51, 0
	s_mov_b32 m0, s54
	v_lshl_add_u64 v[228:229], s[50:51], 0, v[128:129]
	ds_read_b128 v[190:193], v159 offset:32768
	ds_read_b128 v[194:197], v159 offset:33792
	ds_read_b128 v[198:201], v159 offset:34816
	ds_read_b128 v[202:205], v159 offset:35840
	ds_read_b128 v[206:209], v159 offset:36864
	ds_read_b128 v[210:213], v159 offset:37888
	ds_read_b128 v[214:217], v159 offset:38912
	ds_read_b128 v[218:221], v159 offset:39936
	global_load_lds_dwordx4 v[228:229], off
	v_lshl_add_u64 v[228:229], s[50:51], 0, v[132:133]
	s_mov_b32 m0, s55
	s_nop 0
	global_load_lds_dwordx4 v[228:229], off
	s_waitcnt vmcnt(8)
	s_waitcnt lgkmcnt(0)
	s_barrier
	s_setprio 1
	v_mfma_f32_16x16x32_bf16 v[124:127], v[148:151], v[190:193], v[124:127]
	v_mfma_f32_16x16x32_bf16 v[120:123], v[166:169], v[190:193], v[120:123]
	v_mfma_f32_16x16x32_bf16 v[108:111], v[148:151], v[198:201], v[108:111]
	v_mfma_f32_16x16x32_bf16 v[104:107], v[166:169], v[198:201], v[104:107]
	v_mfma_f32_16x16x32_bf16 v[92:95], v[148:151], v[206:209], v[92:95]
	v_mfma_f32_16x16x32_bf16 v[88:91], v[166:169], v[206:209], v[88:91]
	v_mfma_f32_16x16x32_bf16 v[76:79], v[148:151], v[214:217], v[76:79]
	v_mfma_f32_16x16x32_bf16 v[72:75], v[166:169], v[214:217], v[72:75]
	v_mfma_f32_16x16x32_bf16 v[124:127], v[162:165], v[194:197], v[124:127]
	v_mfma_f32_16x16x32_bf16 v[120:123], v[170:173], v[194:197], v[120:123]
	v_mfma_f32_16x16x32_bf16 v[108:111], v[162:165], v[202:205], v[108:111]
	v_mfma_f32_16x16x32_bf16 v[104:107], v[170:173], v[202:205], v[104:107]
	v_mfma_f32_16x16x32_bf16 v[92:95], v[162:165], v[210:213], v[92:95]
	v_mfma_f32_16x16x32_bf16 v[88:91], v[170:173], v[210:213], v[88:91]
	v_mfma_f32_16x16x32_bf16 v[76:79], v[162:165], v[218:221], v[76:79]
	v_mfma_f32_16x16x32_bf16 v[72:75], v[170:173], v[218:221], v[72:75]
	s_setprio 0
	s_setprio 1
	v_mfma_f32_16x16x32_bf16 v[116:119], v[174:177], v[190:193], v[116:119]
	v_mfma_f32_16x16x32_bf16 v[112:115], v[182:185], v[190:193], v[112:115]
	v_mfma_f32_16x16x32_bf16 v[100:103], v[174:177], v[198:201], v[100:103]
	v_mfma_f32_16x16x32_bf16 v[96:99], v[182:185], v[198:201], v[96:99]
	v_mfma_f32_16x16x32_bf16 v[84:87], v[174:177], v[206:209], v[84:87]
	v_mfma_f32_16x16x32_bf16 v[80:83], v[182:185], v[206:209], v[80:83]
	v_mfma_f32_16x16x32_bf16 v[68:71], v[174:177], v[214:217], v[68:71]
	v_mfma_f32_16x16x32_bf16 v[64:67], v[182:185], v[214:217], v[64:67]
	v_mfma_f32_16x16x32_bf16 v[116:119], v[178:181], v[194:197], v[116:119]
	v_mfma_f32_16x16x32_bf16 v[112:115], v[186:189], v[194:197], v[112:115]
	v_mfma_f32_16x16x32_bf16 v[100:103], v[178:181], v[202:205], v[100:103]
	v_mfma_f32_16x16x32_bf16 v[96:99], v[186:189], v[202:205], v[96:99]
	v_mfma_f32_16x16x32_bf16 v[84:87], v[178:181], v[210:213], v[84:87]
	v_mfma_f32_16x16x32_bf16 v[80:83], v[186:189], v[210:213], v[80:83]
	v_mfma_f32_16x16x32_bf16 v[68:71], v[178:181], v[218:221], v[68:71]
	v_mfma_f32_16x16x32_bf16 v[64:67], v[186:189], v[218:221], v[64:67]
	s_setprio 0
	s_barrier
	s_add_i32 s50, s73, s52
	v_lshl_add_u64 v[152:153], v[152:153], 0, s[22:23]
	s_mov_b32 m0, s50
	ds_read_b128 v[190:193], v159 offset:49152
	ds_read_b128 v[194:197], v159 offset:50176
	ds_read_b128 v[198:201], v159 offset:51200
	ds_read_b128 v[202:205], v159 offset:52224
	ds_read_b128 v[206:209], v159 offset:53248
	ds_read_b128 v[210:213], v159 offset:54272
	ds_read_b128 v[214:217], v159 offset:55296
	ds_read_b128 v[218:221], v159 offset:56320
	global_load_lds_dwordx4 v[152:153], off
	s_add_i32 m0, s50, 0x2000
	s_add_u32 s48, s48, 0x80080
	v_lshl_add_u64 v[152:153], v[222:223], 0, s[22:23]
	s_addc_u32 s49, s49, 0
	s_add_i32 s50, s74, s52
	global_load_lds_dwordx4 v[152:153], off
	v_lshl_add_u64 v[152:153], s[48:49], 0, v[130:131]
	s_mov_b32 m0, s50
	s_nop 0
	global_load_lds_dwordx4 v[152:153], off
	v_lshl_add_u64 v[152:153], s[48:49], 0, v[134:135]
	s_add_i32 m0, s50, 0x2000
	s_nop 0
	global_load_lds_dwordx4 v[152:153], off
	v_lshl_add_u64 v[152:153], v[224:225], 0, s[22:23]
	s_mov_b32 m0, s57
	s_nop 0
	global_load_lds_dwordx4 v[152:153], off
	v_lshl_add_u64 v[152:153], v[226:227], 0, s[22:23]
	s_mov_b32 m0, s58
	s_nop 0
	global_load_lds_dwordx4 v[152:153], off
	s_waitcnt vmcnt(8)
	s_waitcnt lgkmcnt(0)
	s_barrier
	s_setprio 1
	v_mfma_f32_16x16x32_bf16 v[60:63], v[148:151], v[190:193], v[60:63]
	v_mfma_f32_16x16x32_bf16 v[56:59], v[166:169], v[190:193], v[56:59]
	v_mfma_f32_16x16x32_bf16 v[44:47], v[148:151], v[198:201], v[44:47]
	v_mfma_f32_16x16x32_bf16 v[40:43], v[166:169], v[198:201], v[40:43]
	v_mfma_f32_16x16x32_bf16 v[28:31], v[148:151], v[206:209], v[28:31]
	v_mfma_f32_16x16x32_bf16 v[24:27], v[166:169], v[206:209], v[24:27]
	v_mfma_f32_16x16x32_bf16 v[12:15], v[148:151], v[214:217], v[12:15]
	v_mfma_f32_16x16x32_bf16 v[8:11], v[166:169], v[214:217], v[8:11]
	v_mfma_f32_16x16x32_bf16 v[60:63], v[162:165], v[194:197], v[60:63]
	v_mfma_f32_16x16x32_bf16 v[56:59], v[170:173], v[194:197], v[56:59]
	v_mfma_f32_16x16x32_bf16 v[44:47], v[162:165], v[202:205], v[44:47]
	v_mfma_f32_16x16x32_bf16 v[40:43], v[170:173], v[202:205], v[40:43]
	v_mfma_f32_16x16x32_bf16 v[28:31], v[162:165], v[210:213], v[28:31]
	v_mfma_f32_16x16x32_bf16 v[24:27], v[170:173], v[210:213], v[24:27]
	v_mfma_f32_16x16x32_bf16 v[12:15], v[162:165], v[218:221], v[12:15]
	v_mfma_f32_16x16x32_bf16 v[8:11], v[170:173], v[218:221], v[8:11]
	s_setprio 0
	s_setprio 1
	v_mfma_f32_16x16x32_bf16 v[52:55], v[174:177], v[190:193], v[52:55]
	v_mfma_f32_16x16x32_bf16 v[48:51], v[182:185], v[190:193], v[48:51]
	v_mfma_f32_16x16x32_bf16 v[36:39], v[174:177], v[198:201], v[36:39]
	v_mfma_f32_16x16x32_bf16 v[32:35], v[182:185], v[198:201], v[32:35]
	v_mfma_f32_16x16x32_bf16 v[20:23], v[174:177], v[206:209], v[20:23]
	v_mfma_f32_16x16x32_bf16 v[16:19], v[182:185], v[206:209], v[16:19]
	v_mfma_f32_16x16x32_bf16 v[4:7], v[174:177], v[214:217], v[4:7]
	v_mfma_f32_16x16x32_bf16 v[0:3], v[182:185], v[214:217], v[0:3]
	v_mfma_f32_16x16x32_bf16 v[52:55], v[178:181], v[194:197], v[52:55]
	v_mfma_f32_16x16x32_bf16 v[48:51], v[186:189], v[194:197], v[48:51]
	v_mfma_f32_16x16x32_bf16 v[36:39], v[178:181], v[202:205], v[36:39]
	v_mfma_f32_16x16x32_bf16 v[32:35], v[186:189], v[202:205], v[32:35]
	v_mfma_f32_16x16x32_bf16 v[20:23], v[178:181], v[210:213], v[20:23]
	v_mfma_f32_16x16x32_bf16 v[16:19], v[186:189], v[210:213], v[16:19]
	v_mfma_f32_16x16x32_bf16 v[4:7], v[178:181], v[218:221], v[4:7]
	v_mfma_f32_16x16x32_bf16 v[0:3], v[186:189], v[218:221], v[0:3]
	s_setprio 0
	s_barrier
	s_add_i32 s72, s72, 2
	s_add_u32 s70, s70, 0x100
	s_addc_u32 s71, s71, 0
	s_add_u32 s46, s46, 0x100
	s_addc_u32 s47, s47, 0
	s_cmp_gt_u32 s72, 29
	s_cbranch_scc0 .LBB0_178
	s_and_b64 vcc, exec, s[24:25]
	s_cbranch_vccz .LBB0_181
	s_barrier

.LBB0_337:
	ds_read_b128 v[144:147], v151
	ds_read_b128 v[156:159], v151 offset:1024
	ds_read_b128 v[160:163], v151 offset:2048
	ds_read_b128 v[164:167], v151 offset:3072
	ds_read_b128 v[168:171], v152
	ds_read_b128 v[172:175], v152 offset:1024
	ds_read_b128 v[176:179], v152 offset:2048
	ds_read_b128 v[180:183], v152 offset:3072
	s_add_u32 s50, s48, 0xfff80080
	s_addc_u32 s51, s49, -1
	s_cmp_eq_u32 s75, 28
	s_cselect_b32 s53, s31, s51
	s_cselect_b32 s52, s47, s50
	s_cselect_b32 s51, s27, s74
	s_cselect_b32 s50, s71, s72
	v_lshl_add_u64 v[216:217], s[48:49], 0, v[138:139]
	s_add_i32 m0, s57, 0xc000
	ds_read_b128 v[184:187], v153
	ds_read_b128 v[188:191], v153 offset:1024
	ds_read_b128 v[192:195], v153 offset:2048
	ds_read_b128 v[196:199], v153 offset:3072
	ds_read_b128 v[200:203], v153 offset:4096
	ds_read_b128 v[204:207], v153 offset:5120
	ds_read_b128 v[208:211], v153 offset:6144
	ds_read_b128 v[212:215], v153 offset:7168
	global_load_lds_dwordx4 v[216:217], off
	v_lshl_add_u64 v[216:217], s[48:49], 0, v[136:137]
	s_add_i32 m0, s57, 0xe000
	s_nop 0
	global_load_lds_dwordx4 v[216:217], off
	s_waitcnt vmcnt(8)
	s_waitcnt lgkmcnt(0)
	s_barrier
	s_setprio 1
	v_mfma_f32_16x16x32_bf16 v[124:127], v[144:147], v[184:187], v[124:127]
	v_mfma_f32_16x16x32_bf16 v[120:123], v[160:163], v[184:187], v[120:123]
	v_mfma_f32_16x16x32_bf16 v[108:111], v[144:147], v[192:195], v[108:111]
	v_mfma_f32_16x16x32_bf16 v[104:107], v[160:163], v[192:195], v[104:107]
	v_mfma_f32_16x16x32_bf16 v[92:95], v[144:147], v[200:203], v[92:95]
	v_mfma_f32_16x16x32_bf16 v[88:91], v[160:163], v[200:203], v[88:91]
	v_mfma_f32_16x16x32_bf16 v[76:79], v[144:147], v[208:211], v[76:79]
	v_mfma_f32_16x16x32_bf16 v[72:75], v[160:163], v[208:211], v[72:75]
	v_mfma_f32_16x16x32_bf16 v[124:127], v[156:159], v[188:191], v[124:127]
	v_mfma_f32_16x16x32_bf16 v[120:123], v[164:167], v[188:191], v[120:123]
	v_mfma_f32_16x16x32_bf16 v[108:111], v[156:159], v[196:199], v[108:111]
	v_mfma_f32_16x16x32_bf16 v[104:107], v[164:167], v[196:199], v[104:107]
	v_mfma_f32_16x16x32_bf16 v[92:95], v[156:159], v[204:207], v[92:95]
	v_mfma_f32_16x16x32_bf16 v[88:91], v[164:167], v[204:207], v[88:91]
	v_mfma_f32_16x16x32_bf16 v[76:79], v[156:159], v[212:215], v[76:79]
	v_mfma_f32_16x16x32_bf16 v[72:75], v[164:167], v[212:215], v[72:75]
	s_setprio 0
	s_setprio 1
	v_mfma_f32_16x16x32_bf16 v[116:119], v[168:171], v[184:187], v[116:119]
	v_mfma_f32_16x16x32_bf16 v[112:115], v[176:179], v[184:187], v[112:115]
	v_mfma_f32_16x16x32_bf16 v[100:103], v[168:171], v[192:195], v[100:103]
	v_mfma_f32_16x16x32_bf16 v[96:99], v[176:179], v[192:195], v[96:99]
	v_mfma_f32_16x16x32_bf16 v[84:87], v[168:171], v[200:203], v[84:87]
	v_mfma_f32_16x16x32_bf16 v[80:83], v[176:179], v[200:203], v[80:83]
	v_mfma_f32_16x16x32_bf16 v[68:71], v[168:171], v[208:211], v[68:71]
	v_mfma_f32_16x16x32_bf16 v[64:67], v[176:179], v[208:211], v[64:67]
	v_mfma_f32_16x16x32_bf16 v[116:119], v[172:175], v[188:191], v[116:119]
	v_mfma_f32_16x16x32_bf16 v[112:115], v[180:183], v[188:191], v[112:115]
	v_mfma_f32_16x16x32_bf16 v[100:103], v[172:175], v[196:199], v[100:103]
	v_mfma_f32_16x16x32_bf16 v[96:99], v[180:183], v[196:199], v[96:99]
	v_mfma_f32_16x16x32_bf16 v[84:87], v[172:175], v[204:207], v[84:87]
	v_mfma_f32_16x16x32_bf16 v[80:83], v[180:183], v[204:207], v[80:83]
	v_mfma_f32_16x16x32_bf16 v[68:71], v[172:175], v[212:215], v[68:71]
	v_mfma_f32_16x16x32_bf16 v[64:67], v[180:183], v[212:215], v[64:67]
	s_setprio 0
	s_barrier
	s_add_i32 s76, s66, s56
	v_lshl_add_u64 v[216:217], s[50:51], 0, v[130:131]
	s_mov_b32 m0, s76
	ds_read_b128 v[184:187], v153 offset:16384
	ds_read_b128 v[188:191], v153 offset:17408
	ds_read_b128 v[192:195], v153 offset:18432
	ds_read_b128 v[196:199], v153 offset:19456
	ds_read_b128 v[200:203], v153 offset:20480
	ds_read_b128 v[204:207], v153 offset:21504
	ds_read_b128 v[208:211], v153 offset:22528
	ds_read_b128 v[212:215], v153 offset:23552
	global_load_lds_dwordx4 v[216:217], off
	s_add_i32 m0, s76, 0x2000
	s_add_u32 s76, s50, 0x80000
	v_lshl_add_u64 v[218:219], s[50:51], 0, v[134:135]
	s_addc_u32 s77, s51, 0
	s_add_i32 s78, s67, s56
	global_load_lds_dwordx4 v[218:219], off
	v_lshl_add_u64 v[220:221], s[76:77], 0, v[130:131]
	s_mov_b32 m0, s78
	v_lshl_add_u64 v[222:223], s[52:53], 0, v[132:133]
	global_load_lds_dwordx4 v[220:221], off
	v_lshl_add_u64 v[220:221], s[76:77], 0, v[134:135]
	s_add_i32 m0, s78, 0x2000
	s_nop 0
	global_load_lds_dwordx4 v[220:221], off
	v_lshl_add_u64 v[220:221], s[52:53], 0, v[128:129]
	s_mov_b32 m0, s57
	s_nop 0
	global_load_lds_dwordx4 v[220:221], off
	s_mov_b32 m0, s58
	s_nop 0
	global_load_lds_dwordx4 v[222:223], off
	s_waitcnt vmcnt(8)
	s_waitcnt lgkmcnt(0)
	s_barrier
	s_setprio 1
	v_mfma_f32_16x16x32_bf16 v[60:63], v[144:147], v[184:187], v[60:63]
	v_mfma_f32_16x16x32_bf16 v[56:59], v[160:163], v[184:187], v[56:59]
	v_mfma_f32_16x16x32_bf16 v[44:47], v[144:147], v[192:195], v[44:47]
	v_mfma_f32_16x16x32_bf16 v[40:43], v[160:163], v[192:195], v[40:43]
	v_mfma_f32_16x16x32_bf16 v[28:31], v[144:147], v[200:203], v[28:31]
	v_mfma_f32_16x16x32_bf16 v[24:27], v[160:163], v[200:203], v[24:27]
	v_mfma_f32_16x16x32_bf16 v[12:15], v[144:147], v[208:211], v[12:15]
	v_mfma_f32_16x16x32_bf16 v[8:11], v[160:163], v[208:211], v[8:11]
	v_mfma_f32_16x16x32_bf16 v[60:63], v[156:159], v[188:191], v[60:63]
	v_mfma_f32_16x16x32_bf16 v[56:59], v[164:167], v[188:191], v[56:59]
	v_mfma_f32_16x16x32_bf16 v[44:47], v[156:159], v[196:199], v[44:47]
	v_mfma_f32_16x16x32_bf16 v[40:43], v[164:167], v[196:199], v[40:43]
	v_mfma_f32_16x16x32_bf16 v[28:31], v[156:159], v[204:207], v[28:31]
	v_mfma_f32_16x16x32_bf16 v[24:27], v[164:167], v[204:207], v[24:27]
	v_mfma_f32_16x16x32_bf16 v[12:15], v[156:159], v[212:215], v[12:15]
	v_mfma_f32_16x16x32_bf16 v[8:11], v[164:167], v[212:215], v[8:11]
	s_setprio 0
	s_setprio 1
	v_mfma_f32_16x16x32_bf16 v[52:55], v[168:171], v[184:187], v[52:55]
	v_mfma_f32_16x16x32_bf16 v[48:51], v[176:179], v[184:187], v[48:51]
	v_mfma_f32_16x16x32_bf16 v[36:39], v[168:171], v[192:195], v[36:39]
	v_mfma_f32_16x16x32_bf16 v[32:35], v[176:179], v[192:195], v[32:35]
	v_mfma_f32_16x16x32_bf16 v[20:23], v[168:171], v[200:203], v[20:23]
	v_mfma_f32_16x16x32_bf16 v[16:19], v[176:179], v[200:203], v[16:19]
	v_mfma_f32_16x16x32_bf16 v[4:7], v[168:171], v[208:211], v[4:7]
	v_mfma_f32_16x16x32_bf16 v[0:3], v[176:179], v[208:211], v[0:3]
	v_mfma_f32_16x16x32_bf16 v[52:55], v[172:175], v[188:191], v[52:55]
	v_mfma_f32_16x16x32_bf16 v[48:51], v[180:183], v[188:191], v[48:51]
	v_mfma_f32_16x16x32_bf16 v[36:39], v[172:175], v[196:199], v[36:39]
	v_mfma_f32_16x16x32_bf16 v[32:35], v[180:183], v[196:199], v[32:35]
	v_mfma_f32_16x16x32_bf16 v[20:23], v[172:175], v[204:207], v[20:23]
	v_mfma_f32_16x16x32_bf16 v[16:19], v[180:183], v[204:207], v[16:19]
	v_mfma_f32_16x16x32_bf16 v[4:7], v[172:175], v[212:215], v[4:7]
	v_mfma_f32_16x16x32_bf16 v[0:3], v[180:183], v[212:215], v[0:3]
	s_setprio 0
	s_barrier
	s_add_i32 s76, 0, 0x18000
	v_add_u32_e32 v155, s76, v149
	s_add_i32 s77, 0, 0x1c000
	ds_read_b128 v[144:147], v155
	ds_read_b128 v[156:159], v155 offset:1024
	ds_read_b128 v[160:163], v155 offset:2048
	ds_read_b128 v[164:167], v155 offset:3072
	v_add_u32_e32 v155, s77, v149
	ds_read_b128 v[168:171], v155
	ds_read_b128 v[172:175], v155 offset:1024
	ds_read_b128 v[176:179], v155 offset:2048
	ds_read_b128 v[180:183], v155 offset:3072
	s_add_u32 s52, s52, 0x80000
	s_addc_u32 s53, s53, 0
	s_mov_b32 m0, s59
	v_lshl_add_u64 v[224:225], s[52:53], 0, v[128:129]
	ds_read_b128 v[184:187], v153 offset:32768
	ds_read_b128 v[188:191], v153 offset:33792
	ds_read_b128 v[192:195], v153 offset:34816
	ds_read_b128 v[196:199], v153 offset:35840
	ds_read_b128 v[200:203], v153 offset:36864
	ds_read_b128 v[204:207], v153 offset:37888
	ds_read_b128 v[208:211], v153 offset:38912
	ds_read_b128 v[212:215], v153 offset:39936
	global_load_lds_dwordx4 v[224:225], off
	v_lshl_add_u64 v[224:225], s[52:53], 0, v[132:133]
	s_mov_b32 m0, s60
	s_nop 0
	global_load_lds_dwordx4 v[224:225], off
	s_waitcnt vmcnt(8)
	s_waitcnt lgkmcnt(0)
	s_barrier
	s_setprio 1
	v_mfma_f32_16x16x32_bf16 v[124:127], v[144:147], v[184:187], v[124:127]
	v_mfma_f32_16x16x32_bf16 v[120:123], v[160:163], v[184:187], v[120:123]
	v_mfma_f32_16x16x32_bf16 v[108:111], v[144:147], v[192:195], v[108:111]
	v_mfma_f32_16x16x32_bf16 v[104:107], v[160:163], v[192:195], v[104:107]
	v_mfma_f32_16x16x32_bf16 v[92:95], v[144:147], v[200:203], v[92:95]
	v_mfma_f32_16x16x32_bf16 v[88:91], v[160:163], v[200:203], v[88:91]
	v_mfma_f32_16x16x32_bf16 v[76:79], v[144:147], v[208:211], v[76:79]
	v_mfma_f32_16x16x32_bf16 v[72:75], v[160:163], v[208:211], v[72:75]
	v_mfma_f32_16x16x32_bf16 v[124:127], v[156:159], v[188:191], v[124:127]
	v_mfma_f32_16x16x32_bf16 v[120:123], v[164:167], v[188:191], v[120:123]
	v_mfma_f32_16x16x32_bf16 v[108:111], v[156:159], v[196:199], v[108:111]
	v_mfma_f32_16x16x32_bf16 v[104:107], v[164:167], v[196:199], v[104:107]
	v_mfma_f32_16x16x32_bf16 v[92:95], v[156:159], v[204:207], v[92:95]
	v_mfma_f32_16x16x32_bf16 v[88:91], v[164:167], v[204:207], v[88:91]
	v_mfma_f32_16x16x32_bf16 v[76:79], v[156:159], v[212:215], v[76:79]
	v_mfma_f32_16x16x32_bf16 v[72:75], v[164:167], v[212:215], v[72:75]
	s_setprio 0
	s_setprio 1
	v_mfma_f32_16x16x32_bf16 v[116:119], v[168:171], v[184:187], v[116:119]
	v_mfma_f32_16x16x32_bf16 v[112:115], v[176:179], v[184:187], v[112:115]
	v_mfma_f32_16x16x32_bf16 v[100:103], v[168:171], v[192:195], v[100:103]
	v_mfma_f32_16x16x32_bf16 v[96:99], v[176:179], v[192:195], v[96:99]
	v_mfma_f32_16x16x32_bf16 v[84:87], v[168:171], v[200:203], v[84:87]
	v_mfma_f32_16x16x32_bf16 v[80:83], v[176:179], v[200:203], v[80:83]
	v_mfma_f32_16x16x32_bf16 v[68:71], v[168:171], v[208:211], v[68:71]
	v_mfma_f32_16x16x32_bf16 v[64:67], v[176:179], v[208:211], v[64:67]
	v_mfma_f32_16x16x32_bf16 v[116:119], v[172:175], v[188:191], v[116:119]
	v_mfma_f32_16x16x32_bf16 v[112:115], v[180:183], v[188:191], v[112:115]
	v_mfma_f32_16x16x32_bf16 v[100:103], v[172:175], v[196:199], v[100:103]
	v_mfma_f32_16x16x32_bf16 v[96:99], v[180:183], v[196:199], v[96:99]
	v_mfma_f32_16x16x32_bf16 v[84:87], v[172:175], v[204:207], v[84:87]
	v_mfma_f32_16x16x32_bf16 v[80:83], v[180:183], v[204:207], v[80:83]
	v_mfma_f32_16x16x32_bf16 v[68:71], v[172:175], v[212:215], v[68:71]
	v_mfma_f32_16x16x32_bf16 v[64:67], v[180:183], v[212:215], v[64:67]
	s_setprio 0
	s_barrier
	s_add_i32 s52, s76, s56
	v_lshl_add_u64 v[216:217], v[216:217], 0, s[22:23]
	s_mov_b32 m0, s52
	ds_read_b128 v[184:187], v153 offset:49152
	ds_read_b128 v[188:191], v153 offset:50176
	ds_read_b128 v[192:195], v153 offset:51200
	ds_read_b128 v[196:199], v153 offset:52224
	ds_read_b128 v[200:203], v153 offset:53248
	ds_read_b128 v[204:207], v153 offset:54272
	ds_read_b128 v[208:211], v153 offset:55296
	ds_read_b128 v[212:215], v153 offset:56320
	global_load_lds_dwordx4 v[216:217], off
	s_add_i32 m0, s52, 0x2000
	s_add_u32 s50, s50, 0x80080
	v_lshl_add_u64 v[216:217], v[218:219], 0, s[22:23]
	s_addc_u32 s51, s51, 0
	s_add_i32 s52, s77, s56
	global_load_lds_dwordx4 v[216:217], off
	v_lshl_add_u64 v[216:217], s[50:51], 0, v[130:131]
	s_mov_b32 m0, s52
	s_nop 0
	global_load_lds_dwordx4 v[216:217], off
	v_lshl_add_u64 v[216:217], s[50:51], 0, v[134:135]
	s_add_i32 m0, s52, 0x2000
	s_nop 0
	global_load_lds_dwordx4 v[216:217], off
	v_lshl_add_u64 v[216:217], v[220:221], 0, s[22:23]
	s_mov_b32 m0, s62
	s_nop 0
	global_load_lds_dwordx4 v[216:217], off
	v_lshl_add_u64 v[216:217], v[222:223], 0, s[22:23]
	s_mov_b32 m0, s63
	s_nop 0
	global_load_lds_dwordx4 v[216:217], off
	s_waitcnt vmcnt(8)
	s_waitcnt lgkmcnt(0)
	s_barrier
	s_setprio 1
	v_mfma_f32_16x16x32_bf16 v[60:63], v[144:147], v[184:187], v[60:63]
	v_mfma_f32_16x16x32_bf16 v[56:59], v[160:163], v[184:187], v[56:59]
	v_mfma_f32_16x16x32_bf16 v[44:47], v[144:147], v[192:195], v[44:47]
	v_mfma_f32_16x16x32_bf16 v[40:43], v[160:163], v[192:195], v[40:43]
	v_mfma_f32_16x16x32_bf16 v[28:31], v[144:147], v[200:203], v[28:31]
	v_mfma_f32_16x16x32_bf16 v[24:27], v[160:163], v[200:203], v[24:27]
	v_mfma_f32_16x16x32_bf16 v[12:15], v[144:147], v[208:211], v[12:15]
	v_mfma_f32_16x16x32_bf16 v[8:11], v[160:163], v[208:211], v[8:11]
	v_mfma_f32_16x16x32_bf16 v[60:63], v[156:159], v[188:191], v[60:63]
	v_mfma_f32_16x16x32_bf16 v[56:59], v[164:167], v[188:191], v[56:59]
	v_mfma_f32_16x16x32_bf16 v[44:47], v[156:159], v[196:199], v[44:47]
	v_mfma_f32_16x16x32_bf16 v[40:43], v[164:167], v[196:199], v[40:43]
	v_mfma_f32_16x16x32_bf16 v[28:31], v[156:159], v[204:207], v[28:31]
	v_mfma_f32_16x16x32_bf16 v[24:27], v[164:167], v[204:207], v[24:27]
	v_mfma_f32_16x16x32_bf16 v[12:15], v[156:159], v[212:215], v[12:15]
	v_mfma_f32_16x16x32_bf16 v[8:11], v[164:167], v[212:215], v[8:11]
	s_setprio 0
	s_setprio 1
	v_mfma_f32_16x16x32_bf16 v[52:55], v[168:171], v[184:187], v[52:55]
	v_mfma_f32_16x16x32_bf16 v[48:51], v[176:179], v[184:187], v[48:51]
	v_mfma_f32_16x16x32_bf16 v[36:39], v[168:171], v[192:195], v[36:39]
	v_mfma_f32_16x16x32_bf16 v[32:35], v[176:179], v[192:195], v[32:35]
	v_mfma_f32_16x16x32_bf16 v[20:23], v[168:171], v[200:203], v[20:23]
	v_mfma_f32_16x16x32_bf16 v[16:19], v[176:179], v[200:203], v[16:19]
	v_mfma_f32_16x16x32_bf16 v[4:7], v[168:171], v[208:211], v[4:7]
	v_mfma_f32_16x16x32_bf16 v[0:3], v[176:179], v[208:211], v[0:3]
	v_mfma_f32_16x16x32_bf16 v[52:55], v[172:175], v[188:191], v[52:55]
	v_mfma_f32_16x16x32_bf16 v[48:51], v[180:183], v[188:191], v[48:51]
	v_mfma_f32_16x16x32_bf16 v[36:39], v[172:175], v[196:199], v[36:39]
	v_mfma_f32_16x16x32_bf16 v[32:35], v[180:183], v[196:199], v[32:35]
	v_mfma_f32_16x16x32_bf16 v[20:23], v[172:175], v[204:207], v[20:23]
	v_mfma_f32_16x16x32_bf16 v[16:19], v[180:183], v[204:207], v[16:19]
	v_mfma_f32_16x16x32_bf16 v[4:7], v[172:175], v[212:215], v[4:7]
	v_mfma_f32_16x16x32_bf16 v[0:3], v[180:183], v[212:215], v[0:3]
	s_setprio 0
	s_barrier
	s_add_i32 s75, s75, 2
	s_add_u32 s72, s72, 0x100
	s_addc_u32 s74, s74, 0
	s_add_u32 s48, s48, 0x100
	s_addc_u32 s49, s49, 0
	s_cmp_gt_u32 s75, 29
	s_cbranch_scc0 .LBB0_337
	s_and_b64 vcc, exec, s[24:25]
	s_cbranch_vccz .LBB0_340
	s_barrier

.LBB0_435:
	ds_read_b128 v[148:151], v222
	ds_read_b128 v[152:155], v222 offset:1024
	ds_read_b128 v[156:159], v222 offset:2048
	ds_read_b128 v[160:163], v222 offset:3072
	ds_read_b128 v[132:135], v223
	ds_read_b128 v[136:139], v223 offset:1024
	ds_read_b128 v[140:143], v223 offset:2048
	ds_read_b128 v[144:147], v223 offset:3072
	s_add_u32 s10, s54, 0xfff80080
	s_addc_u32 s11, s55, -1
	s_cmp_eq_u32 s84, 28
	s_cselect_b32 s59, s25, s11
	s_cselect_b32 s58, s46, s10
	s_cselect_b32 s57, s23, s83
	s_cselect_b32 s56, s47, s82
	v_lshl_add_u64 v[2:3], s[54:55], 0, v[208:209]
	s_add_i32 m0, s37, 0xc000
	s_waitcnt lgkmcnt(0)
	ds_read_b128 v[164:167], v224
	ds_read_b128 v[168:171], v224 offset:1024
	ds_read_b128 v[172:175], v224 offset:2048
	ds_read_b128 v[176:179], v224 offset:3072
	ds_read_b128 v[180:183], v224 offset:4096
	ds_read_b128 v[184:187], v224 offset:5120
	ds_read_b128 v[188:191], v224 offset:6144
	ds_read_b128 v[192:195], v224 offset:7168
	global_load_lds_dwordx4 v[2:3], off
	v_lshl_add_u64 v[2:3], s[54:55], 0, v[206:207]
	s_add_i32 m0, s37, 0xe000
	s_nop 0
	global_load_lds_dwordx4 v[2:3], off
	s_waitcnt vmcnt(8)
	s_waitcnt lgkmcnt(0)
	s_barrier
	s_setprio 1
	v_mfma_f32_16x16x32_bf16 v[120:123], v[148:151], v[164:167], v[120:123]
	v_mfma_f32_16x16x32_bf16 v[116:119], v[156:159], v[164:167], v[116:119]
	v_mfma_f32_16x16x32_bf16 v[104:107], v[148:151], v[172:175], v[104:107]
	v_mfma_f32_16x16x32_bf16 v[100:103], v[156:159], v[172:175], v[100:103]
	v_mfma_f32_16x16x32_bf16 v[88:91], v[148:151], v[180:183], v[88:91]
	v_mfma_f32_16x16x32_bf16 v[84:87], v[156:159], v[180:183], v[84:87]
	v_mfma_f32_16x16x32_bf16 v[76:79], v[148:151], v[188:191], v[76:79]
	v_mfma_f32_16x16x32_bf16 v[72:75], v[156:159], v[188:191], v[72:75]
	v_mfma_f32_16x16x32_bf16 v[120:123], v[152:155], v[168:171], v[120:123]
	v_mfma_f32_16x16x32_bf16 v[116:119], v[160:163], v[168:171], v[116:119]
	v_mfma_f32_16x16x32_bf16 v[104:107], v[152:155], v[176:179], v[104:107]
	v_mfma_f32_16x16x32_bf16 v[100:103], v[160:163], v[176:179], v[100:103]
	v_mfma_f32_16x16x32_bf16 v[88:91], v[152:155], v[184:187], v[88:91]
	v_mfma_f32_16x16x32_bf16 v[84:87], v[160:163], v[184:187], v[84:87]
	v_mfma_f32_16x16x32_bf16 v[76:79], v[152:155], v[192:195], v[76:79]
	v_mfma_f32_16x16x32_bf16 v[72:75], v[160:163], v[192:195], v[72:75]
	s_setprio 0
	s_setprio 1
	v_mfma_f32_16x16x32_bf16 v[128:131], v[132:135], v[164:167], v[128:131]
	v_mfma_f32_16x16x32_bf16 v[124:127], v[140:143], v[164:167], v[124:127]
	v_mfma_f32_16x16x32_bf16 v[112:115], v[132:135], v[172:175], v[112:115]
	v_mfma_f32_16x16x32_bf16 v[108:111], v[140:143], v[172:175], v[108:111]
	v_mfma_f32_16x16x32_bf16 v[96:99], v[132:135], v[180:183], v[96:99]
	v_mfma_f32_16x16x32_bf16 v[92:95], v[140:143], v[180:183], v[92:95]
	v_mfma_f32_16x16x32_bf16 v[80:83], v[132:135], v[188:191], v[80:83]
	v_mfma_f32_16x16x32_bf16 v[68:71], v[140:143], v[188:191], v[68:71]
	v_mfma_f32_16x16x32_bf16 v[128:131], v[136:139], v[168:171], v[128:131]
	v_mfma_f32_16x16x32_bf16 v[124:127], v[144:147], v[168:171], v[124:127]
	v_mfma_f32_16x16x32_bf16 v[112:115], v[136:139], v[176:179], v[112:115]
	v_mfma_f32_16x16x32_bf16 v[108:111], v[144:147], v[176:179], v[108:111]
	v_mfma_f32_16x16x32_bf16 v[96:99], v[136:139], v[184:187], v[96:99]
	v_mfma_f32_16x16x32_bf16 v[92:95], v[144:147], v[184:187], v[92:95]
	v_mfma_f32_16x16x32_bf16 v[80:83], v[136:139], v[192:195], v[80:83]
	v_mfma_f32_16x16x32_bf16 v[68:71], v[144:147], v[192:195], v[68:71]
	s_setprio 0
	s_barrier
	s_add_i32 s10, s67, s48
	v_lshl_add_u64 v[2:3], s[56:57], 0, v[198:199]
	s_mov_b32 m0, s10
	ds_read_b128 v[188:191], v224 offset:16384
	ds_read_b128 v[192:195], v224 offset:17408
	ds_read_b128 v[180:183], v224 offset:18432
	ds_read_b128 v[184:187], v224 offset:19456
	ds_read_b128 v[172:175], v224 offset:20480
	ds_read_b128 v[176:179], v224 offset:21504
	ds_read_b128 v[164:167], v224 offset:22528
	ds_read_b128 v[168:171], v224 offset:23552
	global_load_lds_dwordx4 v[2:3], off
	s_add_i32 m0, s10, 0x2000
	s_add_u32 s10, s56, 0x80000
	v_lshl_add_u64 v[212:213], s[56:57], 0, v[202:203]
	s_addc_u32 s11, s57, 0
	s_add_i32 s78, s70, s48
	global_load_lds_dwordx4 v[212:213], off
	v_lshl_add_u64 v[214:215], s[10:11], 0, v[198:199]
	s_mov_b32 m0, s78
	v_lshl_add_u64 v[216:217], s[58:59], 0, v[200:201]
	global_load_lds_dwordx4 v[214:215], off
	v_lshl_add_u64 v[214:215], s[10:11], 0, v[202:203]
	s_add_i32 m0, s78, 0x2000
	v_cmp_ne_u32_e64 s[10:11], 1, v227
	global_load_lds_dwordx4 v[214:215], off
	v_lshl_add_u64 v[214:215], s[58:59], 0, v[196:197]
	s_mov_b32 m0, s37
	s_andn2_b64 vcc, exec, s[52:53]
	global_load_lds_dwordx4 v[214:215], off
	s_mov_b32 m0, s60
	s_nop 0
	global_load_lds_dwordx4 v[216:217], off
	s_waitcnt vmcnt(8)
	s_waitcnt lgkmcnt(0)
	s_barrier
	s_cbranch_vccnz .LBB0_437
	s_setprio 1
	v_mfma_f32_16x16x32_bf16 v[56:59], v[148:151], v[188:191], v[56:59]
	v_mfma_f32_16x16x32_bf16 v[52:55], v[156:159], v[188:191], v[52:55]
	v_mfma_f32_16x16x32_bf16 v[40:43], v[148:151], v[180:183], v[40:43]
	v_mfma_f32_16x16x32_bf16 v[36:39], v[156:159], v[180:183], v[36:39]
	v_mfma_f32_16x16x32_bf16 v[24:27], v[148:151], v[172:175], v[24:27]
	v_mfma_f32_16x16x32_bf16 v[20:23], v[156:159], v[172:175], v[20:23]
	v_mfma_f32_16x16x32_bf16 v[8:11], v[148:151], v[164:167], v[8:11]
	v_mfma_f32_16x16x32_bf16 v[4:7], v[156:159], v[164:167], v[4:7]
	v_mfma_f32_16x16x32_bf16 v[56:59], v[152:155], v[192:195], v[56:59]
	v_mfma_f32_16x16x32_bf16 v[52:55], v[160:163], v[192:195], v[52:55]
	v_mfma_f32_16x16x32_bf16 v[40:43], v[152:155], v[184:187], v[40:43]
	v_mfma_f32_16x16x32_bf16 v[36:39], v[160:163], v[184:187], v[36:39]
	v_mfma_f32_16x16x32_bf16 v[24:27], v[152:155], v[176:179], v[24:27]
	v_mfma_f32_16x16x32_bf16 v[20:23], v[160:163], v[176:179], v[20:23]
	v_mfma_f32_16x16x32_bf16 v[8:11], v[152:155], v[168:171], v[8:11]
	v_mfma_f32_16x16x32_bf16 v[4:7], v[160:163], v[168:171], v[4:7]
	s_setprio 0
	s_setprio 1
	v_mfma_f32_16x16x32_bf16 v[64:67], v[132:135], v[188:191], v[64:67]
	v_mfma_f32_16x16x32_bf16 v[60:63], v[140:143], v[188:191], v[60:63]
	v_mfma_f32_16x16x32_bf16 v[48:51], v[132:135], v[180:183], v[48:51]
	v_mfma_f32_16x16x32_bf16 v[44:47], v[140:143], v[180:183], v[44:47]
	v_mfma_f32_16x16x32_bf16 v[32:35], v[132:135], v[172:175], v[32:35]
	v_mfma_f32_16x16x32_bf16 v[28:31], v[140:143], v[172:175], v[28:31]
	v_mfma_f32_16x16x32_bf16 v[16:19], v[132:135], v[164:167], v[16:19]
	v_mfma_f32_16x16x32_bf16 v[12:15], v[140:143], v[164:167], v[12:15]
	v_mfma_f32_16x16x32_bf16 v[64:67], v[136:139], v[192:195], v[64:67]
	v_mfma_f32_16x16x32_bf16 v[60:63], v[144:147], v[192:195], v[60:63]
	v_mfma_f32_16x16x32_bf16 v[48:51], v[136:139], v[184:187], v[48:51]
	v_mfma_f32_16x16x32_bf16 v[44:47], v[144:147], v[184:187], v[44:47]
	v_mfma_f32_16x16x32_bf16 v[32:35], v[136:139], v[176:179], v[32:35]
	v_mfma_f32_16x16x32_bf16 v[28:31], v[144:147], v[176:179], v[28:31]
	v_mfma_f32_16x16x32_bf16 v[16:19], v[136:139], v[168:171], v[16:19]
	v_mfma_f32_16x16x32_bf16 v[12:15], v[144:147], v[168:171], v[12:15]
	s_setprio 0
.LBB0_437:
	s_barrier
	s_add_i32 s78, 0, 0x18000
	v_add_u32_e32 v1, s78, v220
	s_add_i32 s79, 0, 0x1c000
	ds_read_b128 v[148:151], v1
	ds_read_b128 v[152:155], v1 offset:1024
	ds_read_b128 v[156:159], v1 offset:2048
	ds_read_b128 v[160:163], v1 offset:3072
	v_add_u32_e32 v1, s79, v220
	ds_read_b128 v[132:135], v1
	ds_read_b128 v[136:139], v1 offset:1024
	ds_read_b128 v[140:143], v1 offset:2048
	ds_read_b128 v[144:147], v1 offset:3072
	s_add_u32 s58, s58, 0x80000
	s_addc_u32 s59, s59, 0
	s_mov_b32 m0, s61
	v_lshl_add_u64 v[228:229], s[58:59], 0, v[196:197]
	s_waitcnt lgkmcnt(0)
	ds_read_b128 v[164:167], v224 offset:32768
	ds_read_b128 v[168:171], v224 offset:33792
	ds_read_b128 v[172:175], v224 offset:34816
	ds_read_b128 v[176:179], v224 offset:35840
	ds_read_b128 v[180:183], v224 offset:36864
	ds_read_b128 v[184:187], v224 offset:37888
	ds_read_b128 v[188:191], v224 offset:38912
	ds_read_b128 v[192:195], v224 offset:39936
	global_load_lds_dwordx4 v[228:229], off
	v_lshl_add_u64 v[228:229], s[58:59], 0, v[200:201]
	s_mov_b32 m0, s62
	s_nop 0
	global_load_lds_dwordx4 v[228:229], off
	s_waitcnt vmcnt(8)
	s_waitcnt lgkmcnt(0)
	s_barrier
	s_setprio 1
	v_mfma_f32_16x16x32_bf16 v[120:123], v[148:151], v[164:167], v[120:123]
	v_mfma_f32_16x16x32_bf16 v[116:119], v[156:159], v[164:167], v[116:119]
	v_mfma_f32_16x16x32_bf16 v[104:107], v[148:151], v[172:175], v[104:107]
	v_mfma_f32_16x16x32_bf16 v[100:103], v[156:159], v[172:175], v[100:103]
	v_mfma_f32_16x16x32_bf16 v[88:91], v[148:151], v[180:183], v[88:91]
	v_mfma_f32_16x16x32_bf16 v[84:87], v[156:159], v[180:183], v[84:87]
	v_mfma_f32_16x16x32_bf16 v[76:79], v[148:151], v[188:191], v[76:79]
	v_mfma_f32_16x16x32_bf16 v[72:75], v[156:159], v[188:191], v[72:75]
	v_mfma_f32_16x16x32_bf16 v[120:123], v[152:155], v[168:171], v[120:123]
	v_mfma_f32_16x16x32_bf16 v[116:119], v[160:163], v[168:171], v[116:119]
	v_mfma_f32_16x16x32_bf16 v[104:107], v[152:155], v[176:179], v[104:107]
	v_mfma_f32_16x16x32_bf16 v[100:103], v[160:163], v[176:179], v[100:103]
	v_mfma_f32_16x16x32_bf16 v[88:91], v[152:155], v[184:187], v[88:91]
	v_mfma_f32_16x16x32_bf16 v[84:87], v[160:163], v[184:187], v[84:87]
	v_mfma_f32_16x16x32_bf16 v[76:79], v[152:155], v[192:195], v[76:79]
	v_mfma_f32_16x16x32_bf16 v[72:75], v[160:163], v[192:195], v[72:75]
	s_setprio 0
	s_setprio 1
	v_mfma_f32_16x16x32_bf16 v[128:131], v[132:135], v[164:167], v[128:131]
	v_mfma_f32_16x16x32_bf16 v[124:127], v[140:143], v[164:167], v[124:127]
	v_mfma_f32_16x16x32_bf16 v[112:115], v[132:135], v[172:175], v[112:115]
	v_mfma_f32_16x16x32_bf16 v[108:111], v[140:143], v[172:175], v[108:111]
	v_mfma_f32_16x16x32_bf16 v[96:99], v[132:135], v[180:183], v[96:99]
	v_mfma_f32_16x16x32_bf16 v[92:95], v[140:143], v[180:183], v[92:95]
	v_mfma_f32_16x16x32_bf16 v[80:83], v[132:135], v[188:191], v[80:83]
	v_mfma_f32_16x16x32_bf16 v[68:71], v[140:143], v[188:191], v[68:71]
	v_mfma_f32_16x16x32_bf16 v[128:131], v[136:139], v[168:171], v[128:131]
	v_mfma_f32_16x16x32_bf16 v[124:127], v[144:147], v[168:171], v[124:127]
	v_mfma_f32_16x16x32_bf16 v[112:115], v[136:139], v[176:179], v[112:115]
	v_mfma_f32_16x16x32_bf16 v[108:111], v[144:147], v[176:179], v[108:111]
	v_mfma_f32_16x16x32_bf16 v[96:99], v[136:139], v[184:187], v[96:99]
	v_mfma_f32_16x16x32_bf16 v[92:95], v[144:147], v[184:187], v[92:95]
	v_mfma_f32_16x16x32_bf16 v[80:83], v[136:139], v[192:195], v[80:83]
	v_mfma_f32_16x16x32_bf16 v[68:71], v[144:147], v[192:195], v[68:71]
	s_setprio 0
	s_barrier
	s_add_i32 s58, s78, s48
	v_lshl_add_u64 v[2:3], v[2:3], 0, s[16:17]
	s_mov_b32 m0, s58
	ds_read_b128 v[188:191], v224 offset:49152
	ds_read_b128 v[192:195], v224 offset:50176
	ds_read_b128 v[180:183], v224 offset:51200
	ds_read_b128 v[184:187], v224 offset:52224
	ds_read_b128 v[172:175], v224 offset:53248
	ds_read_b128 v[176:179], v224 offset:54272
	ds_read_b128 v[164:167], v224 offset:55296
	ds_read_b128 v[168:171], v224 offset:56320
	global_load_lds_dwordx4 v[2:3], off
	s_add_i32 m0, s58, 0x2000
	s_add_u32 s56, s56, 0x80080
	v_lshl_add_u64 v[2:3], v[212:213], 0, s[16:17]
	s_addc_u32 s57, s57, 0
	s_add_i32 s58, s79, s48
	global_load_lds_dwordx4 v[2:3], off
	v_lshl_add_u64 v[2:3], s[56:57], 0, v[198:199]
	s_mov_b32 m0, s58
	s_and_b64 vcc, exec, s[10:11]
	global_load_lds_dwordx4 v[2:3], off
	v_lshl_add_u64 v[2:3], s[56:57], 0, v[202:203]
	s_add_i32 m0, s58, 0x2000
	s_nop 0
	global_load_lds_dwordx4 v[2:3], off
	v_lshl_add_u64 v[2:3], v[214:215], 0, s[16:17]
	s_mov_b32 m0, s63
	s_nop 0
	global_load_lds_dwordx4 v[2:3], off
	v_lshl_add_u64 v[2:3], v[216:217], 0, s[16:17]
	s_mov_b32 m0, s64
	s_nop 0
	global_load_lds_dwordx4 v[2:3], off
	s_waitcnt vmcnt(8)
	s_waitcnt lgkmcnt(0)
	s_barrier
	s_cbranch_vccnz .LBB0_434
	s_setprio 1
	v_mfma_f32_16x16x32_bf16 v[56:59], v[148:151], v[188:191], v[56:59]
	v_mfma_f32_16x16x32_bf16 v[52:55], v[156:159], v[188:191], v[52:55]
	v_mfma_f32_16x16x32_bf16 v[40:43], v[148:151], v[180:183], v[40:43]
	v_mfma_f32_16x16x32_bf16 v[36:39], v[156:159], v[180:183], v[36:39]
	v_mfma_f32_16x16x32_bf16 v[24:27], v[148:151], v[172:175], v[24:27]
	v_mfma_f32_16x16x32_bf16 v[20:23], v[156:159], v[172:175], v[20:23]
	v_mfma_f32_16x16x32_bf16 v[8:11], v[148:151], v[164:167], v[8:11]
	v_mfma_f32_16x16x32_bf16 v[2:5], v[156:159], v[164:167], v[4:7]
	v_mfma_f32_16x16x32_bf16 v[56:59], v[152:155], v[192:195], v[56:59]
	v_mfma_f32_16x16x32_bf16 v[52:55], v[160:163], v[192:195], v[52:55]
	v_mfma_f32_16x16x32_bf16 v[40:43], v[152:155], v[184:187], v[40:43]
	v_mfma_f32_16x16x32_bf16 v[36:39], v[160:163], v[184:187], v[36:39]
	v_mfma_f32_16x16x32_bf16 v[24:27], v[152:155], v[176:179], v[24:27]
	v_mfma_f32_16x16x32_bf16 v[20:23], v[160:163], v[176:179], v[20:23]
	v_mfma_f32_16x16x32_bf16 v[8:11], v[152:155], v[168:171], v[8:11]
	v_mfma_f32_16x16x32_bf16 v[4:7], v[160:163], v[168:171], v[2:5]
	s_setprio 0
	s_setprio 1
	v_mfma_f32_16x16x32_bf16 v[64:67], v[132:135], v[188:191], v[64:67]
	v_mfma_f32_16x16x32_bf16 v[60:63], v[140:143], v[188:191], v[60:63]
	v_mfma_f32_16x16x32_bf16 v[48:51], v[132:135], v[180:183], v[48:51]
	v_mfma_f32_16x16x32_bf16 v[44:47], v[140:143], v[180:183], v[44:47]
	v_mfma_f32_16x16x32_bf16 v[32:35], v[132:135], v[172:175], v[32:35]
	v_mfma_f32_16x16x32_bf16 v[28:31], v[140:143], v[172:175], v[28:31]
	v_mfma_f32_16x16x32_bf16 v[16:19], v[132:135], v[164:167], v[16:19]
	v_mfma_f32_16x16x32_bf16 v[12:15], v[140:143], v[164:167], v[12:15]
	v_mfma_f32_16x16x32_bf16 v[64:67], v[136:139], v[192:195], v[64:67]
	v_mfma_f32_16x16x32_bf16 v[60:63], v[144:147], v[192:195], v[60:63]
	v_mfma_f32_16x16x32_bf16 v[48:51], v[136:139], v[184:187], v[48:51]
	v_mfma_f32_16x16x32_bf16 v[44:47], v[144:147], v[184:187], v[44:47]
	v_mfma_f32_16x16x32_bf16 v[32:35], v[136:139], v[176:179], v[32:35]
	v_mfma_f32_16x16x32_bf16 v[28:31], v[144:147], v[176:179], v[28:31]
	v_mfma_f32_16x16x32_bf16 v[16:19], v[136:139], v[168:171], v[16:19]
	v_mfma_f32_16x16x32_bf16 v[12:15], v[144:147], v[168:171], v[12:15]
	s_setprio 0
	s_branch .LBB0_434

.LBB0_523:
	ds_read_b128 v[144:147], v151
	ds_read_b128 v[156:159], v151 offset:1024
	ds_read_b128 v[160:163], v151 offset:2048
	ds_read_b128 v[164:167], v151 offset:3072
	ds_read_b128 v[168:171], v152
	ds_read_b128 v[172:175], v152 offset:1024
	ds_read_b128 v[176:179], v152 offset:2048
	ds_read_b128 v[180:183], v152 offset:3072
	s_add_u32 s36, s34, 0x100
	s_addc_u32 s37, s35, 0
	s_cmpk_eq_i32 s66, 0x54
	s_cselect_b32 s55, s13, s37
	s_cselect_b32 s54, s12, s36
	s_cselect_b32 s53, s31, s47
	s_cselect_b32 s52, s30, s46
	v_lshl_add_u64 v[216:217], s[34:35], 0, v[138:139]
	s_add_i32 m0, s49, 0xc000
	ds_read_b128 v[184:187], v153
	ds_read_b128 v[188:191], v153 offset:1024
	ds_read_b128 v[192:195], v153 offset:2048
	ds_read_b128 v[196:199], v153 offset:3072
	ds_read_b128 v[200:203], v153 offset:4096
	ds_read_b128 v[204:207], v153 offset:5120
	ds_read_b128 v[208:211], v153 offset:6144
	ds_read_b128 v[212:215], v153 offset:7168
	global_load_lds_dwordx4 v[216:217], off
	v_lshl_add_u64 v[216:217], s[34:35], 0, v[136:137]
	s_add_i32 m0, s49, 0xe000
	s_nop 0
	global_load_lds_dwordx4 v[216:217], off
	s_waitcnt vmcnt(8)
	s_waitcnt lgkmcnt(0)
	s_barrier
	s_setprio 1
	v_mfma_f32_16x16x32_bf16 v[124:127], v[144:147], v[184:187], v[124:127]
	v_mfma_f32_16x16x32_bf16 v[120:123], v[160:163], v[184:187], v[120:123]
	v_mfma_f32_16x16x32_bf16 v[108:111], v[144:147], v[192:195], v[108:111]
	v_mfma_f32_16x16x32_bf16 v[104:107], v[160:163], v[192:195], v[104:107]
	v_mfma_f32_16x16x32_bf16 v[92:95], v[144:147], v[200:203], v[92:95]
	v_mfma_f32_16x16x32_bf16 v[88:91], v[160:163], v[200:203], v[88:91]
	v_mfma_f32_16x16x32_bf16 v[76:79], v[144:147], v[208:211], v[76:79]
	v_mfma_f32_16x16x32_bf16 v[72:75], v[160:163], v[208:211], v[72:75]
	v_mfma_f32_16x16x32_bf16 v[124:127], v[156:159], v[188:191], v[124:127]
	v_mfma_f32_16x16x32_bf16 v[120:123], v[164:167], v[188:191], v[120:123]
	v_mfma_f32_16x16x32_bf16 v[108:111], v[156:159], v[196:199], v[108:111]
	v_mfma_f32_16x16x32_bf16 v[104:107], v[164:167], v[196:199], v[104:107]
	v_mfma_f32_16x16x32_bf16 v[92:95], v[156:159], v[204:207], v[92:95]
	v_mfma_f32_16x16x32_bf16 v[88:91], v[164:167], v[204:207], v[88:91]
	v_mfma_f32_16x16x32_bf16 v[76:79], v[156:159], v[212:215], v[76:79]
	v_mfma_f32_16x16x32_bf16 v[72:75], v[164:167], v[212:215], v[72:75]
	s_setprio 0
	s_setprio 1
	v_mfma_f32_16x16x32_bf16 v[116:119], v[168:171], v[184:187], v[116:119]
	v_mfma_f32_16x16x32_bf16 v[112:115], v[176:179], v[184:187], v[112:115]
	v_mfma_f32_16x16x32_bf16 v[100:103], v[168:171], v[192:195], v[100:103]
	v_mfma_f32_16x16x32_bf16 v[96:99], v[176:179], v[192:195], v[96:99]
	v_mfma_f32_16x16x32_bf16 v[84:87], v[168:171], v[200:203], v[84:87]
	v_mfma_f32_16x16x32_bf16 v[80:83], v[176:179], v[200:203], v[80:83]
	v_mfma_f32_16x16x32_bf16 v[68:71], v[168:171], v[208:211], v[68:71]
	v_mfma_f32_16x16x32_bf16 v[64:67], v[176:179], v[208:211], v[64:67]
	v_mfma_f32_16x16x32_bf16 v[116:119], v[172:175], v[188:191], v[116:119]
	v_mfma_f32_16x16x32_bf16 v[112:115], v[180:183], v[188:191], v[112:115]
	v_mfma_f32_16x16x32_bf16 v[100:103], v[172:175], v[196:199], v[100:103]
	v_mfma_f32_16x16x32_bf16 v[96:99], v[180:183], v[196:199], v[96:99]
	v_mfma_f32_16x16x32_bf16 v[84:87], v[172:175], v[204:207], v[84:87]
	v_mfma_f32_16x16x32_bf16 v[80:83], v[180:183], v[204:207], v[80:83]
	v_mfma_f32_16x16x32_bf16 v[68:71], v[172:175], v[212:215], v[68:71]
	v_mfma_f32_16x16x32_bf16 v[64:67], v[180:183], v[212:215], v[64:67]
	s_setprio 0
	s_barrier
	s_add_i32 s34, s62, s48
	v_lshl_add_u64 v[216:217], s[52:53], 0, v[130:131]
	s_mov_b32 m0, s34
	ds_read_b128 v[184:187], v153 offset:16384
	ds_read_b128 v[188:191], v153 offset:17408
	ds_read_b128 v[192:195], v153 offset:18432
	ds_read_b128 v[196:199], v153 offset:19456
	ds_read_b128 v[200:203], v153 offset:20480
	ds_read_b128 v[204:207], v153 offset:21504
	ds_read_b128 v[208:211], v153 offset:22528
	ds_read_b128 v[212:215], v153 offset:23552
	global_load_lds_dwordx4 v[216:217], off
	s_add_i32 m0, s34, 0x2000
	s_add_u32 s34, s52, 0x160000
	v_lshl_add_u64 v[218:219], s[52:53], 0, v[134:135]
	s_addc_u32 s35, s53, 0
	s_add_i32 s67, s63, s48
	global_load_lds_dwordx4 v[218:219], off
	v_lshl_add_u64 v[220:221], s[34:35], 0, v[130:131]
	s_mov_b32 m0, s67
	v_lshl_add_u64 v[222:223], s[54:55], 0, v[132:133]
	global_load_lds_dwordx4 v[220:221], off
	v_lshl_add_u64 v[220:221], s[34:35], 0, v[134:135]
	s_add_i32 m0, s67, 0x2000
	s_nop 0
	global_load_lds_dwordx4 v[220:221], off
	v_lshl_add_u64 v[220:221], s[54:55], 0, v[128:129]
	s_mov_b32 m0, s49
	s_nop 0
	global_load_lds_dwordx4 v[220:221], off
	s_mov_b32 m0, s56
	s_nop 0
	global_load_lds_dwordx4 v[222:223], off
	s_waitcnt vmcnt(8)
	s_waitcnt lgkmcnt(0)
	s_barrier
	s_setprio 1
	v_mfma_f32_16x16x32_bf16 v[60:63], v[144:147], v[184:187], v[60:63]
	v_mfma_f32_16x16x32_bf16 v[56:59], v[160:163], v[184:187], v[56:59]
	v_mfma_f32_16x16x32_bf16 v[44:47], v[144:147], v[192:195], v[44:47]
	v_mfma_f32_16x16x32_bf16 v[40:43], v[160:163], v[192:195], v[40:43]
	v_mfma_f32_16x16x32_bf16 v[28:31], v[144:147], v[200:203], v[28:31]
	v_mfma_f32_16x16x32_bf16 v[24:27], v[160:163], v[200:203], v[24:27]
	v_mfma_f32_16x16x32_bf16 v[12:15], v[144:147], v[208:211], v[12:15]
	v_mfma_f32_16x16x32_bf16 v[8:11], v[160:163], v[208:211], v[8:11]
	v_mfma_f32_16x16x32_bf16 v[60:63], v[156:159], v[188:191], v[60:63]
	v_mfma_f32_16x16x32_bf16 v[56:59], v[164:167], v[188:191], v[56:59]
	v_mfma_f32_16x16x32_bf16 v[44:47], v[156:159], v[196:199], v[44:47]
	v_mfma_f32_16x16x32_bf16 v[40:43], v[164:167], v[196:199], v[40:43]
	v_mfma_f32_16x16x32_bf16 v[28:31], v[156:159], v[204:207], v[28:31]
	v_mfma_f32_16x16x32_bf16 v[24:27], v[164:167], v[204:207], v[24:27]
	v_mfma_f32_16x16x32_bf16 v[12:15], v[156:159], v[212:215], v[12:15]
	v_mfma_f32_16x16x32_bf16 v[8:11], v[164:167], v[212:215], v[8:11]
	s_setprio 0
	s_setprio 1
	v_mfma_f32_16x16x32_bf16 v[52:55], v[168:171], v[184:187], v[52:55]
	v_mfma_f32_16x16x32_bf16 v[48:51], v[176:179], v[184:187], v[48:51]
	v_mfma_f32_16x16x32_bf16 v[36:39], v[168:171], v[192:195], v[36:39]
	v_mfma_f32_16x16x32_bf16 v[32:35], v[176:179], v[192:195], v[32:35]
	v_mfma_f32_16x16x32_bf16 v[20:23], v[168:171], v[200:203], v[20:23]
	v_mfma_f32_16x16x32_bf16 v[16:19], v[176:179], v[200:203], v[16:19]
	v_mfma_f32_16x16x32_bf16 v[4:7], v[168:171], v[208:211], v[4:7]
	v_mfma_f32_16x16x32_bf16 v[0:3], v[176:179], v[208:211], v[0:3]
	v_mfma_f32_16x16x32_bf16 v[52:55], v[172:175], v[188:191], v[52:55]
	v_mfma_f32_16x16x32_bf16 v[48:51], v[180:183], v[188:191], v[48:51]
	v_mfma_f32_16x16x32_bf16 v[36:39], v[172:175], v[196:199], v[36:39]
	v_mfma_f32_16x16x32_bf16 v[32:35], v[180:183], v[196:199], v[32:35]
	v_mfma_f32_16x16x32_bf16 v[20:23], v[172:175], v[204:207], v[20:23]
	v_mfma_f32_16x16x32_bf16 v[16:19], v[180:183], v[204:207], v[16:19]
	v_mfma_f32_16x16x32_bf16 v[4:7], v[172:175], v[212:215], v[4:7]
	v_mfma_f32_16x16x32_bf16 v[0:3], v[180:183], v[212:215], v[0:3]
	s_setprio 0
	s_barrier
	s_add_i32 s67, 0, 0x18000
	v_add_u32_e32 v155, s67, v149
	s_add_i32 s70, 0, 0x1c000
	ds_read_b128 v[144:147], v155
	ds_read_b128 v[156:159], v155 offset:1024
	ds_read_b128 v[160:163], v155 offset:2048
	ds_read_b128 v[164:167], v155 offset:3072
	v_add_u32_e32 v155, s70, v149
	ds_read_b128 v[168:171], v155
	ds_read_b128 v[172:175], v155 offset:1024
	ds_read_b128 v[176:179], v155 offset:2048
	ds_read_b128 v[180:183], v155 offset:3072
	s_add_u32 s34, s54, 0x160000
	s_addc_u32 s35, s55, 0
	s_mov_b32 m0, s57
	v_lshl_add_u64 v[224:225], s[34:35], 0, v[128:129]
	ds_read_b128 v[184:187], v153 offset:32768
	ds_read_b128 v[188:191], v153 offset:33792
	ds_read_b128 v[192:195], v153 offset:34816
	ds_read_b128 v[196:199], v153 offset:35840
	ds_read_b128 v[200:203], v153 offset:36864
	ds_read_b128 v[204:207], v153 offset:37888
	ds_read_b128 v[208:211], v153 offset:38912
	ds_read_b128 v[212:215], v153 offset:39936
	global_load_lds_dwordx4 v[224:225], off
	v_lshl_add_u64 v[224:225], s[34:35], 0, v[132:133]
	s_mov_b32 m0, s58
	s_nop 0
	global_load_lds_dwordx4 v[224:225], off
	s_waitcnt vmcnt(8)
	s_waitcnt lgkmcnt(0)
	s_barrier
	s_setprio 1
	v_mfma_f32_16x16x32_bf16 v[124:127], v[144:147], v[184:187], v[124:127]
	v_mfma_f32_16x16x32_bf16 v[120:123], v[160:163], v[184:187], v[120:123]
	v_mfma_f32_16x16x32_bf16 v[108:111], v[144:147], v[192:195], v[108:111]
	v_mfma_f32_16x16x32_bf16 v[104:107], v[160:163], v[192:195], v[104:107]
	v_mfma_f32_16x16x32_bf16 v[92:95], v[144:147], v[200:203], v[92:95]
	v_mfma_f32_16x16x32_bf16 v[88:91], v[160:163], v[200:203], v[88:91]
	v_mfma_f32_16x16x32_bf16 v[76:79], v[144:147], v[208:211], v[76:79]
	v_mfma_f32_16x16x32_bf16 v[72:75], v[160:163], v[208:211], v[72:75]
	v_mfma_f32_16x16x32_bf16 v[124:127], v[156:159], v[188:191], v[124:127]
	v_mfma_f32_16x16x32_bf16 v[120:123], v[164:167], v[188:191], v[120:123]
	v_mfma_f32_16x16x32_bf16 v[108:111], v[156:159], v[196:199], v[108:111]
	v_mfma_f32_16x16x32_bf16 v[104:107], v[164:167], v[196:199], v[104:107]
	v_mfma_f32_16x16x32_bf16 v[92:95], v[156:159], v[204:207], v[92:95]
	v_mfma_f32_16x16x32_bf16 v[88:91], v[164:167], v[204:207], v[88:91]
	v_mfma_f32_16x16x32_bf16 v[76:79], v[156:159], v[212:215], v[76:79]
	v_mfma_f32_16x16x32_bf16 v[72:75], v[164:167], v[212:215], v[72:75]
	s_setprio 0
	s_setprio 1
	v_mfma_f32_16x16x32_bf16 v[116:119], v[168:171], v[184:187], v[116:119]
	v_mfma_f32_16x16x32_bf16 v[112:115], v[176:179], v[184:187], v[112:115]
	v_mfma_f32_16x16x32_bf16 v[100:103], v[168:171], v[192:195], v[100:103]
	v_mfma_f32_16x16x32_bf16 v[96:99], v[176:179], v[192:195], v[96:99]
	v_mfma_f32_16x16x32_bf16 v[84:87], v[168:171], v[200:203], v[84:87]
	v_mfma_f32_16x16x32_bf16 v[80:83], v[176:179], v[200:203], v[80:83]
	v_mfma_f32_16x16x32_bf16 v[68:71], v[168:171], v[208:211], v[68:71]
	v_mfma_f32_16x16x32_bf16 v[64:67], v[176:179], v[208:211], v[64:67]
	v_mfma_f32_16x16x32_bf16 v[116:119], v[172:175], v[188:191], v[116:119]
	v_mfma_f32_16x16x32_bf16 v[112:115], v[180:183], v[188:191], v[112:115]
	v_mfma_f32_16x16x32_bf16 v[100:103], v[172:175], v[196:199], v[100:103]
	v_mfma_f32_16x16x32_bf16 v[96:99], v[180:183], v[196:199], v[96:99]
	v_mfma_f32_16x16x32_bf16 v[84:87], v[172:175], v[204:207], v[84:87]
	v_mfma_f32_16x16x32_bf16 v[80:83], v[180:183], v[204:207], v[80:83]
	v_mfma_f32_16x16x32_bf16 v[68:71], v[172:175], v[212:215], v[68:71]
	v_mfma_f32_16x16x32_bf16 v[64:67], v[180:183], v[212:215], v[64:67]
	s_setprio 0
	s_barrier
	s_add_i32 s34, s67, s48
	v_lshl_add_u64 v[216:217], v[216:217], 0, s[24:25]
	s_mov_b32 m0, s34
	ds_read_b128 v[184:187], v153 offset:49152
	ds_read_b128 v[188:191], v153 offset:50176
	ds_read_b128 v[192:195], v153 offset:51200
	ds_read_b128 v[196:199], v153 offset:52224
	ds_read_b128 v[200:203], v153 offset:53248
	ds_read_b128 v[204:207], v153 offset:54272
	ds_read_b128 v[208:211], v153 offset:55296
	ds_read_b128 v[212:215], v153 offset:56320
	global_load_lds_dwordx4 v[216:217], off
	s_add_i32 m0, s34, 0x2000
	s_add_u32 s34, s52, 0x160080
	v_lshl_add_u64 v[216:217], v[218:219], 0, s[24:25]
	s_addc_u32 s35, s53, 0
	s_add_i32 s52, s70, s48
	global_load_lds_dwordx4 v[216:217], off
	v_lshl_add_u64 v[216:217], s[34:35], 0, v[130:131]
	s_mov_b32 m0, s52
	s_nop 0
	global_load_lds_dwordx4 v[216:217], off
	v_lshl_add_u64 v[216:217], s[34:35], 0, v[134:135]
	s_add_i32 m0, s52, 0x2000
	s_nop 0
	global_load_lds_dwordx4 v[216:217], off
	v_lshl_add_u64 v[216:217], v[220:221], 0, s[24:25]
	s_mov_b32 m0, s60
	s_nop 0
	global_load_lds_dwordx4 v[216:217], off
	v_lshl_add_u64 v[216:217], v[222:223], 0, s[24:25]
	s_mov_b32 m0, s61
	s_nop 0
	global_load_lds_dwordx4 v[216:217], off
	s_waitcnt vmcnt(8)
	s_waitcnt lgkmcnt(0)
	s_barrier
	s_setprio 1
	v_mfma_f32_16x16x32_bf16 v[60:63], v[144:147], v[184:187], v[60:63]
	v_mfma_f32_16x16x32_bf16 v[56:59], v[160:163], v[184:187], v[56:59]
	v_mfma_f32_16x16x32_bf16 v[44:47], v[144:147], v[192:195], v[44:47]
	v_mfma_f32_16x16x32_bf16 v[40:43], v[160:163], v[192:195], v[40:43]
	v_mfma_f32_16x16x32_bf16 v[28:31], v[144:147], v[200:203], v[28:31]
	v_mfma_f32_16x16x32_bf16 v[24:27], v[160:163], v[200:203], v[24:27]
	v_mfma_f32_16x16x32_bf16 v[12:15], v[144:147], v[208:211], v[12:15]
	v_mfma_f32_16x16x32_bf16 v[8:11], v[160:163], v[208:211], v[8:11]
	v_mfma_f32_16x16x32_bf16 v[60:63], v[156:159], v[188:191], v[60:63]
	v_mfma_f32_16x16x32_bf16 v[56:59], v[164:167], v[188:191], v[56:59]
	v_mfma_f32_16x16x32_bf16 v[44:47], v[156:159], v[196:199], v[44:47]
	v_mfma_f32_16x16x32_bf16 v[40:43], v[164:167], v[196:199], v[40:43]
	v_mfma_f32_16x16x32_bf16 v[28:31], v[156:159], v[204:207], v[28:31]
	v_mfma_f32_16x16x32_bf16 v[24:27], v[164:167], v[204:207], v[24:27]
	v_mfma_f32_16x16x32_bf16 v[12:15], v[156:159], v[212:215], v[12:15]
	v_mfma_f32_16x16x32_bf16 v[8:11], v[164:167], v[212:215], v[8:11]
	s_setprio 0
	s_setprio 1
	v_mfma_f32_16x16x32_bf16 v[52:55], v[168:171], v[184:187], v[52:55]
	v_mfma_f32_16x16x32_bf16 v[48:51], v[176:179], v[184:187], v[48:51]
	v_mfma_f32_16x16x32_bf16 v[36:39], v[168:171], v[192:195], v[36:39]
	v_mfma_f32_16x16x32_bf16 v[32:35], v[176:179], v[192:195], v[32:35]
	v_mfma_f32_16x16x32_bf16 v[20:23], v[168:171], v[200:203], v[20:23]
	v_mfma_f32_16x16x32_bf16 v[16:19], v[176:179], v[200:203], v[16:19]
	v_mfma_f32_16x16x32_bf16 v[4:7], v[168:171], v[208:211], v[4:7]
	v_mfma_f32_16x16x32_bf16 v[0:3], v[176:179], v[208:211], v[0:3]
	v_mfma_f32_16x16x32_bf16 v[52:55], v[172:175], v[188:191], v[52:55]
	v_mfma_f32_16x16x32_bf16 v[48:51], v[180:183], v[188:191], v[48:51]
	v_mfma_f32_16x16x32_bf16 v[36:39], v[172:175], v[196:199], v[36:39]
	v_mfma_f32_16x16x32_bf16 v[32:35], v[180:183], v[196:199], v[32:35]
	v_mfma_f32_16x16x32_bf16 v[20:23], v[172:175], v[204:207], v[20:23]
	v_mfma_f32_16x16x32_bf16 v[16:19], v[180:183], v[204:207], v[16:19]
	v_mfma_f32_16x16x32_bf16 v[4:7], v[172:175], v[212:215], v[4:7]
	v_mfma_f32_16x16x32_bf16 v[0:3], v[180:183], v[212:215], v[0:3]
	s_setprio 0
	s_barrier
	s_add_i32 s66, s66, 2
	s_add_u32 s46, s46, 0x100
	s_addc_u32 s47, s47, 0
	s_cmpk_gt_u32 s66, 0x55
	s_mov_b64 s[34:35], s[36:37]
	s_cbranch_scc0 .LBB0_523
	s_and_b64 vcc, exec, s[26:27]
	s_cbranch_vccz .LBB0_526
	s_barrier

.LBB0_617:
	ds_read_b128 v[146:149], v159
	ds_read_b128 v[150:153], v159 offset:1024
	ds_read_b128 v[164:167], v159 offset:2048
	ds_read_b128 v[168:171], v159 offset:3072
	ds_read_b128 v[172:175], v160
	ds_read_b128 v[176:179], v160 offset:1024
	ds_read_b128 v[180:183], v160 offset:2048
	ds_read_b128 v[184:187], v160 offset:3072
	s_add_u32 s58, s56, 0xfff80080
	s_addc_u32 s59, s57, -1
	s_cmp_eq_u32 s55, 28
	s_cselect_b32 s61, s35, s59
	s_cselect_b32 s60, s46, s58
	s_cselect_b32 s59, s31, s51
	s_cselect_b32 s58, s47, s50
	v_lshl_add_u64 v[154:155], s[56:57], 0, v[140:141]
	s_add_i32 m0, s45, 0xc000
	ds_read_b128 v[188:191], v161
	ds_read_b128 v[192:195], v161 offset:1024
	ds_read_b128 v[196:199], v161 offset:2048
	ds_read_b128 v[200:203], v161 offset:3072
	ds_read_b128 v[204:207], v161 offset:4096
	ds_read_b128 v[208:211], v161 offset:5120
	ds_read_b128 v[212:215], v161 offset:6144
	ds_read_b128 v[216:219], v161 offset:7168
	global_load_lds_dwordx4 v[154:155], off
	v_lshl_add_u64 v[154:155], s[56:57], 0, v[138:139]
	s_add_i32 m0, s45, 0xe000
	s_nop 0
	global_load_lds_dwordx4 v[154:155], off
	s_waitcnt vmcnt(8)
	s_waitcnt lgkmcnt(0)
	s_barrier
	s_setprio 1
	v_mfma_f32_16x16x32_bf16 v[124:127], v[146:149], v[188:191], v[124:127]
	v_mfma_f32_16x16x32_bf16 v[120:123], v[164:167], v[188:191], v[120:123]
	v_mfma_f32_16x16x32_bf16 v[108:111], v[146:149], v[196:199], v[108:111]
	v_mfma_f32_16x16x32_bf16 v[104:107], v[164:167], v[196:199], v[104:107]
	v_mfma_f32_16x16x32_bf16 v[92:95], v[146:149], v[204:207], v[92:95]
	v_mfma_f32_16x16x32_bf16 v[88:91], v[164:167], v[204:207], v[88:91]
	v_mfma_f32_16x16x32_bf16 v[76:79], v[146:149], v[212:215], v[76:79]
	v_mfma_f32_16x16x32_bf16 v[72:75], v[164:167], v[212:215], v[72:75]
	v_mfma_f32_16x16x32_bf16 v[124:127], v[150:153], v[192:195], v[124:127]
	v_mfma_f32_16x16x32_bf16 v[120:123], v[168:171], v[192:195], v[120:123]
	v_mfma_f32_16x16x32_bf16 v[108:111], v[150:153], v[200:203], v[108:111]
	v_mfma_f32_16x16x32_bf16 v[104:107], v[168:171], v[200:203], v[104:107]
	v_mfma_f32_16x16x32_bf16 v[92:95], v[150:153], v[208:211], v[92:95]
	v_mfma_f32_16x16x32_bf16 v[88:91], v[168:171], v[208:211], v[88:91]
	v_mfma_f32_16x16x32_bf16 v[76:79], v[150:153], v[216:219], v[76:79]
	v_mfma_f32_16x16x32_bf16 v[72:75], v[168:171], v[216:219], v[72:75]
	s_setprio 0
	s_setprio 1
	v_mfma_f32_16x16x32_bf16 v[116:119], v[172:175], v[188:191], v[116:119]
	v_mfma_f32_16x16x32_bf16 v[112:115], v[180:183], v[188:191], v[112:115]
	v_mfma_f32_16x16x32_bf16 v[100:103], v[172:175], v[196:199], v[100:103]
	v_mfma_f32_16x16x32_bf16 v[96:99], v[180:183], v[196:199], v[96:99]
	v_mfma_f32_16x16x32_bf16 v[84:87], v[172:175], v[204:207], v[84:87]
	v_mfma_f32_16x16x32_bf16 v[80:83], v[180:183], v[204:207], v[80:83]
	v_mfma_f32_16x16x32_bf16 v[68:71], v[172:175], v[212:215], v[68:71]
	v_mfma_f32_16x16x32_bf16 v[64:67], v[180:183], v[212:215], v[64:67]
	v_mfma_f32_16x16x32_bf16 v[116:119], v[176:179], v[192:195], v[116:119]
	v_mfma_f32_16x16x32_bf16 v[112:115], v[184:187], v[192:195], v[112:115]
	v_mfma_f32_16x16x32_bf16 v[100:103], v[176:179], v[200:203], v[100:103]
	v_mfma_f32_16x16x32_bf16 v[96:99], v[184:187], v[200:203], v[96:99]
	v_mfma_f32_16x16x32_bf16 v[84:87], v[176:179], v[208:211], v[84:87]
	v_mfma_f32_16x16x32_bf16 v[80:83], v[184:187], v[208:211], v[80:83]
	v_mfma_f32_16x16x32_bf16 v[68:71], v[176:179], v[216:219], v[68:71]
	v_mfma_f32_16x16x32_bf16 v[64:67], v[184:187], v[216:219], v[64:67]
	s_setprio 0
	s_barrier
	s_add_i32 s72, s66, s44
	v_lshl_add_u64 v[154:155], s[58:59], 0, v[130:131]
	s_mov_b32 m0, s72
	ds_read_b128 v[188:191], v161 offset:16384
	ds_read_b128 v[192:195], v161 offset:17408
	ds_read_b128 v[196:199], v161 offset:18432
	ds_read_b128 v[200:203], v161 offset:19456
	ds_read_b128 v[204:207], v161 offset:20480
	ds_read_b128 v[208:211], v161 offset:21504
	ds_read_b128 v[212:215], v161 offset:22528
	ds_read_b128 v[216:219], v161 offset:23552
	global_load_lds_dwordx4 v[154:155], off
	s_add_i32 m0, s72, 0x2000
	s_add_u32 s80, s58, 0x80000
	v_lshl_add_u64 v[220:221], s[58:59], 0, v[134:135]
	s_addc_u32 s81, s59, 0
	s_add_i32 s72, s67, s44
	global_load_lds_dwordx4 v[220:221], off
	v_lshl_add_u64 v[222:223], s[80:81], 0, v[130:131]
	s_mov_b32 m0, s72
	v_lshl_add_u64 v[224:225], s[60:61], 0, v[132:133]
	global_load_lds_dwordx4 v[222:223], off
	v_lshl_add_u64 v[222:223], s[80:81], 0, v[134:135]
	s_add_i32 m0, s72, 0x2000
	s_nop 0
	global_load_lds_dwordx4 v[222:223], off
	v_lshl_add_u64 v[222:223], s[60:61], 0, v[128:129]
	s_mov_b32 m0, s45
	s_nop 0
	global_load_lds_dwordx4 v[222:223], off
	s_mov_b32 m0, s48
	s_nop 0
	global_load_lds_dwordx4 v[224:225], off
	s_waitcnt vmcnt(8)
	s_waitcnt lgkmcnt(0)
	s_barrier
	s_setprio 1
	v_mfma_f32_16x16x32_bf16 v[60:63], v[146:149], v[188:191], v[60:63]
	v_mfma_f32_16x16x32_bf16 v[56:59], v[164:167], v[188:191], v[56:59]
	v_mfma_f32_16x16x32_bf16 v[44:47], v[146:149], v[196:199], v[44:47]
	v_mfma_f32_16x16x32_bf16 v[40:43], v[164:167], v[196:199], v[40:43]
	v_mfma_f32_16x16x32_bf16 v[28:31], v[146:149], v[204:207], v[28:31]
	v_mfma_f32_16x16x32_bf16 v[24:27], v[164:167], v[204:207], v[24:27]
	v_mfma_f32_16x16x32_bf16 v[12:15], v[146:149], v[212:215], v[12:15]
	v_mfma_f32_16x16x32_bf16 v[8:11], v[164:167], v[212:215], v[8:11]
	v_mfma_f32_16x16x32_bf16 v[60:63], v[150:153], v[192:195], v[60:63]
	v_mfma_f32_16x16x32_bf16 v[56:59], v[168:171], v[192:195], v[56:59]
	v_mfma_f32_16x16x32_bf16 v[44:47], v[150:153], v[200:203], v[44:47]
	v_mfma_f32_16x16x32_bf16 v[40:43], v[168:171], v[200:203], v[40:43]
	v_mfma_f32_16x16x32_bf16 v[28:31], v[150:153], v[208:211], v[28:31]
	v_mfma_f32_16x16x32_bf16 v[24:27], v[168:171], v[208:211], v[24:27]
	v_mfma_f32_16x16x32_bf16 v[12:15], v[150:153], v[216:219], v[12:15]
	v_mfma_f32_16x16x32_bf16 v[8:11], v[168:171], v[216:219], v[8:11]
	s_setprio 0
	s_setprio 1
	v_mfma_f32_16x16x32_bf16 v[52:55], v[172:175], v[188:191], v[52:55]
	v_mfma_f32_16x16x32_bf16 v[48:51], v[180:183], v[188:191], v[48:51]
	v_mfma_f32_16x16x32_bf16 v[36:39], v[172:175], v[196:199], v[36:39]
	v_mfma_f32_16x16x32_bf16 v[32:35], v[180:183], v[196:199], v[32:35]
	v_mfma_f32_16x16x32_bf16 v[20:23], v[172:175], v[204:207], v[20:23]
	v_mfma_f32_16x16x32_bf16 v[16:19], v[180:183], v[204:207], v[16:19]
	v_mfma_f32_16x16x32_bf16 v[4:7], v[172:175], v[212:215], v[4:7]
	v_mfma_f32_16x16x32_bf16 v[0:3], v[180:183], v[212:215], v[0:3]
	v_mfma_f32_16x16x32_bf16 v[52:55], v[176:179], v[192:195], v[52:55]
	v_mfma_f32_16x16x32_bf16 v[48:51], v[184:187], v[192:195], v[48:51]
	v_mfma_f32_16x16x32_bf16 v[36:39], v[176:179], v[200:203], v[36:39]
	v_mfma_f32_16x16x32_bf16 v[32:35], v[184:187], v[200:203], v[32:35]
	v_mfma_f32_16x16x32_bf16 v[20:23], v[176:179], v[208:211], v[20:23]
	v_mfma_f32_16x16x32_bf16 v[16:19], v[184:187], v[208:211], v[16:19]
	v_mfma_f32_16x16x32_bf16 v[4:7], v[176:179], v[216:219], v[4:7]
	v_mfma_f32_16x16x32_bf16 v[0:3], v[184:187], v[216:219], v[0:3]
	s_setprio 0
	s_barrier
	s_add_i32 s72, 0, 0x18000
	s_add_i32 s78, 0, 0x1c000
	v_add_u32_e32 v168, s72, v157
	v_add_u32_e32 v184, s78, v157
	ds_read_b128 v[146:149], v168
	ds_read_b128 v[150:153], v168 offset:1024
	ds_read_b128 v[164:167], v168 offset:2048
	ds_read_b128 v[168:171], v168 offset:3072
	ds_read_b128 v[172:175], v184
	ds_read_b128 v[176:179], v184 offset:1024
	ds_read_b128 v[180:183], v184 offset:2048
	ds_read_b128 v[184:187], v184 offset:3072
	s_add_u32 s60, s60, 0x80000
	s_addc_u32 s61, s61, 0
	s_mov_b32 m0, s49
	v_lshl_add_u64 v[226:227], s[60:61], 0, v[128:129]
	ds_read_b128 v[188:191], v161 offset:32768
	ds_read_b128 v[192:195], v161 offset:33792
	ds_read_b128 v[196:199], v161 offset:34816
	ds_read_b128 v[200:203], v161 offset:35840
	ds_read_b128 v[204:207], v161 offset:36864
	ds_read_b128 v[208:211], v161 offset:37888
	ds_read_b128 v[212:215], v161 offset:38912
	ds_read_b128 v[216:219], v161 offset:39936
	global_load_lds_dwordx4 v[226:227], off
	v_lshl_add_u64 v[226:227], s[60:61], 0, v[132:133]
	s_mov_b32 m0, s62
	s_nop 0
	global_load_lds_dwordx4 v[226:227], off
	s_waitcnt vmcnt(8)
	s_waitcnt lgkmcnt(0)
	s_barrier
	s_setprio 1
	v_mfma_f32_16x16x32_bf16 v[124:127], v[146:149], v[188:191], v[124:127]
	v_mfma_f32_16x16x32_bf16 v[120:123], v[164:167], v[188:191], v[120:123]
	v_mfma_f32_16x16x32_bf16 v[108:111], v[146:149], v[196:199], v[108:111]
	v_mfma_f32_16x16x32_bf16 v[104:107], v[164:167], v[196:199], v[104:107]
	v_mfma_f32_16x16x32_bf16 v[92:95], v[146:149], v[204:207], v[92:95]
	v_mfma_f32_16x16x32_bf16 v[88:91], v[164:167], v[204:207], v[88:91]
	v_mfma_f32_16x16x32_bf16 v[76:79], v[146:149], v[212:215], v[76:79]
	v_mfma_f32_16x16x32_bf16 v[72:75], v[164:167], v[212:215], v[72:75]
	v_mfma_f32_16x16x32_bf16 v[124:127], v[150:153], v[192:195], v[124:127]
	v_mfma_f32_16x16x32_bf16 v[120:123], v[168:171], v[192:195], v[120:123]
	v_mfma_f32_16x16x32_bf16 v[108:111], v[150:153], v[200:203], v[108:111]
	v_mfma_f32_16x16x32_bf16 v[104:107], v[168:171], v[200:203], v[104:107]
	v_mfma_f32_16x16x32_bf16 v[92:95], v[150:153], v[208:211], v[92:95]
	v_mfma_f32_16x16x32_bf16 v[88:91], v[168:171], v[208:211], v[88:91]
	v_mfma_f32_16x16x32_bf16 v[76:79], v[150:153], v[216:219], v[76:79]
	v_mfma_f32_16x16x32_bf16 v[72:75], v[168:171], v[216:219], v[72:75]
	s_setprio 0
	s_setprio 1
	v_mfma_f32_16x16x32_bf16 v[116:119], v[172:175], v[188:191], v[116:119]
	v_mfma_f32_16x16x32_bf16 v[112:115], v[180:183], v[188:191], v[112:115]
	v_mfma_f32_16x16x32_bf16 v[100:103], v[172:175], v[196:199], v[100:103]
	v_mfma_f32_16x16x32_bf16 v[96:99], v[180:183], v[196:199], v[96:99]
	v_mfma_f32_16x16x32_bf16 v[84:87], v[172:175], v[204:207], v[84:87]
	v_mfma_f32_16x16x32_bf16 v[80:83], v[180:183], v[204:207], v[80:83]
	v_mfma_f32_16x16x32_bf16 v[68:71], v[172:175], v[212:215], v[68:71]
	v_mfma_f32_16x16x32_bf16 v[64:67], v[180:183], v[212:215], v[64:67]
	v_mfma_f32_16x16x32_bf16 v[116:119], v[176:179], v[192:195], v[116:119]
	v_mfma_f32_16x16x32_bf16 v[112:115], v[184:187], v[192:195], v[112:115]
	v_mfma_f32_16x16x32_bf16 v[100:103], v[176:179], v[200:203], v[100:103]
	v_mfma_f32_16x16x32_bf16 v[96:99], v[184:187], v[200:203], v[96:99]
	v_mfma_f32_16x16x32_bf16 v[84:87], v[176:179], v[208:211], v[84:87]
	v_mfma_f32_16x16x32_bf16 v[80:83], v[184:187], v[208:211], v[80:83]
	v_mfma_f32_16x16x32_bf16 v[68:71], v[176:179], v[216:219], v[68:71]
	v_mfma_f32_16x16x32_bf16 v[64:67], v[184:187], v[216:219], v[64:67]
	s_setprio 0
	s_barrier
	s_add_i32 s60, s72, s44
	v_lshl_add_u64 v[154:155], v[154:155], 0, s[24:25]
	s_mov_b32 m0, s60
	ds_read_b128 v[188:191], v161 offset:49152
	ds_read_b128 v[192:195], v161 offset:50176
	ds_read_b128 v[196:199], v161 offset:51200
	ds_read_b128 v[200:203], v161 offset:52224
	ds_read_b128 v[204:207], v161 offset:53248
	ds_read_b128 v[208:211], v161 offset:54272
	ds_read_b128 v[212:215], v161 offset:55296
	ds_read_b128 v[216:219], v161 offset:56320
	global_load_lds_dwordx4 v[154:155], off
	s_add_i32 m0, s60, 0x2000
	s_add_u32 s58, s58, 0x80080
	v_lshl_add_u64 v[154:155], v[220:221], 0, s[24:25]
	s_addc_u32 s59, s59, 0
	s_add_i32 s60, s78, s44
	global_load_lds_dwordx4 v[154:155], off
	v_lshl_add_u64 v[154:155], s[58:59], 0, v[130:131]
	s_mov_b32 m0, s60
	s_nop 0
	global_load_lds_dwordx4 v[154:155], off
	v_lshl_add_u64 v[154:155], s[58:59], 0, v[134:135]
	s_add_i32 m0, s60, 0x2000
	s_nop 0
	global_load_lds_dwordx4 v[154:155], off
	v_lshl_add_u64 v[154:155], v[222:223], 0, s[24:25]
	s_mov_b32 m0, s64
	s_nop 0
	global_load_lds_dwordx4 v[154:155], off
	v_lshl_add_u64 v[154:155], v[224:225], 0, s[24:25]
	s_mov_b32 m0, s65
	s_nop 0
	global_load_lds_dwordx4 v[154:155], off
	s_waitcnt vmcnt(8)
	s_waitcnt lgkmcnt(0)
	s_barrier
	s_setprio 1
	v_mfma_f32_16x16x32_bf16 v[60:63], v[146:149], v[188:191], v[60:63]
	v_mfma_f32_16x16x32_bf16 v[56:59], v[164:167], v[188:191], v[56:59]
	v_mfma_f32_16x16x32_bf16 v[44:47], v[146:149], v[196:199], v[44:47]
	v_mfma_f32_16x16x32_bf16 v[40:43], v[164:167], v[196:199], v[40:43]
	v_mfma_f32_16x16x32_bf16 v[28:31], v[146:149], v[204:207], v[28:31]
	v_mfma_f32_16x16x32_bf16 v[24:27], v[164:167], v[204:207], v[24:27]
	v_mfma_f32_16x16x32_bf16 v[12:15], v[146:149], v[212:215], v[12:15]
	v_mfma_f32_16x16x32_bf16 v[8:11], v[164:167], v[212:215], v[8:11]
	v_mfma_f32_16x16x32_bf16 v[60:63], v[150:153], v[192:195], v[60:63]
	v_mfma_f32_16x16x32_bf16 v[56:59], v[168:171], v[192:195], v[56:59]
	v_mfma_f32_16x16x32_bf16 v[44:47], v[150:153], v[200:203], v[44:47]
	v_mfma_f32_16x16x32_bf16 v[40:43], v[168:171], v[200:203], v[40:43]
	v_mfma_f32_16x16x32_bf16 v[28:31], v[150:153], v[208:211], v[28:31]
	v_mfma_f32_16x16x32_bf16 v[24:27], v[168:171], v[208:211], v[24:27]
	v_mfma_f32_16x16x32_bf16 v[12:15], v[150:153], v[216:219], v[12:15]
	v_mfma_f32_16x16x32_bf16 v[8:11], v[168:171], v[216:219], v[8:11]
	s_setprio 0
	s_setprio 1
	v_mfma_f32_16x16x32_bf16 v[52:55], v[172:175], v[188:191], v[52:55]
	v_mfma_f32_16x16x32_bf16 v[48:51], v[180:183], v[188:191], v[48:51]
	v_mfma_f32_16x16x32_bf16 v[36:39], v[172:175], v[196:199], v[36:39]
	v_mfma_f32_16x16x32_bf16 v[32:35], v[180:183], v[196:199], v[32:35]
	v_mfma_f32_16x16x32_bf16 v[20:23], v[172:175], v[204:207], v[20:23]
	v_mfma_f32_16x16x32_bf16 v[16:19], v[180:183], v[204:207], v[16:19]
	v_mfma_f32_16x16x32_bf16 v[4:7], v[172:175], v[212:215], v[4:7]
	v_mfma_f32_16x16x32_bf16 v[0:3], v[180:183], v[212:215], v[0:3]
	v_mfma_f32_16x16x32_bf16 v[52:55], v[176:179], v[192:195], v[52:55]
	v_mfma_f32_16x16x32_bf16 v[48:51], v[184:187], v[192:195], v[48:51]
	v_mfma_f32_16x16x32_bf16 v[36:39], v[176:179], v[200:203], v[36:39]
	v_mfma_f32_16x16x32_bf16 v[32:35], v[184:187], v[200:203], v[32:35]
	v_mfma_f32_16x16x32_bf16 v[20:23], v[176:179], v[208:211], v[20:23]
	v_mfma_f32_16x16x32_bf16 v[16:19], v[184:187], v[208:211], v[16:19]
	v_mfma_f32_16x16x32_bf16 v[4:7], v[176:179], v[216:219], v[4:7]
	v_mfma_f32_16x16x32_bf16 v[0:3], v[184:187], v[216:219], v[0:3]
	s_setprio 0
	s_barrier
	s_add_i32 s55, s55, 2
	s_add_u32 s50, s50, 0x100
	s_addc_u32 s51, s51, 0
	s_add_u32 s56, s56, 0x100
	s_addc_u32 s57, s57, 0
	s_cmp_gt_u32 s55, 29
	s_cbranch_scc0 .LBB0_617
	s_and_b64 vcc, exec, s[26:27]
	s_cbranch_vccz .LBB0_620
	s_barrier

.LBB0_708:
	ds_read_b128 v[0:3], v145
	ds_read_b128 v[4:7], v145 offset:1024
	ds_read_b128 v[8:11], v145 offset:2048
	ds_read_b128 v[12:15], v145 offset:3072
	ds_read_b128 v[16:19], v146
	ds_read_b128 v[20:23], v146 offset:1024
	ds_read_b128 v[24:27], v146 offset:2048
	ds_read_b128 v[28:31], v146 offset:3072
	s_ashr_i32 s37, s36, 31
	s_lshl_b64 s[52:53], s[36:37], 17
	s_add_u32 s52, s6, s52
	s_addc_u32 s53, s7, s53
	s_and_b64 s[54:55], s[8:9], exec
	s_cselect_b32 s65, s53, s59
	s_cselect_b32 s64, s52, s58
	s_ashr_i32 s35, s34, 31
	s_lshl_b64 s[54:55], s[34:35], 17
	s_add_u32 s54, s44, s54
	s_addc_u32 s55, s45, s55
	s_and_b64 s[62:63], s[8:9], exec
	s_cselect_b32 s63, s55, s61
	s_cselect_b32 s62, s54, s60
	s_add_u32 s86, s58, 0x10080
	s_addc_u32 s87, s59, 0
	s_mov_b32 m0, s72
	v_lshl_add_u64 v[64:65], s[86:87], 0, v[128:129]
	ds_read_b128 v[32:35], v147
	ds_read_b128 v[36:39], v147 offset:1024
	ds_read_b128 v[40:43], v147 offset:2048
	ds_read_b128 v[44:47], v147 offset:3072
	ds_read_b128 v[48:51], v147 offset:4096
	ds_read_b128 v[52:55], v147 offset:5120
	ds_read_b128 v[56:59], v147 offset:6144
	ds_read_b128 v[60:63], v147 offset:7168
	global_load_lds_dwordx4 v[64:65], off
	v_lshl_add_u64 v[64:65], s[86:87], 0, v[132:133]
	s_mov_b32 m0, s80
	s_nop 0
	global_load_lds_dwordx4 v[64:65], off
	s_waitcnt vmcnt(8)
	s_waitcnt lgkmcnt(0)
	s_barrier
	s_setprio 1
	v_mfma_f32_16x16x32_bf16 v[64:67], v[0:3], v[32:35], 0
	v_mfma_f32_16x16x32_bf16 v[68:71], v[8:11], v[32:35], 0
	v_mfma_f32_16x16x32_bf16 v[72:75], v[0:3], v[40:43], 0
	v_mfma_f32_16x16x32_bf16 v[76:79], v[8:11], v[40:43], 0
	v_mfma_f32_16x16x32_bf16 v[80:83], v[0:3], v[48:51], 0
	v_mfma_f32_16x16x32_bf16 v[84:87], v[8:11], v[48:51], 0
	v_mfma_f32_16x16x32_bf16 v[88:91], v[0:3], v[56:59], 0
	v_mfma_f32_16x16x32_bf16 v[92:95], v[8:11], v[56:59], 0
	v_mfma_f32_16x16x32_bf16 v[64:67], v[4:7], v[36:39], v[64:67]
	v_mfma_f32_16x16x32_bf16 v[68:71], v[12:15], v[36:39], v[68:71]
	v_mfma_f32_16x16x32_bf16 v[72:75], v[4:7], v[44:47], v[72:75]
	v_mfma_f32_16x16x32_bf16 v[76:79], v[12:15], v[44:47], v[76:79]
	v_mfma_f32_16x16x32_bf16 v[80:83], v[4:7], v[52:55], v[80:83]
	v_mfma_f32_16x16x32_bf16 v[84:87], v[12:15], v[52:55], v[84:87]
	v_mfma_f32_16x16x32_bf16 v[88:91], v[4:7], v[60:63], v[88:91]
	v_mfma_f32_16x16x32_bf16 v[92:95], v[12:15], v[60:63], v[92:95]
	s_setprio 0
	s_setprio 1
	v_mfma_f32_16x16x32_bf16 v[96:99], v[16:19], v[32:35], 0
	v_mfma_f32_16x16x32_bf16 v[32:35], v[24:27], v[32:35], 0
	v_mfma_f32_16x16x32_bf16 v[96:99], v[20:23], v[36:39], v[96:99]
	v_mfma_f32_16x16x32_bf16 v[32:35], v[28:31], v[36:39], v[32:35]
	v_mfma_f32_16x16x32_bf16 v[36:39], v[16:19], v[40:43], 0
	v_mfma_f32_16x16x32_bf16 v[40:43], v[24:27], v[40:43], 0
	v_mfma_f32_16x16x32_bf16 v[36:39], v[20:23], v[44:47], v[36:39]
	v_mfma_f32_16x16x32_bf16 v[40:43], v[28:31], v[44:47], v[40:43]
	v_mfma_f32_16x16x32_bf16 v[44:47], v[16:19], v[48:51], 0
	v_mfma_f32_16x16x32_bf16 v[48:51], v[24:27], v[48:51], 0
	v_mfma_f32_16x16x32_bf16 v[44:47], v[20:23], v[52:55], v[44:47]
	v_mfma_f32_16x16x32_bf16 v[48:51], v[28:31], v[52:55], v[48:51]
	v_mfma_f32_16x16x32_bf16 v[52:55], v[16:19], v[56:59], 0
	v_mfma_f32_16x16x32_bf16 v[56:59], v[24:27], v[56:59], 0
	v_mfma_f32_16x16x32_bf16 v[52:55], v[20:23], v[60:63], v[52:55]
	v_mfma_f32_16x16x32_bf16 v[56:59], v[28:31], v[60:63], v[56:59]
	s_setprio 0
	s_barrier
	s_add_i32 s85, s70, s48
	v_lshl_add_u64 v[140:141], s[60:61], 0, v[130:131]
	s_add_i32 s35, s85, 0x2000
	v_lshl_add_u64 v[148:149], v[140:141], 0, s[20:21]
	s_mov_b32 m0, s85
	v_lshl_add_u64 v[212:213], s[60:61], 0, v[134:135]
	s_add_u32 s86, s60, 0x10100
	ds_read_b128 v[60:63], v147 offset:16384
	ds_read_b128 v[100:103], v147 offset:17408
	ds_read_b128 v[104:107], v147 offset:18432
	ds_read_b128 v[108:111], v147 offset:19456
	ds_read_b128 v[112:115], v147 offset:20480
	ds_read_b128 v[116:119], v147 offset:21504
	ds_read_b128 v[120:123], v147 offset:22528
	ds_read_b128 v[124:127], v147 offset:23552
	global_load_lds_dwordx4 v[148:149], off
	v_lshl_add_u64 v[148:149], v[212:213], 0, s[20:21]
	s_mov_b32 m0, s35
	s_addc_u32 s87, s61, 0
	s_add_i32 s37, s71, s48
	global_load_lds_dwordx4 v[148:149], off
	v_lshl_add_u64 v[148:149], s[86:87], 0, v[130:131]
	s_mov_b32 m0, s37
	s_add_i32 s47, s37, 0x2000
	global_load_lds_dwordx4 v[148:149], off
	v_lshl_add_u64 v[148:149], s[86:87], 0, v[134:135]
	s_mov_b32 m0, s47
	v_lshl_add_u64 v[214:215], s[58:59], 0, v[128:129]
	global_load_lds_dwordx4 v[148:149], off
	v_lshl_add_u64 v[148:149], v[214:215], 0, s[20:21]
	s_mov_b32 m0, s49
	v_lshl_add_u64 v[216:217], s[58:59], 0, v[132:133]
	global_load_lds_dwordx4 v[148:149], off
	v_lshl_add_u64 v[148:149], v[216:217], 0, s[20:21]
	s_mov_b32 m0, s50
	s_nop 0
	global_load_lds_dwordx4 v[148:149], off
	s_waitcnt vmcnt(8)
	s_waitcnt lgkmcnt(0)
	s_barrier
	s_setprio 1
	v_mfma_f32_16x16x32_bf16 v[148:151], v[0:3], v[60:63], 0
	v_mfma_f32_16x16x32_bf16 v[156:159], v[0:3], v[104:107], 0
	v_mfma_f32_16x16x32_bf16 v[164:167], v[0:3], v[112:115], 0
	v_mfma_f32_16x16x32_bf16 v[0:3], v[0:3], v[120:123], 0
	v_mfma_f32_16x16x32_bf16 v[148:151], v[4:7], v[100:103], v[148:151]
	v_mfma_f32_16x16x32_bf16 v[156:159], v[4:7], v[108:111], v[156:159]
	v_mfma_f32_16x16x32_bf16 v[164:167], v[4:7], v[116:119], v[164:167]
	v_mfma_f32_16x16x32_bf16 v[0:3], v[4:7], v[124:127], v[0:3]
	v_mfma_f32_16x16x32_bf16 v[4:7], v[8:11], v[120:123], 0
	v_mfma_f32_16x16x32_bf16 v[152:155], v[8:11], v[60:63], 0
	v_mfma_f32_16x16x32_bf16 v[160:163], v[8:11], v[104:107], 0
	v_mfma_f32_16x16x32_bf16 v[168:171], v[8:11], v[112:115], 0
	v_mfma_f32_16x16x32_bf16 v[4:7], v[12:15], v[124:127], v[4:7]
	v_mfma_f32_16x16x32_bf16 v[152:155], v[12:15], v[100:103], v[152:155]
	v_mfma_f32_16x16x32_bf16 v[160:163], v[12:15], v[108:111], v[160:163]
	v_mfma_f32_16x16x32_bf16 v[168:171], v[12:15], v[116:119], v[168:171]
	s_setprio 0
	s_setprio 1
	v_mfma_f32_16x16x32_bf16 v[8:11], v[16:19], v[60:63], 0
	v_mfma_f32_16x16x32_bf16 v[12:15], v[24:27], v[60:63], 0
	v_mfma_f32_16x16x32_bf16 v[8:11], v[20:23], v[100:103], v[8:11]
	v_mfma_f32_16x16x32_bf16 v[12:15], v[28:31], v[100:103], v[12:15]
	v_mfma_f32_16x16x32_bf16 v[60:63], v[16:19], v[104:107], 0
	v_mfma_f32_16x16x32_bf16 v[100:103], v[24:27], v[104:107], 0
	v_mfma_f32_16x16x32_bf16 v[104:107], v[16:19], v[112:115], 0
	v_mfma_f32_16x16x32_bf16 v[16:19], v[16:19], v[120:123], 0
	v_mfma_f32_16x16x32_bf16 v[60:63], v[20:23], v[108:111], v[60:63]
	v_mfma_f32_16x16x32_bf16 v[100:103], v[28:31], v[108:111], v[100:103]
	v_mfma_f32_16x16x32_bf16 v[104:107], v[20:23], v[116:119], v[104:107]
	v_mfma_f32_16x16x32_bf16 v[108:111], v[24:27], v[112:115], 0
	v_mfma_f32_16x16x32_bf16 v[16:19], v[20:23], v[124:127], v[16:19]
	v_mfma_f32_16x16x32_bf16 v[20:23], v[24:27], v[120:123], 0
	v_mfma_f32_16x16x32_bf16 v[108:111], v[28:31], v[116:119], v[108:111]
	v_mfma_f32_16x16x32_bf16 v[20:23], v[28:31], v[124:127], v[20:23]
	s_setprio 0
	s_barrier
	s_add_i32 s78, 0, 0x18000
	s_add_i32 s79, 0, 0x1c000
	v_add_u32_e32 v224, s78, v143
	v_add_u32_e32 v232, s79, v143
	ds_read_b128 v[24:27], v224
	ds_read_b128 v[28:31], v224 offset:1024
	ds_read_b128 v[112:115], v224 offset:2048
	ds_read_b128 v[116:119], v224 offset:3072
	ds_read_b128 v[120:123], v232
	ds_read_b128 v[124:127], v232 offset:1024
	ds_read_b128 v[172:175], v232 offset:2048
	ds_read_b128 v[176:179], v232 offset:3072
	s_add_u32 s86, s58, 0x10100
	s_addc_u32 s87, s59, 0
	s_mov_b32 m0, s51
	v_lshl_add_u64 v[218:219], s[86:87], 0, v[128:129]
	ds_read_b128 v[180:183], v147 offset:32768
	ds_read_b128 v[184:187], v147 offset:33792
	ds_read_b128 v[188:191], v147 offset:34816
	ds_read_b128 v[192:195], v147 offset:35840
	ds_read_b128 v[196:199], v147 offset:36864
	ds_read_b128 v[200:203], v147 offset:37888
	ds_read_b128 v[204:207], v147 offset:38912
	ds_read_b128 v[208:211], v147 offset:39936
	global_load_lds_dwordx4 v[218:219], off
	v_lshl_add_u64 v[218:219], s[86:87], 0, v[132:133]
	s_mov_b32 m0, s57
	s_nop 0
	global_load_lds_dwordx4 v[218:219], off
	s_waitcnt vmcnt(8)
	s_waitcnt lgkmcnt(0)
	s_barrier
	s_setprio 1
	v_mfma_f32_16x16x32_bf16 v[64:67], v[24:27], v[180:183], v[64:67]
	v_mfma_f32_16x16x32_bf16 v[68:71], v[112:115], v[180:183], v[68:71]
	v_mfma_f32_16x16x32_bf16 v[72:75], v[24:27], v[188:191], v[72:75]
	v_mfma_f32_16x16x32_bf16 v[76:79], v[112:115], v[188:191], v[76:79]
	v_mfma_f32_16x16x32_bf16 v[80:83], v[24:27], v[196:199], v[80:83]
	v_mfma_f32_16x16x32_bf16 v[84:87], v[112:115], v[196:199], v[84:87]
	v_mfma_f32_16x16x32_bf16 v[88:91], v[24:27], v[204:207], v[88:91]
	v_mfma_f32_16x16x32_bf16 v[92:95], v[112:115], v[204:207], v[92:95]
	v_mfma_f32_16x16x32_bf16 v[64:67], v[28:31], v[184:187], v[64:67]
	v_mfma_f32_16x16x32_bf16 v[68:71], v[116:119], v[184:187], v[68:71]
	v_mfma_f32_16x16x32_bf16 v[72:75], v[28:31], v[192:195], v[72:75]
	v_mfma_f32_16x16x32_bf16 v[76:79], v[116:119], v[192:195], v[76:79]
	v_mfma_f32_16x16x32_bf16 v[80:83], v[28:31], v[200:203], v[80:83]
	v_mfma_f32_16x16x32_bf16 v[84:87], v[116:119], v[200:203], v[84:87]
	v_mfma_f32_16x16x32_bf16 v[88:91], v[28:31], v[208:211], v[88:91]
	v_mfma_f32_16x16x32_bf16 v[92:95], v[116:119], v[208:211], v[92:95]
	s_setprio 0
	s_setprio 1
	v_mfma_f32_16x16x32_bf16 v[96:99], v[120:123], v[180:183], v[96:99]
	v_mfma_f32_16x16x32_bf16 v[32:35], v[172:175], v[180:183], v[32:35]
	v_mfma_f32_16x16x32_bf16 v[36:39], v[120:123], v[188:191], v[36:39]
	v_mfma_f32_16x16x32_bf16 v[40:43], v[172:175], v[188:191], v[40:43]
	v_mfma_f32_16x16x32_bf16 v[44:47], v[120:123], v[196:199], v[44:47]
	v_mfma_f32_16x16x32_bf16 v[48:51], v[172:175], v[196:199], v[48:51]
	v_mfma_f32_16x16x32_bf16 v[52:55], v[120:123], v[204:207], v[52:55]
	v_mfma_f32_16x16x32_bf16 v[56:59], v[172:175], v[204:207], v[56:59]
	v_mfma_f32_16x16x32_bf16 v[96:99], v[124:127], v[184:187], v[96:99]
	v_mfma_f32_16x16x32_bf16 v[32:35], v[176:179], v[184:187], v[32:35]
	v_mfma_f32_16x16x32_bf16 v[36:39], v[124:127], v[192:195], v[36:39]
	v_mfma_f32_16x16x32_bf16 v[40:43], v[176:179], v[192:195], v[40:43]
	v_mfma_f32_16x16x32_bf16 v[44:47], v[124:127], v[200:203], v[44:47]
	v_mfma_f32_16x16x32_bf16 v[48:51], v[176:179], v[200:203], v[48:51]
	v_mfma_f32_16x16x32_bf16 v[52:55], v[124:127], v[208:211], v[52:55]
	v_mfma_f32_16x16x32_bf16 v[56:59], v[176:179], v[208:211], v[56:59]
	s_setprio 0
	s_barrier
	s_add_i32 s87, s78, s48
	s_add_i32 s86, s87, 0x2000
	v_lshl_add_u64 v[140:141], v[140:141], 0, s[22:23]
	s_mov_b32 m0, s87
	s_add_u32 s88, s60, 0x10180
	ds_read_b128 v[180:183], v147 offset:49152
	ds_read_b128 v[184:187], v147 offset:50176
	ds_read_b128 v[188:191], v147 offset:51200
	ds_read_b128 v[192:195], v147 offset:52224
	ds_read_b128 v[196:199], v147 offset:53248
	ds_read_b128 v[200:203], v147 offset:54272
	ds_read_b128 v[204:207], v147 offset:55296
	ds_read_b128 v[208:211], v147 offset:56320
	global_load_lds_dwordx4 v[140:141], off
	v_lshl_add_u64 v[140:141], v[212:213], 0, s[22:23]
	s_mov_b32 m0, s86
	s_addc_u32 s89, s61, 0
	s_add_i32 s60, s79, s48
	global_load_lds_dwordx4 v[140:141], off
	v_lshl_add_u64 v[140:141], s[88:89], 0, v[130:131]
	s_mov_b32 m0, s60
	s_add_i32 s61, s60, 0x2000
	global_load_lds_dwordx4 v[140:141], off
	v_lshl_add_u64 v[140:141], s[88:89], 0, v[134:135]
	s_mov_b32 m0, s61
	s_nop 0
	global_load_lds_dwordx4 v[140:141], off
	v_lshl_add_u64 v[140:141], v[214:215], 0, s[22:23]
	s_mov_b32 m0, s66
	s_nop 0
	global_load_lds_dwordx4 v[140:141], off
	v_lshl_add_u64 v[140:141], v[216:217], 0, s[22:23]
	s_mov_b32 m0, s67
	s_nop 0
	global_load_lds_dwordx4 v[140:141], off
	s_waitcnt vmcnt(8)
	s_waitcnt lgkmcnt(0)
	s_barrier
	s_setprio 1
	v_mfma_f32_16x16x32_bf16 v[0:3], v[24:27], v[204:207], v[0:3]
	v_mfma_f32_16x16x32_bf16 v[4:7], v[112:115], v[204:207], v[4:7]
	v_mfma_f32_16x16x32_bf16 v[148:151], v[24:27], v[180:183], v[148:151]
	v_mfma_f32_16x16x32_bf16 v[152:155], v[112:115], v[180:183], v[152:155]
	v_mfma_f32_16x16x32_bf16 v[156:159], v[24:27], v[188:191], v[156:159]
	v_mfma_f32_16x16x32_bf16 v[160:163], v[112:115], v[188:191], v[160:163]
	v_mfma_f32_16x16x32_bf16 v[164:167], v[24:27], v[196:199], v[164:167]
	v_mfma_f32_16x16x32_bf16 v[168:171], v[112:115], v[196:199], v[168:171]
	v_mfma_f32_16x16x32_bf16 v[0:3], v[28:31], v[208:211], v[0:3]
	v_mfma_f32_16x16x32_bf16 v[4:7], v[116:119], v[208:211], v[4:7]
	v_mfma_f32_16x16x32_bf16 v[148:151], v[28:31], v[184:187], v[148:151]
	v_mfma_f32_16x16x32_bf16 v[152:155], v[116:119], v[184:187], v[152:155]
	v_mfma_f32_16x16x32_bf16 v[156:159], v[28:31], v[192:195], v[156:159]
	v_mfma_f32_16x16x32_bf16 v[160:163], v[116:119], v[192:195], v[160:163]
	v_mfma_f32_16x16x32_bf16 v[164:167], v[28:31], v[200:203], v[164:167]
	v_mfma_f32_16x16x32_bf16 v[168:171], v[116:119], v[200:203], v[168:171]
	s_setprio 0
	s_setprio 1
	v_mfma_f32_16x16x32_bf16 v[8:11], v[120:123], v[180:183], v[8:11]
	v_mfma_f32_16x16x32_bf16 v[12:15], v[172:175], v[180:183], v[12:15]
	v_mfma_f32_16x16x32_bf16 v[24:27], v[120:123], v[188:191], v[60:63]
	v_mfma_f32_16x16x32_bf16 v[28:31], v[172:175], v[188:191], v[100:103]
	v_mfma_f32_16x16x32_bf16 v[60:63], v[120:123], v[196:199], v[104:107]
	v_mfma_f32_16x16x32_bf16 v[100:103], v[172:175], v[196:199], v[108:111]
	v_mfma_f32_16x16x32_bf16 v[16:19], v[120:123], v[204:207], v[16:19]
	v_mfma_f32_16x16x32_bf16 v[20:23], v[172:175], v[204:207], v[20:23]
	v_mfma_f32_16x16x32_bf16 v[8:11], v[124:127], v[184:187], v[8:11]
	v_mfma_f32_16x16x32_bf16 v[12:15], v[176:179], v[184:187], v[12:15]
	v_mfma_f32_16x16x32_bf16 v[24:27], v[124:127], v[192:195], v[24:27]
	v_mfma_f32_16x16x32_bf16 v[28:31], v[176:179], v[192:195], v[28:31]
	v_mfma_f32_16x16x32_bf16 v[60:63], v[124:127], v[200:203], v[60:63]
	v_mfma_f32_16x16x32_bf16 v[100:103], v[176:179], v[200:203], v[100:103]
	v_mfma_f32_16x16x32_bf16 v[16:19], v[124:127], v[208:211], v[16:19]
	v_mfma_f32_16x16x32_bf16 v[20:23], v[176:179], v[208:211], v[20:23]
	s_setprio 0
	s_barrier
	ds_read_b128 v[104:107], v145
	ds_read_b128 v[108:111], v145 offset:1024
	ds_read_b128 v[112:115], v145 offset:2048
	ds_read_b128 v[116:119], v145 offset:3072
	ds_read_b128 v[120:123], v146
	ds_read_b128 v[124:127], v146 offset:1024
	ds_read_b128 v[172:175], v146 offset:2048
	ds_read_b128 v[176:179], v146 offset:3072
	s_add_u32 s58, s58, 0x10180
	s_addc_u32 s59, s59, 0
	s_mov_b32 m0, s72
	v_lshl_add_u64 v[140:141], s[58:59], 0, v[128:129]
	ds_read_b128 v[180:183], v147
	ds_read_b128 v[184:187], v147 offset:1024
	ds_read_b128 v[188:191], v147 offset:2048
	ds_read_b128 v[192:195], v147 offset:3072
	ds_read_b128 v[196:199], v147 offset:4096
	ds_read_b128 v[200:203], v147 offset:5120
	ds_read_b128 v[204:207], v147 offset:6144
	ds_read_b128 v[208:211], v147 offset:7168
	global_load_lds_dwordx4 v[140:141], off
	v_lshl_add_u64 v[140:141], s[58:59], 0, v[132:133]
	s_mov_b32 m0, s80
	s_nop 0
	global_load_lds_dwordx4 v[140:141], off
	s_waitcnt vmcnt(8)
	s_waitcnt lgkmcnt(0)
	s_barrier
	s_setprio 1
	v_mfma_f32_16x16x32_bf16 v[88:91], v[104:107], v[204:207], v[88:91]
	v_mfma_f32_16x16x32_bf16 v[64:67], v[104:107], v[180:183], v[64:67]
	v_mfma_f32_16x16x32_bf16 v[68:71], v[112:115], v[180:183], v[68:71]
	v_mfma_f32_16x16x32_bf16 v[72:75], v[104:107], v[188:191], v[72:75]
	v_mfma_f32_16x16x32_bf16 v[76:79], v[112:115], v[188:191], v[76:79]
	v_mfma_f32_16x16x32_bf16 v[80:83], v[104:107], v[196:199], v[80:83]
	v_mfma_f32_16x16x32_bf16 v[84:87], v[112:115], v[196:199], v[84:87]
	v_mfma_f32_16x16x32_bf16 v[212:215], v[108:111], v[208:211], v[88:91]
	v_mfma_f32_16x16x32_bf16 v[88:91], v[112:115], v[204:207], v[92:95]
	v_mfma_f32_16x16x32_bf16 v[64:67], v[108:111], v[184:187], v[64:67]
	v_mfma_f32_16x16x32_bf16 v[68:71], v[116:119], v[184:187], v[68:71]
	v_mfma_f32_16x16x32_bf16 v[72:75], v[108:111], v[192:195], v[72:75]
	v_mfma_f32_16x16x32_bf16 v[76:79], v[116:119], v[192:195], v[76:79]
	v_mfma_f32_16x16x32_bf16 v[80:83], v[108:111], v[200:203], v[80:83]
	v_mfma_f32_16x16x32_bf16 v[84:87], v[116:119], v[200:203], v[84:87]
	v_mfma_f32_16x16x32_bf16 v[92:95], v[116:119], v[208:211], v[88:91]
	s_setprio 0
	s_setprio 1
	v_mfma_f32_16x16x32_bf16 v[48:51], v[172:175], v[196:199], v[48:51]
	v_mfma_f32_16x16x32_bf16 v[88:91], v[120:123], v[180:183], v[96:99]
	v_mfma_f32_16x16x32_bf16 v[32:35], v[172:175], v[180:183], v[32:35]
	v_mfma_f32_16x16x32_bf16 v[36:39], v[120:123], v[188:191], v[36:39]
	v_mfma_f32_16x16x32_bf16 v[40:43], v[172:175], v[188:191], v[40:43]
	v_mfma_f32_16x16x32_bf16 v[44:47], v[120:123], v[196:199], v[44:47]
	v_mfma_f32_16x16x32_bf16 v[180:183], v[176:179], v[200:203], v[48:51]
	v_mfma_f32_16x16x32_bf16 v[48:51], v[120:123], v[204:207], v[52:55]
	v_mfma_f32_16x16x32_bf16 v[32:35], v[176:179], v[184:187], v[32:35]
	v_mfma_f32_16x16x32_bf16 v[36:39], v[124:127], v[192:195], v[36:39]
	v_mfma_f32_16x16x32_bf16 v[40:43], v[176:179], v[192:195], v[40:43]
	v_mfma_f32_16x16x32_bf16 v[44:47], v[124:127], v[200:203], v[44:47]
	v_mfma_f32_16x16x32_bf16 v[52:55], v[124:127], v[208:211], v[48:51]
	v_mfma_f32_16x16x32_bf16 v[48:51], v[172:175], v[204:207], v[56:59]
	v_mfma_f32_16x16x32_bf16 v[216:219], v[124:127], v[184:187], v[88:91]
	v_mfma_f32_16x16x32_bf16 v[184:187], v[176:179], v[208:211], v[48:51]
	s_setprio 0
	s_barrier
	s_mov_b32 m0, s85
	v_lshl_add_u64 v[140:141], s[62:63], 0, v[130:131]
	s_add_u32 s58, s62, 0x10000
	s_nop 0
	ds_read_b128 v[48:51], v147 offset:16384
	ds_read_b128 v[56:59], v147 offset:17408
	ds_read_b128 v[88:91], v147 offset:18432
	ds_read_b128 v[96:99], v147 offset:19456
	ds_read_b128 v[188:191], v147 offset:20480
	ds_read_b128 v[192:195], v147 offset:21504
	ds_read_b128 v[196:199], v147 offset:22528
	ds_read_b128 v[200:203], v147 offset:23552
	global_load_lds_dwordx4 v[140:141], off
	v_lshl_add_u64 v[252:253], s[62:63], 0, v[134:135]
	s_mov_b32 m0, s35
	s_addc_u32 s59, s63, 0
	global_load_lds_dwordx4 v[252:253], off
	v_lshl_add_u64 v[204:205], s[58:59], 0, v[130:131]
	s_mov_b32 m0, s37
	v_lshl_add_u64 v[136:137], s[64:65], 0, v[128:129]
	global_load_lds_dwordx4 v[204:205], off
	v_lshl_add_u64 v[204:205], s[58:59], 0, v[134:135]
	s_mov_b32 m0, s47
	v_lshl_add_u64 v[138:139], s[64:65], 0, v[132:133]
	global_load_lds_dwordx4 v[204:205], off
	s_mov_b32 m0, s49
	s_nop 0
	global_load_lds_dwordx4 v[136:137], off
	s_mov_b32 m0, s50
	s_nop 0
	global_load_lds_dwordx4 v[138:139], off
	s_waitcnt vmcnt(8)
	s_waitcnt lgkmcnt(0)
	s_barrier
	s_setprio 1
	v_mfma_f32_16x16x32_bf16 v[0:3], v[104:107], v[196:199], v[0:3]
	v_mfma_f32_16x16x32_bf16 v[4:7], v[112:115], v[196:199], v[4:7]
	v_mfma_f32_16x16x32_bf16 v[148:151], v[104:107], v[48:51], v[148:151]
	v_mfma_f32_16x16x32_bf16 v[152:155], v[112:115], v[48:51], v[152:155]
	v_mfma_f32_16x16x32_bf16 v[156:159], v[104:107], v[88:91], v[156:159]
	v_mfma_f32_16x16x32_bf16 v[160:163], v[112:115], v[88:91], v[160:163]
	v_mfma_f32_16x16x32_bf16 v[164:167], v[104:107], v[188:191], v[164:167]
	v_mfma_f32_16x16x32_bf16 v[168:171], v[112:115], v[188:191], v[168:171]
	v_mfma_f32_16x16x32_bf16 v[0:3], v[108:111], v[200:203], v[0:3]
	v_mfma_f32_16x16x32_bf16 v[4:7], v[116:119], v[200:203], v[4:7]
	v_mfma_f32_16x16x32_bf16 v[148:151], v[108:111], v[56:59], v[148:151]
	v_mfma_f32_16x16x32_bf16 v[152:155], v[116:119], v[56:59], v[152:155]
	v_mfma_f32_16x16x32_bf16 v[156:159], v[108:111], v[96:99], v[156:159]
	v_mfma_f32_16x16x32_bf16 v[160:163], v[116:119], v[96:99], v[160:163]
	v_mfma_f32_16x16x32_bf16 v[164:167], v[108:111], v[192:195], v[164:167]
	v_mfma_f32_16x16x32_bf16 v[168:171], v[116:119], v[192:195], v[168:171]
	s_setprio 0
	s_setprio 1
	v_mfma_f32_16x16x32_bf16 v[12:15], v[172:175], v[48:51], v[12:15]
	v_mfma_f32_16x16x32_bf16 v[204:207], v[176:179], v[56:59], v[12:15]
	v_mfma_f32_16x16x32_bf16 v[12:15], v[120:123], v[88:91], v[24:27]
	v_mfma_f32_16x16x32_bf16 v[24:27], v[124:127], v[96:99], v[12:15]
	v_mfma_f32_16x16x32_bf16 v[12:15], v[172:175], v[88:91], v[28:31]
	v_mfma_f32_16x16x32_bf16 v[208:211], v[176:179], v[96:99], v[12:15]
	v_mfma_f32_16x16x32_bf16 v[12:15], v[120:123], v[188:191], v[60:63]
	v_mfma_f32_16x16x32_bf16 v[220:223], v[124:127], v[192:195], v[12:15]
	v_mfma_f32_16x16x32_bf16 v[12:15], v[172:175], v[188:191], v[100:103]
	v_mfma_f32_16x16x32_bf16 v[8:11], v[120:123], v[48:51], v[8:11]
	v_mfma_f32_16x16x32_bf16 v[188:191], v[176:179], v[192:195], v[12:15]
	v_mfma_f32_16x16x32_bf16 v[12:15], v[120:123], v[196:199], v[16:19]
	v_mfma_f32_16x16x32_bf16 v[8:11], v[124:127], v[56:59], v[8:11]
	v_mfma_f32_16x16x32_bf16 v[192:195], v[124:127], v[200:203], v[12:15]
	v_mfma_f32_16x16x32_bf16 v[12:15], v[172:175], v[196:199], v[20:23]
	v_mfma_f32_16x16x32_bf16 v[172:175], v[176:179], v[200:203], v[12:15]
	s_setprio 0
	s_barrier
	s_nop 4
	ds_read_b128 v[12:15], v224
	ds_read_b128 v[16:19], v224 offset:1024
	ds_read_b128 v[176:179], v224 offset:2048
	ds_read_b128 v[196:199], v224 offset:3072
	ds_read_b128 v[200:203], v232
	ds_read_b128 v[224:227], v232 offset:1024
	ds_read_b128 v[228:231], v232 offset:2048
	ds_read_b128 v[232:235], v232 offset:3072
	s_add_u32 s58, s64, 0x10000
	s_addc_u32 s59, s65, 0
	s_mov_b32 m0, s51
	v_lshl_add_u64 v[48:49], s[58:59], 0, v[128:129]
	ds_read_b128 v[20:23], v147 offset:32768
	ds_read_b128 v[28:31], v147 offset:33792
	ds_read_b128 v[60:63], v147 offset:34816
	ds_read_b128 v[100:103], v147 offset:35840
	ds_read_b128 v[236:239], v147 offset:36864
	ds_read_b128 v[240:243], v147 offset:37888
	ds_read_b128 v[244:247], v147 offset:38912
	ds_read_b128 v[248:251], v147 offset:39936
	global_load_lds_dwordx4 v[48:49], off
	v_lshl_add_u64 v[48:49], s[58:59], 0, v[132:133]
	s_mov_b32 m0, s57
	s_nop 0
	global_load_lds_dwordx4 v[48:49], off
	s_waitcnt vmcnt(8)
	s_waitcnt lgkmcnt(0)
	s_barrier
	s_setprio 1
	v_mfma_f32_16x16x32_bf16 v[48:51], v[12:15], v[20:23], v[64:67]
	v_mfma_f32_16x16x32_bf16 v[120:123], v[16:19], v[28:31], v[48:51]
	v_mfma_f32_16x16x32_bf16 v[48:51], v[176:179], v[20:23], v[68:71]
	v_mfma_f32_16x16x32_bf16 v[112:115], v[196:199], v[28:31], v[48:51]
	v_mfma_f32_16x16x32_bf16 v[48:51], v[12:15], v[60:63], v[72:75]
	v_mfma_f32_16x16x32_bf16 v[104:107], v[16:19], v[100:103], v[48:51]
	v_mfma_f32_16x16x32_bf16 v[48:51], v[176:179], v[60:63], v[76:79]
	v_mfma_f32_16x16x32_bf16 v[96:99], v[196:199], v[100:103], v[48:51]
	v_mfma_f32_16x16x32_bf16 v[48:51], v[12:15], v[236:239], v[80:83]
	v_mfma_f32_16x16x32_bf16 v[88:91], v[16:19], v[240:243], v[48:51]
	v_mfma_f32_16x16x32_bf16 v[48:51], v[176:179], v[236:239], v[84:87]
	v_mfma_f32_16x16x32_bf16 v[80:83], v[196:199], v[240:243], v[48:51]
	v_mfma_f32_16x16x32_bf16 v[48:51], v[12:15], v[244:247], v[212:215]
	v_mfma_f32_16x16x32_bf16 v[56:59], v[16:19], v[248:251], v[48:51]
	v_mfma_f32_16x16x32_bf16 v[48:51], v[176:179], v[244:247], v[92:95]
	v_mfma_f32_16x16x32_bf16 v[48:51], v[196:199], v[248:251], v[48:51]
	s_setprio 0
	s_setprio 1
	v_mfma_f32_16x16x32_bf16 v[64:67], v[200:203], v[20:23], v[216:219]
	v_mfma_f32_16x16x32_bf16 v[20:23], v[228:231], v[20:23], v[32:35]
	v_mfma_f32_16x16x32_bf16 v[116:119], v[232:235], v[28:31], v[20:23]
	v_mfma_f32_16x16x32_bf16 v[20:23], v[200:203], v[60:63], v[36:39]
	v_mfma_f32_16x16x32_bf16 v[108:111], v[224:227], v[100:103], v[20:23]
	v_mfma_f32_16x16x32_bf16 v[20:23], v[228:231], v[60:63], v[40:43]
	v_mfma_f32_16x16x32_bf16 v[100:103], v[232:235], v[100:103], v[20:23]
	v_mfma_f32_16x16x32_bf16 v[20:23], v[200:203], v[236:239], v[44:47]
	v_mfma_f32_16x16x32_bf16 v[92:95], v[224:227], v[240:243], v[20:23]
	v_mfma_f32_16x16x32_bf16 v[20:23], v[228:231], v[236:239], v[180:183]
	v_mfma_f32_16x16x32_bf16 v[84:87], v[232:235], v[240:243], v[20:23]
	v_mfma_f32_16x16x32_bf16 v[20:23], v[200:203], v[244:247], v[52:55]
	v_mfma_f32_16x16x32_bf16 v[60:63], v[224:227], v[248:251], v[20:23]
	v_mfma_f32_16x16x32_bf16 v[20:23], v[228:231], v[244:247], v[184:187]
	v_mfma_f32_16x16x32_bf16 v[124:127], v[224:227], v[28:31], v[64:67]
	v_mfma_f32_16x16x32_bf16 v[52:55], v[232:235], v[248:251], v[20:23]
	s_setprio 0
	s_barrier
	s_mov_b32 m0, s87
	s_nop 2
	v_lshl_add_u64 v[20:21], v[140:141], 0, s[14:15]
	s_add_u32 s58, s62, 0x10080
	ds_read_b128 v[32:35], v147 offset:49152
	ds_read_b128 v[40:43], v147 offset:50176
	ds_read_b128 v[180:183], v147 offset:51200
	ds_read_b128 v[184:187], v147 offset:52224
	ds_read_b128 v[212:215], v147 offset:53248
	ds_read_b128 v[216:219], v147 offset:54272
	ds_read_b128 v[236:239], v147 offset:55296
	ds_read_b128 v[240:243], v147 offset:56320
	global_load_lds_dwordx4 v[20:21], off
	v_lshl_add_u64 v[20:21], v[252:253], 0, s[14:15]
	s_mov_b32 m0, s86
	s_addc_u32 s59, s63, 0
	global_load_lds_dwordx4 v[20:21], off
	v_lshl_add_u64 v[20:21], s[58:59], 0, v[130:131]
	s_mov_b32 m0, s60
	s_nop 0
	global_load_lds_dwordx4 v[20:21], off
	v_lshl_add_u64 v[20:21], s[58:59], 0, v[134:135]
	s_mov_b32 m0, s61
	s_nop 0
	global_load_lds_dwordx4 v[20:21], off
	v_lshl_add_u64 v[20:21], v[136:137], 0, s[14:15]
	s_mov_b32 m0, s66
	s_nop 0
	global_load_lds_dwordx4 v[20:21], off
	v_lshl_add_u64 v[20:21], v[138:139], 0, s[14:15]
	s_mov_b32 m0, s67
	s_nop 0
	global_load_lds_dwordx4 v[20:21], off
	s_waitcnt vmcnt(8)
	s_waitcnt lgkmcnt(0)
	s_barrier
	s_setprio 1
	v_mfma_f32_16x16x32_bf16 v[20:23], v[12:15], v[32:35], v[148:151]
	v_mfma_f32_16x16x32_bf16 v[76:79], v[16:19], v[40:43], v[20:23]
	v_mfma_f32_16x16x32_bf16 v[20:23], v[176:179], v[32:35], v[152:155]
	v_mfma_f32_16x16x32_bf16 v[68:71], v[196:199], v[40:43], v[20:23]
	v_mfma_f32_16x16x32_bf16 v[20:23], v[12:15], v[180:183], v[156:159]
	v_mfma_f32_16x16x32_bf16 v[44:47], v[16:19], v[184:187], v[20:23]
	v_mfma_f32_16x16x32_bf16 v[20:23], v[176:179], v[180:183], v[160:163]
	v_mfma_f32_16x16x32_bf16 v[36:39], v[196:199], v[184:187], v[20:23]
	v_mfma_f32_16x16x32_bf16 v[20:23], v[12:15], v[212:215], v[164:167]
	v_mfma_f32_16x16x32_bf16 v[0:3], v[12:15], v[236:239], v[0:3]
	v_mfma_f32_16x16x32_bf16 v[28:31], v[16:19], v[216:219], v[20:23]
	v_mfma_f32_16x16x32_bf16 v[20:23], v[176:179], v[212:215], v[168:171]
	v_mfma_f32_16x16x32_bf16 v[12:15], v[16:19], v[240:243], v[0:3]
	v_mfma_f32_16x16x32_bf16 v[0:3], v[176:179], v[236:239], v[4:7]
	v_mfma_f32_16x16x32_bf16 v[20:23], v[196:199], v[216:219], v[20:23]
	v_mfma_f32_16x16x32_bf16 v[4:7], v[196:199], v[240:243], v[0:3]
	s_setprio 0
	s_setprio 1
	v_mfma_f32_16x16x32_bf16 v[0:3], v[200:203], v[32:35], v[8:11]
	v_mfma_f32_16x16x32_bf16 v[72:75], v[224:227], v[40:43], v[0:3]
	v_mfma_f32_16x16x32_bf16 v[0:3], v[228:231], v[32:35], v[204:207]
	v_mfma_f32_16x16x32_bf16 v[64:67], v[232:235], v[40:43], v[0:3]
	v_mfma_f32_16x16x32_bf16 v[0:3], v[200:203], v[180:183], v[24:27]
	v_mfma_f32_16x16x32_bf16 v[40:43], v[224:227], v[184:187], v[0:3]
	v_mfma_f32_16x16x32_bf16 v[0:3], v[228:231], v[180:183], v[208:211]
	v_mfma_f32_16x16x32_bf16 v[32:35], v[232:235], v[184:187], v[0:3]
	v_mfma_f32_16x16x32_bf16 v[0:3], v[200:203], v[212:215], v[220:223]
	v_mfma_f32_16x16x32_bf16 v[24:27], v[224:227], v[216:219], v[0:3]
	v_mfma_f32_16x16x32_bf16 v[0:3], v[228:231], v[212:215], v[188:191]
	v_mfma_f32_16x16x32_bf16 v[16:19], v[232:235], v[216:219], v[0:3]
	v_mfma_f32_16x16x32_bf16 v[0:3], v[200:203], v[236:239], v[192:195]
	v_mfma_f32_16x16x32_bf16 v[8:11], v[224:227], v[240:243], v[0:3]
	v_mfma_f32_16x16x32_bf16 v[0:3], v[228:231], v[236:239], v[172:175]
	v_mfma_f32_16x16x32_bf16 v[0:3], v[232:235], v[240:243], v[0:3]
	s_setprio 0
	s_barrier
	s_andn2_b64 vcc, exec, s[16:17]
	s_cbranch_vccnz .LBB0_710
	s_barrier

.LBB0_731:
	ds_read_b128 v[146:149], v153
	ds_read_b128 v[158:161], v153 offset:1024
	ds_read_b128 v[162:165], v153 offset:2048
	ds_read_b128 v[166:169], v153 offset:3072
	ds_read_b128 v[170:173], v154
	ds_read_b128 v[174:177], v154 offset:1024
	ds_read_b128 v[178:181], v154 offset:2048
	ds_read_b128 v[182:185], v154 offset:3072
	s_add_u32 s34, s30, 0xfff80080
	s_addc_u32 s35, s31, -1
	s_cmp_eq_u32 s61, 28
	s_cselect_b32 s37, s21, s35
	s_cselect_b32 s36, s46, s34
	s_cselect_b32 s35, s19, s60
	s_cselect_b32 s34, s47, s59
	v_lshl_add_u64 v[218:219], s[30:31], 0, v[140:141]
	s_add_i32 m0, s27, 0xc000
	ds_read_b128 v[186:189], v155
	ds_read_b128 v[190:193], v155 offset:1024
	ds_read_b128 v[194:197], v155 offset:2048
	ds_read_b128 v[198:201], v155 offset:3072
	ds_read_b128 v[202:205], v155 offset:4096
	ds_read_b128 v[206:209], v155 offset:5120
	ds_read_b128 v[210:213], v155 offset:6144
	ds_read_b128 v[214:217], v155 offset:7168
	global_load_lds_dwordx4 v[218:219], off
	v_lshl_add_u64 v[218:219], s[30:31], 0, v[138:139]
	s_add_i32 m0, s27, 0xe000
	s_nop 0
	global_load_lds_dwordx4 v[218:219], off
	s_waitcnt vmcnt(8)
	s_waitcnt lgkmcnt(0)
	s_barrier
	s_setprio 1
	v_mfma_f32_16x16x32_bf16 v[124:127], v[146:149], v[186:189], v[124:127]
	v_mfma_f32_16x16x32_bf16 v[120:123], v[162:165], v[186:189], v[120:123]
	v_mfma_f32_16x16x32_bf16 v[108:111], v[146:149], v[194:197], v[108:111]
	v_mfma_f32_16x16x32_bf16 v[104:107], v[162:165], v[194:197], v[104:107]
	v_mfma_f32_16x16x32_bf16 v[92:95], v[146:149], v[202:205], v[92:95]
	v_mfma_f32_16x16x32_bf16 v[88:91], v[162:165], v[202:205], v[88:91]
	v_mfma_f32_16x16x32_bf16 v[76:79], v[146:149], v[210:213], v[76:79]
	v_mfma_f32_16x16x32_bf16 v[72:75], v[162:165], v[210:213], v[72:75]
	v_mfma_f32_16x16x32_bf16 v[124:127], v[158:161], v[190:193], v[124:127]
	v_mfma_f32_16x16x32_bf16 v[120:123], v[166:169], v[190:193], v[120:123]
	v_mfma_f32_16x16x32_bf16 v[108:111], v[158:161], v[198:201], v[108:111]
	v_mfma_f32_16x16x32_bf16 v[104:107], v[166:169], v[198:201], v[104:107]
	v_mfma_f32_16x16x32_bf16 v[92:95], v[158:161], v[206:209], v[92:95]
	v_mfma_f32_16x16x32_bf16 v[88:91], v[166:169], v[206:209], v[88:91]
	v_mfma_f32_16x16x32_bf16 v[76:79], v[158:161], v[214:217], v[76:79]
	v_mfma_f32_16x16x32_bf16 v[72:75], v[166:169], v[214:217], v[72:75]
	s_setprio 0
	s_setprio 1
	v_mfma_f32_16x16x32_bf16 v[116:119], v[170:173], v[186:189], v[116:119]
	v_mfma_f32_16x16x32_bf16 v[112:115], v[178:181], v[186:189], v[112:115]
	v_mfma_f32_16x16x32_bf16 v[100:103], v[170:173], v[194:197], v[100:103]
	v_mfma_f32_16x16x32_bf16 v[96:99], v[178:181], v[194:197], v[96:99]
	v_mfma_f32_16x16x32_bf16 v[84:87], v[170:173], v[202:205], v[84:87]
	v_mfma_f32_16x16x32_bf16 v[80:83], v[178:181], v[202:205], v[80:83]
	v_mfma_f32_16x16x32_bf16 v[68:71], v[170:173], v[210:213], v[68:71]
	v_mfma_f32_16x16x32_bf16 v[64:67], v[178:181], v[210:213], v[64:67]
	v_mfma_f32_16x16x32_bf16 v[116:119], v[174:177], v[190:193], v[116:119]
	v_mfma_f32_16x16x32_bf16 v[112:115], v[182:185], v[190:193], v[112:115]
	v_mfma_f32_16x16x32_bf16 v[100:103], v[174:177], v[198:201], v[100:103]
	v_mfma_f32_16x16x32_bf16 v[96:99], v[182:185], v[198:201], v[96:99]
	v_mfma_f32_16x16x32_bf16 v[84:87], v[174:177], v[206:209], v[84:87]
	v_mfma_f32_16x16x32_bf16 v[80:83], v[182:185], v[206:209], v[80:83]
	v_mfma_f32_16x16x32_bf16 v[68:71], v[174:177], v[214:217], v[68:71]
	v_mfma_f32_16x16x32_bf16 v[64:67], v[182:185], v[214:217], v[64:67]
	s_setprio 0
	s_barrier
	s_add_i32 s62, s55, s48
	v_lshl_add_u64 v[218:219], s[34:35], 0, v[130:131]
	s_mov_b32 m0, s62
	ds_read_b128 v[186:189], v155 offset:16384
	ds_read_b128 v[190:193], v155 offset:17408
	ds_read_b128 v[194:197], v155 offset:18432
	ds_read_b128 v[198:201], v155 offset:19456
	ds_read_b128 v[202:205], v155 offset:20480
	ds_read_b128 v[206:209], v155 offset:21504
	ds_read_b128 v[210:213], v155 offset:22528
	ds_read_b128 v[214:217], v155 offset:23552
	global_load_lds_dwordx4 v[218:219], off
	s_add_i32 m0, s62, 0x2000
	s_add_u32 s62, s34, 0x80000
	v_lshl_add_u64 v[220:221], s[34:35], 0, v[134:135]
	s_addc_u32 s63, s35, 0
	s_add_i32 s64, s56, s48
	global_load_lds_dwordx4 v[220:221], off
	v_lshl_add_u64 v[222:223], s[62:63], 0, v[130:131]
	s_mov_b32 m0, s64
	v_lshl_add_u64 v[224:225], s[36:37], 0, v[132:133]
	global_load_lds_dwordx4 v[222:223], off
	v_lshl_add_u64 v[222:223], s[62:63], 0, v[134:135]
	s_add_i32 m0, s64, 0x2000
	s_nop 0
	global_load_lds_dwordx4 v[222:223], off
	v_lshl_add_u64 v[222:223], s[36:37], 0, v[128:129]
	s_mov_b32 m0, s27
	s_nop 0
	global_load_lds_dwordx4 v[222:223], off
	s_mov_b32 m0, s49
	s_nop 0
	global_load_lds_dwordx4 v[224:225], off
	s_waitcnt vmcnt(8)
	s_waitcnt lgkmcnt(0)
	s_barrier
	s_setprio 1
	v_mfma_f32_16x16x32_bf16 v[60:63], v[146:149], v[186:189], v[60:63]
	v_mfma_f32_16x16x32_bf16 v[56:59], v[162:165], v[186:189], v[56:59]
	v_mfma_f32_16x16x32_bf16 v[44:47], v[146:149], v[194:197], v[44:47]
	v_mfma_f32_16x16x32_bf16 v[40:43], v[162:165], v[194:197], v[40:43]
	v_mfma_f32_16x16x32_bf16 v[28:31], v[146:149], v[202:205], v[28:31]
	v_mfma_f32_16x16x32_bf16 v[24:27], v[162:165], v[202:205], v[24:27]
	v_mfma_f32_16x16x32_bf16 v[12:15], v[146:149], v[210:213], v[12:15]
	v_mfma_f32_16x16x32_bf16 v[8:11], v[162:165], v[210:213], v[8:11]
	v_mfma_f32_16x16x32_bf16 v[60:63], v[158:161], v[190:193], v[60:63]
	v_mfma_f32_16x16x32_bf16 v[56:59], v[166:169], v[190:193], v[56:59]
	v_mfma_f32_16x16x32_bf16 v[44:47], v[158:161], v[198:201], v[44:47]
	v_mfma_f32_16x16x32_bf16 v[40:43], v[166:169], v[198:201], v[40:43]
	v_mfma_f32_16x16x32_bf16 v[28:31], v[158:161], v[206:209], v[28:31]
	v_mfma_f32_16x16x32_bf16 v[24:27], v[166:169], v[206:209], v[24:27]
	v_mfma_f32_16x16x32_bf16 v[12:15], v[158:161], v[214:217], v[12:15]
	v_mfma_f32_16x16x32_bf16 v[8:11], v[166:169], v[214:217], v[8:11]
	s_setprio 0
	s_setprio 1
	v_mfma_f32_16x16x32_bf16 v[52:55], v[170:173], v[186:189], v[52:55]
	v_mfma_f32_16x16x32_bf16 v[48:51], v[178:181], v[186:189], v[48:51]
	v_mfma_f32_16x16x32_bf16 v[36:39], v[170:173], v[194:197], v[36:39]
	v_mfma_f32_16x16x32_bf16 v[32:35], v[178:181], v[194:197], v[32:35]
	v_mfma_f32_16x16x32_bf16 v[20:23], v[170:173], v[202:205], v[20:23]
	v_mfma_f32_16x16x32_bf16 v[16:19], v[178:181], v[202:205], v[16:19]
	v_mfma_f32_16x16x32_bf16 v[4:7], v[170:173], v[210:213], v[4:7]
	v_mfma_f32_16x16x32_bf16 v[0:3], v[178:181], v[210:213], v[0:3]
	v_mfma_f32_16x16x32_bf16 v[52:55], v[174:177], v[190:193], v[52:55]
	v_mfma_f32_16x16x32_bf16 v[48:51], v[182:185], v[190:193], v[48:51]
	v_mfma_f32_16x16x32_bf16 v[36:39], v[174:177], v[198:201], v[36:39]
	v_mfma_f32_16x16x32_bf16 v[32:35], v[182:185], v[198:201], v[32:35]
	v_mfma_f32_16x16x32_bf16 v[20:23], v[174:177], v[206:209], v[20:23]
	v_mfma_f32_16x16x32_bf16 v[16:19], v[182:185], v[206:209], v[16:19]
	v_mfma_f32_16x16x32_bf16 v[4:7], v[174:177], v[214:217], v[4:7]
	v_mfma_f32_16x16x32_bf16 v[0:3], v[182:185], v[214:217], v[0:3]
	s_setprio 0
	s_barrier
	s_add_i32 s62, 0, 0x18000
	s_add_i32 s63, 0, 0x1c000
	v_add_u32_e32 v166, s62, v151
	v_add_u32_e32 v182, s63, v151
	ds_read_b128 v[146:149], v166
	ds_read_b128 v[158:161], v166 offset:1024
	ds_read_b128 v[162:165], v166 offset:2048
	ds_read_b128 v[166:169], v166 offset:3072
	ds_read_b128 v[170:173], v182
	ds_read_b128 v[174:177], v182 offset:1024
	ds_read_b128 v[178:181], v182 offset:2048
	ds_read_b128 v[182:185], v182 offset:3072
	s_add_u32 s36, s36, 0x80000
	s_addc_u32 s37, s37, 0
	s_mov_b32 m0, s50
	v_lshl_add_u64 v[226:227], s[36:37], 0, v[128:129]
	ds_read_b128 v[186:189], v155 offset:32768
	ds_read_b128 v[190:193], v155 offset:33792
	ds_read_b128 v[194:197], v155 offset:34816
	ds_read_b128 v[198:201], v155 offset:35840
	ds_read_b128 v[202:205], v155 offset:36864
	ds_read_b128 v[206:209], v155 offset:37888
	ds_read_b128 v[210:213], v155 offset:38912
	ds_read_b128 v[214:217], v155 offset:39936
	global_load_lds_dwordx4 v[226:227], off
	v_lshl_add_u64 v[226:227], s[36:37], 0, v[132:133]
	s_mov_b32 m0, s51
	s_nop 0
	global_load_lds_dwordx4 v[226:227], off
	s_waitcnt vmcnt(8)
	s_waitcnt lgkmcnt(0)
	s_barrier
	s_setprio 1
	v_mfma_f32_16x16x32_bf16 v[124:127], v[146:149], v[186:189], v[124:127]
	v_mfma_f32_16x16x32_bf16 v[120:123], v[162:165], v[186:189], v[120:123]
	v_mfma_f32_16x16x32_bf16 v[108:111], v[146:149], v[194:197], v[108:111]
	v_mfma_f32_16x16x32_bf16 v[104:107], v[162:165], v[194:197], v[104:107]
	v_mfma_f32_16x16x32_bf16 v[92:95], v[146:149], v[202:205], v[92:95]
	v_mfma_f32_16x16x32_bf16 v[88:91], v[162:165], v[202:205], v[88:91]
	v_mfma_f32_16x16x32_bf16 v[76:79], v[146:149], v[210:213], v[76:79]
	v_mfma_f32_16x16x32_bf16 v[72:75], v[162:165], v[210:213], v[72:75]
	v_mfma_f32_16x16x32_bf16 v[124:127], v[158:161], v[190:193], v[124:127]
	v_mfma_f32_16x16x32_bf16 v[120:123], v[166:169], v[190:193], v[120:123]
	v_mfma_f32_16x16x32_bf16 v[108:111], v[158:161], v[198:201], v[108:111]
	v_mfma_f32_16x16x32_bf16 v[104:107], v[166:169], v[198:201], v[104:107]
	v_mfma_f32_16x16x32_bf16 v[92:95], v[158:161], v[206:209], v[92:95]
	v_mfma_f32_16x16x32_bf16 v[88:91], v[166:169], v[206:209], v[88:91]
	v_mfma_f32_16x16x32_bf16 v[76:79], v[158:161], v[214:217], v[76:79]
	v_mfma_f32_16x16x32_bf16 v[72:75], v[166:169], v[214:217], v[72:75]
	s_setprio 0
	s_setprio 1
	v_mfma_f32_16x16x32_bf16 v[116:119], v[170:173], v[186:189], v[116:119]
	v_mfma_f32_16x16x32_bf16 v[112:115], v[178:181], v[186:189], v[112:115]
	v_mfma_f32_16x16x32_bf16 v[100:103], v[170:173], v[194:197], v[100:103]
	v_mfma_f32_16x16x32_bf16 v[96:99], v[178:181], v[194:197], v[96:99]
	v_mfma_f32_16x16x32_bf16 v[84:87], v[170:173], v[202:205], v[84:87]
	v_mfma_f32_16x16x32_bf16 v[80:83], v[178:181], v[202:205], v[80:83]
	v_mfma_f32_16x16x32_bf16 v[68:71], v[170:173], v[210:213], v[68:71]
	v_mfma_f32_16x16x32_bf16 v[64:67], v[178:181], v[210:213], v[64:67]
	v_mfma_f32_16x16x32_bf16 v[116:119], v[174:177], v[190:193], v[116:119]
	v_mfma_f32_16x16x32_bf16 v[112:115], v[182:185], v[190:193], v[112:115]
	v_mfma_f32_16x16x32_bf16 v[100:103], v[174:177], v[198:201], v[100:103]
	v_mfma_f32_16x16x32_bf16 v[96:99], v[182:185], v[198:201], v[96:99]
	v_mfma_f32_16x16x32_bf16 v[84:87], v[174:177], v[206:209], v[84:87]
	v_mfma_f32_16x16x32_bf16 v[80:83], v[182:185], v[206:209], v[80:83]
	v_mfma_f32_16x16x32_bf16 v[68:71], v[174:177], v[214:217], v[68:71]
	v_mfma_f32_16x16x32_bf16 v[64:67], v[182:185], v[214:217], v[64:67]
	s_setprio 0
	s_barrier
	s_add_i32 s36, s62, s48
	v_lshl_add_u64 v[218:219], v[218:219], 0, s[14:15]
	s_mov_b32 m0, s36
	ds_read_b128 v[186:189], v155 offset:49152
	ds_read_b128 v[190:193], v155 offset:50176
	ds_read_b128 v[194:197], v155 offset:51200
	ds_read_b128 v[198:201], v155 offset:52224
	ds_read_b128 v[202:205], v155 offset:53248
	ds_read_b128 v[206:209], v155 offset:54272
	ds_read_b128 v[210:213], v155 offset:55296
	ds_read_b128 v[214:217], v155 offset:56320
	global_load_lds_dwordx4 v[218:219], off
	s_add_i32 m0, s36, 0x2000
	s_add_u32 s34, s34, 0x80080
	v_lshl_add_u64 v[218:219], v[220:221], 0, s[14:15]
	s_addc_u32 s35, s35, 0
	s_add_i32 s36, s63, s48
	global_load_lds_dwordx4 v[218:219], off
	v_lshl_add_u64 v[218:219], s[34:35], 0, v[130:131]
	s_mov_b32 m0, s36
	s_nop 0
	global_load_lds_dwordx4 v[218:219], off
	v_lshl_add_u64 v[218:219], s[34:35], 0, v[134:135]
	s_add_i32 m0, s36, 0x2000
	s_nop 0
	global_load_lds_dwordx4 v[218:219], off
	v_lshl_add_u64 v[218:219], v[222:223], 0, s[14:15]
	s_mov_b32 m0, s53
	s_nop 0
	global_load_lds_dwordx4 v[218:219], off
	v_lshl_add_u64 v[218:219], v[224:225], 0, s[14:15]
	s_mov_b32 m0, s54
	s_nop 0
	global_load_lds_dwordx4 v[218:219], off
	s_waitcnt vmcnt(8)
	s_waitcnt lgkmcnt(0)
	s_barrier
	s_setprio 1
	v_mfma_f32_16x16x32_bf16 v[60:63], v[146:149], v[186:189], v[60:63]
	v_mfma_f32_16x16x32_bf16 v[56:59], v[162:165], v[186:189], v[56:59]
	v_mfma_f32_16x16x32_bf16 v[44:47], v[146:149], v[194:197], v[44:47]
	v_mfma_f32_16x16x32_bf16 v[40:43], v[162:165], v[194:197], v[40:43]
	v_mfma_f32_16x16x32_bf16 v[28:31], v[146:149], v[202:205], v[28:31]
	v_mfma_f32_16x16x32_bf16 v[24:27], v[162:165], v[202:205], v[24:27]
	v_mfma_f32_16x16x32_bf16 v[12:15], v[146:149], v[210:213], v[12:15]
	v_mfma_f32_16x16x32_bf16 v[8:11], v[162:165], v[210:213], v[8:11]
	v_mfma_f32_16x16x32_bf16 v[60:63], v[158:161], v[190:193], v[60:63]
	v_mfma_f32_16x16x32_bf16 v[56:59], v[166:169], v[190:193], v[56:59]
	v_mfma_f32_16x16x32_bf16 v[44:47], v[158:161], v[198:201], v[44:47]
	v_mfma_f32_16x16x32_bf16 v[40:43], v[166:169], v[198:201], v[40:43]
	v_mfma_f32_16x16x32_bf16 v[28:31], v[158:161], v[206:209], v[28:31]
	v_mfma_f32_16x16x32_bf16 v[24:27], v[166:169], v[206:209], v[24:27]
	v_mfma_f32_16x16x32_bf16 v[12:15], v[158:161], v[214:217], v[12:15]
	v_mfma_f32_16x16x32_bf16 v[8:11], v[166:169], v[214:217], v[8:11]
	s_setprio 0
	s_setprio 1
	v_mfma_f32_16x16x32_bf16 v[52:55], v[170:173], v[186:189], v[52:55]
	v_mfma_f32_16x16x32_bf16 v[48:51], v[178:181], v[186:189], v[48:51]
	v_mfma_f32_16x16x32_bf16 v[36:39], v[170:173], v[194:197], v[36:39]
	v_mfma_f32_16x16x32_bf16 v[32:35], v[178:181], v[194:197], v[32:35]
	v_mfma_f32_16x16x32_bf16 v[20:23], v[170:173], v[202:205], v[20:23]
	v_mfma_f32_16x16x32_bf16 v[16:19], v[178:181], v[202:205], v[16:19]
	v_mfma_f32_16x16x32_bf16 v[4:7], v[170:173], v[210:213], v[4:7]
	v_mfma_f32_16x16x32_bf16 v[0:3], v[178:181], v[210:213], v[0:3]
	v_mfma_f32_16x16x32_bf16 v[52:55], v[174:177], v[190:193], v[52:55]
	v_mfma_f32_16x16x32_bf16 v[48:51], v[182:185], v[190:193], v[48:51]
	v_mfma_f32_16x16x32_bf16 v[36:39], v[174:177], v[198:201], v[36:39]
	v_mfma_f32_16x16x32_bf16 v[32:35], v[182:185], v[198:201], v[32:35]
	v_mfma_f32_16x16x32_bf16 v[20:23], v[174:177], v[206:209], v[20:23]
	v_mfma_f32_16x16x32_bf16 v[16:19], v[182:185], v[206:209], v[16:19]
	v_mfma_f32_16x16x32_bf16 v[4:7], v[174:177], v[214:217], v[4:7]
	v_mfma_f32_16x16x32_bf16 v[0:3], v[182:185], v[214:217], v[0:3]
	s_setprio 0
	s_barrier
	s_add_i32 s61, s61, 2
	s_add_u32 s59, s59, 0x100
	s_addc_u32 s60, s60, 0
	s_add_u32 s30, s30, 0x100
	s_addc_u32 s31, s31, 0
	s_cmp_gt_u32 s61, 29
	s_cbranch_scc0 .LBB0_731
	s_and_b64 vcc, exec, s[16:17]
	s_cbranch_vccz .LBB0_734
	s_barrier

.LBB0_952:
	ds_read_b128 v[144:147], v151
	ds_read_b128 v[156:159], v151 offset:1024
	ds_read_b128 v[160:163], v151 offset:2048
	ds_read_b128 v[164:167], v151 offset:3072
	ds_read_b128 v[168:171], v152
	ds_read_b128 v[172:175], v152 offset:1024
	ds_read_b128 v[176:179], v152 offset:2048
	ds_read_b128 v[180:183], v152 offset:3072
	s_add_u32 s54, s52, 0xfff80080
	s_addc_u32 s55, s53, -1
	s_cmp_eq_u32 s68, 28
	s_cselect_b32 s57, s27, s55
	s_cselect_b32 s56, s37, s54
	s_cselect_b32 s55, s25, s67
	s_cselect_b32 s54, s46, s47
	v_lshl_add_u64 v[216:217], s[52:53], 0, v[138:139]
	s_add_i32 m0, s59, 0xc000
	ds_read_b128 v[184:187], v153
	ds_read_b128 v[188:191], v153 offset:1024
	ds_read_b128 v[192:195], v153 offset:2048
	ds_read_b128 v[196:199], v153 offset:3072
	ds_read_b128 v[200:203], v153 offset:4096
	ds_read_b128 v[204:207], v153 offset:5120
	ds_read_b128 v[208:211], v153 offset:6144
	ds_read_b128 v[212:215], v153 offset:7168
	global_load_lds_dwordx4 v[216:217], off
	v_lshl_add_u64 v[216:217], s[52:53], 0, v[136:137]
	s_add_i32 m0, s59, 0xe000
	s_nop 0
	global_load_lds_dwordx4 v[216:217], off
	s_waitcnt vmcnt(8)
	s_waitcnt lgkmcnt(0)
	s_barrier
	s_setprio 1
	v_mfma_f32_16x16x32_bf16 v[116:119], v[144:147], v[184:187], v[116:119]
	v_mfma_f32_16x16x32_bf16 v[112:115], v[160:163], v[184:187], v[112:115]
	v_mfma_f32_16x16x32_bf16 v[104:107], v[144:147], v[192:195], v[104:107]
	v_mfma_f32_16x16x32_bf16 v[96:99], v[160:163], v[192:195], v[96:99]
	v_mfma_f32_16x16x32_bf16 v[88:91], v[144:147], v[200:203], v[88:91]
	v_mfma_f32_16x16x32_bf16 v[80:83], v[160:163], v[200:203], v[80:83]
	v_mfma_f32_16x16x32_bf16 v[72:75], v[144:147], v[208:211], v[72:75]
	v_mfma_f32_16x16x32_bf16 v[64:67], v[160:163], v[208:211], v[64:67]
	v_mfma_f32_16x16x32_bf16 v[116:119], v[156:159], v[188:191], v[116:119]
	v_mfma_f32_16x16x32_bf16 v[112:115], v[164:167], v[188:191], v[112:115]
	v_mfma_f32_16x16x32_bf16 v[104:107], v[156:159], v[196:199], v[104:107]
	v_mfma_f32_16x16x32_bf16 v[96:99], v[164:167], v[196:199], v[96:99]
	v_mfma_f32_16x16x32_bf16 v[88:91], v[156:159], v[204:207], v[88:91]
	v_mfma_f32_16x16x32_bf16 v[80:83], v[164:167], v[204:207], v[80:83]
	v_mfma_f32_16x16x32_bf16 v[72:75], v[156:159], v[212:215], v[72:75]
	v_mfma_f32_16x16x32_bf16 v[64:67], v[164:167], v[212:215], v[64:67]
	s_setprio 0
	s_setprio 1
	v_mfma_f32_16x16x32_bf16 v[124:127], v[168:171], v[184:187], v[124:127]
	v_mfma_f32_16x16x32_bf16 v[120:123], v[176:179], v[184:187], v[120:123]
	v_mfma_f32_16x16x32_bf16 v[108:111], v[168:171], v[192:195], v[108:111]
	v_mfma_f32_16x16x32_bf16 v[100:103], v[176:179], v[192:195], v[100:103]
	v_mfma_f32_16x16x32_bf16 v[92:95], v[168:171], v[200:203], v[92:95]
	v_mfma_f32_16x16x32_bf16 v[84:87], v[176:179], v[200:203], v[84:87]
	v_mfma_f32_16x16x32_bf16 v[76:79], v[168:171], v[208:211], v[76:79]
	v_mfma_f32_16x16x32_bf16 v[68:71], v[176:179], v[208:211], v[68:71]
	v_mfma_f32_16x16x32_bf16 v[124:127], v[172:175], v[188:191], v[124:127]
	v_mfma_f32_16x16x32_bf16 v[120:123], v[180:183], v[188:191], v[120:123]
	v_mfma_f32_16x16x32_bf16 v[108:111], v[172:175], v[196:199], v[108:111]
	v_mfma_f32_16x16x32_bf16 v[100:103], v[180:183], v[196:199], v[100:103]
	v_mfma_f32_16x16x32_bf16 v[92:95], v[172:175], v[204:207], v[92:95]
	v_mfma_f32_16x16x32_bf16 v[84:87], v[180:183], v[204:207], v[84:87]
	v_mfma_f32_16x16x32_bf16 v[76:79], v[172:175], v[212:215], v[76:79]
	v_mfma_f32_16x16x32_bf16 v[68:71], v[180:183], v[212:215], v[68:71]
	s_setprio 0
	s_barrier
	s_add_i32 s69, s64, s58
	v_lshl_add_u64 v[216:217], s[54:55], 0, v[130:131]
	s_mov_b32 m0, s69
	ds_read_b128 v[184:187], v153 offset:16384
	ds_read_b128 v[188:191], v153 offset:17408
	ds_read_b128 v[192:195], v153 offset:18432
	ds_read_b128 v[196:199], v153 offset:19456
	ds_read_b128 v[200:203], v153 offset:20480
	ds_read_b128 v[204:207], v153 offset:21504
	ds_read_b128 v[208:211], v153 offset:22528
	ds_read_b128 v[212:215], v153 offset:23552
	global_load_lds_dwordx4 v[216:217], off
	s_add_i32 m0, s69, 0x2000
	s_add_u32 s70, s54, 0x80000
	v_lshl_add_u64 v[218:219], s[54:55], 0, v[134:135]
	s_addc_u32 s71, s55, 0
	s_add_i32 s69, s65, s58
	global_load_lds_dwordx4 v[218:219], off
	v_lshl_add_u64 v[220:221], s[70:71], 0, v[130:131]
	s_mov_b32 m0, s69
	v_lshl_add_u64 v[222:223], s[56:57], 0, v[132:133]
	global_load_lds_dwordx4 v[220:221], off
	v_lshl_add_u64 v[220:221], s[70:71], 0, v[134:135]
	s_add_i32 m0, s69, 0x2000
	s_nop 0
	global_load_lds_dwordx4 v[220:221], off
	v_lshl_add_u64 v[220:221], s[56:57], 0, v[128:129]
	s_mov_b32 m0, s59
	s_nop 0
	global_load_lds_dwordx4 v[220:221], off
	s_mov_b32 m0, s50
	s_nop 0
	global_load_lds_dwordx4 v[222:223], off
	s_waitcnt vmcnt(8)
	s_waitcnt lgkmcnt(0)
	s_barrier
	s_setprio 1
	v_mfma_f32_16x16x32_bf16 v[56:59], v[144:147], v[184:187], v[56:59]
	v_mfma_f32_16x16x32_bf16 v[48:51], v[160:163], v[184:187], v[48:51]
	v_mfma_f32_16x16x32_bf16 v[40:43], v[144:147], v[192:195], v[40:43]
	v_mfma_f32_16x16x32_bf16 v[32:35], v[160:163], v[192:195], v[32:35]
	v_mfma_f32_16x16x32_bf16 v[24:27], v[144:147], v[200:203], v[24:27]
	v_mfma_f32_16x16x32_bf16 v[16:19], v[160:163], v[200:203], v[16:19]
	v_mfma_f32_16x16x32_bf16 v[8:11], v[144:147], v[208:211], v[8:11]
	v_mfma_f32_16x16x32_bf16 v[0:3], v[160:163], v[208:211], v[0:3]
	v_mfma_f32_16x16x32_bf16 v[56:59], v[156:159], v[188:191], v[56:59]
	v_mfma_f32_16x16x32_bf16 v[48:51], v[164:167], v[188:191], v[48:51]
	v_mfma_f32_16x16x32_bf16 v[40:43], v[156:159], v[196:199], v[40:43]
	v_mfma_f32_16x16x32_bf16 v[32:35], v[164:167], v[196:199], v[32:35]
	v_mfma_f32_16x16x32_bf16 v[24:27], v[156:159], v[204:207], v[24:27]
	v_mfma_f32_16x16x32_bf16 v[16:19], v[164:167], v[204:207], v[16:19]
	v_mfma_f32_16x16x32_bf16 v[8:11], v[156:159], v[212:215], v[8:11]
	v_mfma_f32_16x16x32_bf16 v[0:3], v[164:167], v[212:215], v[0:3]
	s_setprio 0
	s_setprio 1
	v_mfma_f32_16x16x32_bf16 v[60:63], v[168:171], v[184:187], v[60:63]
	v_mfma_f32_16x16x32_bf16 v[52:55], v[176:179], v[184:187], v[52:55]
	v_mfma_f32_16x16x32_bf16 v[44:47], v[168:171], v[192:195], v[44:47]
	v_mfma_f32_16x16x32_bf16 v[36:39], v[176:179], v[192:195], v[36:39]
	v_mfma_f32_16x16x32_bf16 v[28:31], v[168:171], v[200:203], v[28:31]
	v_mfma_f32_16x16x32_bf16 v[20:23], v[176:179], v[200:203], v[20:23]
	v_mfma_f32_16x16x32_bf16 v[12:15], v[168:171], v[208:211], v[12:15]
	v_mfma_f32_16x16x32_bf16 v[4:7], v[176:179], v[208:211], v[4:7]
	v_mfma_f32_16x16x32_bf16 v[60:63], v[172:175], v[188:191], v[60:63]
	v_mfma_f32_16x16x32_bf16 v[52:55], v[180:183], v[188:191], v[52:55]
	v_mfma_f32_16x16x32_bf16 v[44:47], v[172:175], v[196:199], v[44:47]
	v_mfma_f32_16x16x32_bf16 v[36:39], v[180:183], v[196:199], v[36:39]
	v_mfma_f32_16x16x32_bf16 v[28:31], v[172:175], v[204:207], v[28:31]
	v_mfma_f32_16x16x32_bf16 v[20:23], v[180:183], v[204:207], v[20:23]
	v_mfma_f32_16x16x32_bf16 v[12:15], v[172:175], v[212:215], v[12:15]
	v_mfma_f32_16x16x32_bf16 v[4:7], v[180:183], v[212:215], v[4:7]
	s_setprio 0
	s_barrier
	s_add_i32 s69, 0, 0x18000
	v_add_u32_e32 v155, s69, v149
	s_add_i32 s70, 0, 0x1c000
	ds_read_b128 v[144:147], v155
	ds_read_b128 v[156:159], v155 offset:1024
	ds_read_b128 v[160:163], v155 offset:2048
	ds_read_b128 v[164:167], v155 offset:3072
	v_add_u32_e32 v155, s70, v149
	ds_read_b128 v[168:171], v155
	ds_read_b128 v[172:175], v155 offset:1024
	ds_read_b128 v[176:179], v155 offset:2048
	ds_read_b128 v[180:183], v155 offset:3072
	s_add_u32 s56, s56, 0x80000
	s_addc_u32 s57, s57, 0
	s_mov_b32 m0, s51
	v_lshl_add_u64 v[224:225], s[56:57], 0, v[128:129]
	ds_read_b128 v[184:187], v153 offset:32768
	ds_read_b128 v[188:191], v153 offset:33792
	ds_read_b128 v[192:195], v153 offset:34816
	ds_read_b128 v[196:199], v153 offset:35840
	ds_read_b128 v[200:203], v153 offset:36864
	ds_read_b128 v[204:207], v153 offset:37888
	ds_read_b128 v[208:211], v153 offset:38912
	ds_read_b128 v[212:215], v153 offset:39936
	global_load_lds_dwordx4 v[224:225], off
	v_lshl_add_u64 v[224:225], s[56:57], 0, v[132:133]
	s_mov_b32 m0, s60
	s_nop 0
	global_load_lds_dwordx4 v[224:225], off
	s_waitcnt vmcnt(8)
	s_waitcnt lgkmcnt(0)
	s_barrier
	s_setprio 1
	v_mfma_f32_16x16x32_bf16 v[116:119], v[144:147], v[184:187], v[116:119]
	v_mfma_f32_16x16x32_bf16 v[112:115], v[160:163], v[184:187], v[112:115]
	v_mfma_f32_16x16x32_bf16 v[104:107], v[144:147], v[192:195], v[104:107]
	v_mfma_f32_16x16x32_bf16 v[96:99], v[160:163], v[192:195], v[96:99]
	v_mfma_f32_16x16x32_bf16 v[88:91], v[144:147], v[200:203], v[88:91]
	v_mfma_f32_16x16x32_bf16 v[80:83], v[160:163], v[200:203], v[80:83]
	v_mfma_f32_16x16x32_bf16 v[72:75], v[144:147], v[208:211], v[72:75]
	v_mfma_f32_16x16x32_bf16 v[64:67], v[160:163], v[208:211], v[64:67]
	v_mfma_f32_16x16x32_bf16 v[116:119], v[156:159], v[188:191], v[116:119]
	v_mfma_f32_16x16x32_bf16 v[112:115], v[164:167], v[188:191], v[112:115]
	v_mfma_f32_16x16x32_bf16 v[104:107], v[156:159], v[196:199], v[104:107]
	v_mfma_f32_16x16x32_bf16 v[96:99], v[164:167], v[196:199], v[96:99]
	v_mfma_f32_16x16x32_bf16 v[88:91], v[156:159], v[204:207], v[88:91]
	v_mfma_f32_16x16x32_bf16 v[80:83], v[164:167], v[204:207], v[80:83]
	v_mfma_f32_16x16x32_bf16 v[72:75], v[156:159], v[212:215], v[72:75]
	v_mfma_f32_16x16x32_bf16 v[64:67], v[164:167], v[212:215], v[64:67]
	s_setprio 0
	s_setprio 1
	v_mfma_f32_16x16x32_bf16 v[124:127], v[168:171], v[184:187], v[124:127]
	v_mfma_f32_16x16x32_bf16 v[120:123], v[176:179], v[184:187], v[120:123]
	v_mfma_f32_16x16x32_bf16 v[108:111], v[168:171], v[192:195], v[108:111]
	v_mfma_f32_16x16x32_bf16 v[100:103], v[176:179], v[192:195], v[100:103]
	v_mfma_f32_16x16x32_bf16 v[92:95], v[168:171], v[200:203], v[92:95]
	v_mfma_f32_16x16x32_bf16 v[84:87], v[176:179], v[200:203], v[84:87]
	v_mfma_f32_16x16x32_bf16 v[76:79], v[168:171], v[208:211], v[76:79]
	v_mfma_f32_16x16x32_bf16 v[68:71], v[176:179], v[208:211], v[68:71]
	v_mfma_f32_16x16x32_bf16 v[124:127], v[172:175], v[188:191], v[124:127]
	v_mfma_f32_16x16x32_bf16 v[120:123], v[180:183], v[188:191], v[120:123]
	v_mfma_f32_16x16x32_bf16 v[108:111], v[172:175], v[196:199], v[108:111]
	v_mfma_f32_16x16x32_bf16 v[100:103], v[180:183], v[196:199], v[100:103]
	v_mfma_f32_16x16x32_bf16 v[92:95], v[172:175], v[204:207], v[92:95]
	v_mfma_f32_16x16x32_bf16 v[84:87], v[180:183], v[204:207], v[84:87]
	v_mfma_f32_16x16x32_bf16 v[76:79], v[172:175], v[212:215], v[76:79]
	v_mfma_f32_16x16x32_bf16 v[68:71], v[180:183], v[212:215], v[68:71]
	s_setprio 0
	s_barrier
	s_add_i32 s56, s69, s58
	v_lshl_add_u64 v[216:217], v[216:217], 0, s[20:21]
	s_mov_b32 m0, s56
	ds_read_b128 v[184:187], v153 offset:49152
	ds_read_b128 v[188:191], v153 offset:50176
	ds_read_b128 v[192:195], v153 offset:51200
	ds_read_b128 v[196:199], v153 offset:52224
	ds_read_b128 v[200:203], v153 offset:53248
	ds_read_b128 v[204:207], v153 offset:54272
	ds_read_b128 v[208:211], v153 offset:55296
	ds_read_b128 v[212:215], v153 offset:56320
	global_load_lds_dwordx4 v[216:217], off
	s_add_i32 m0, s56, 0x2000
	s_add_u32 s54, s54, 0x80080
	v_lshl_add_u64 v[216:217], v[218:219], 0, s[20:21]
	s_addc_u32 s55, s55, 0
	s_add_i32 s56, s70, s58
	global_load_lds_dwordx4 v[216:217], off
	v_lshl_add_u64 v[216:217], s[54:55], 0, v[130:131]
	s_mov_b32 m0, s56
	s_nop 0
	global_load_lds_dwordx4 v[216:217], off
	v_lshl_add_u64 v[216:217], s[54:55], 0, v[134:135]
	s_add_i32 m0, s56, 0x2000
	s_nop 0
	global_load_lds_dwordx4 v[216:217], off
	v_lshl_add_u64 v[216:217], v[220:221], 0, s[20:21]
	s_mov_b32 m0, s62
	s_nop 0
	global_load_lds_dwordx4 v[216:217], off
	v_lshl_add_u64 v[216:217], v[222:223], 0, s[20:21]
	s_mov_b32 m0, s63
	s_nop 0
	global_load_lds_dwordx4 v[216:217], off
	s_waitcnt vmcnt(8)
	s_waitcnt lgkmcnt(0)
	s_barrier
	s_setprio 1
	v_mfma_f32_16x16x32_bf16 v[56:59], v[144:147], v[184:187], v[56:59]
	v_mfma_f32_16x16x32_bf16 v[48:51], v[160:163], v[184:187], v[48:51]
	v_mfma_f32_16x16x32_bf16 v[40:43], v[144:147], v[192:195], v[40:43]
	v_mfma_f32_16x16x32_bf16 v[32:35], v[160:163], v[192:195], v[32:35]
	v_mfma_f32_16x16x32_bf16 v[24:27], v[144:147], v[200:203], v[24:27]
	v_mfma_f32_16x16x32_bf16 v[16:19], v[160:163], v[200:203], v[16:19]
	v_mfma_f32_16x16x32_bf16 v[8:11], v[144:147], v[208:211], v[8:11]
	v_mfma_f32_16x16x32_bf16 v[0:3], v[160:163], v[208:211], v[0:3]
	v_mfma_f32_16x16x32_bf16 v[56:59], v[156:159], v[188:191], v[56:59]
	v_mfma_f32_16x16x32_bf16 v[48:51], v[164:167], v[188:191], v[48:51]
	v_mfma_f32_16x16x32_bf16 v[40:43], v[156:159], v[196:199], v[40:43]
	v_mfma_f32_16x16x32_bf16 v[32:35], v[164:167], v[196:199], v[32:35]
	v_mfma_f32_16x16x32_bf16 v[24:27], v[156:159], v[204:207], v[24:27]
	v_mfma_f32_16x16x32_bf16 v[16:19], v[164:167], v[204:207], v[16:19]
	v_mfma_f32_16x16x32_bf16 v[8:11], v[156:159], v[212:215], v[8:11]
	v_mfma_f32_16x16x32_bf16 v[0:3], v[164:167], v[212:215], v[0:3]
	s_setprio 0
	s_setprio 1
	v_mfma_f32_16x16x32_bf16 v[60:63], v[168:171], v[184:187], v[60:63]
	v_mfma_f32_16x16x32_bf16 v[52:55], v[176:179], v[184:187], v[52:55]
	v_mfma_f32_16x16x32_bf16 v[44:47], v[168:171], v[192:195], v[44:47]
	v_mfma_f32_16x16x32_bf16 v[36:39], v[176:179], v[192:195], v[36:39]
	v_mfma_f32_16x16x32_bf16 v[28:31], v[168:171], v[200:203], v[28:31]
	v_mfma_f32_16x16x32_bf16 v[20:23], v[176:179], v[200:203], v[20:23]
	v_mfma_f32_16x16x32_bf16 v[12:15], v[168:171], v[208:211], v[12:15]
	v_mfma_f32_16x16x32_bf16 v[4:7], v[176:179], v[208:211], v[4:7]
	v_mfma_f32_16x16x32_bf16 v[60:63], v[172:175], v[188:191], v[60:63]
	v_mfma_f32_16x16x32_bf16 v[52:55], v[180:183], v[188:191], v[52:55]
	v_mfma_f32_16x16x32_bf16 v[44:47], v[172:175], v[196:199], v[44:47]
	v_mfma_f32_16x16x32_bf16 v[36:39], v[180:183], v[196:199], v[36:39]
	v_mfma_f32_16x16x32_bf16 v[28:31], v[172:175], v[204:207], v[28:31]
	v_mfma_f32_16x16x32_bf16 v[20:23], v[180:183], v[204:207], v[20:23]
	v_mfma_f32_16x16x32_bf16 v[12:15], v[172:175], v[212:215], v[12:15]
	v_mfma_f32_16x16x32_bf16 v[4:7], v[180:183], v[212:215], v[4:7]
	s_setprio 0
	s_barrier
	s_add_i32 s68, s68, 2
	s_add_u32 s47, s47, 0x100
	s_addc_u32 s67, s67, 0
	s_add_u32 s52, s52, 0x100
	s_addc_u32 s53, s53, 0
	s_cmp_gt_u32 s68, 29
	s_cbranch_scc0 .LBB0_952
	s_and_b64 vcc, exec, s[22:23]
	s_cbranch_vccz .LBB0_955
	s_barrier

.LBB0_1049:
	ds_read_b128 v[148:151], v222
	ds_read_b128 v[152:155], v222 offset:1024
	ds_read_b128 v[156:159], v222 offset:2048
	ds_read_b128 v[160:163], v222 offset:3072
	ds_read_b128 v[132:135], v223
	ds_read_b128 v[136:139], v223 offset:1024
	ds_read_b128 v[140:143], v223 offset:2048
	ds_read_b128 v[144:147], v223 offset:3072
	s_add_u32 s8, s48, 0xfff80080
	s_addc_u32 s9, s49, -1
	s_cmp_eq_u32 s81, 28
	s_cselect_b32 s53, s23, s9
	s_cselect_b32 s52, s46, s8
	s_cselect_b32 s51, s21, s80
	s_cselect_b32 s50, s47, s79
	v_lshl_add_u64 v[2:3], s[48:49], 0, v[208:209]
	s_add_i32 m0, s35, 0xc000
	s_waitcnt lgkmcnt(0)
	ds_read_b128 v[164:167], v224
	ds_read_b128 v[168:171], v224 offset:1024
	ds_read_b128 v[172:175], v224 offset:2048
	ds_read_b128 v[176:179], v224 offset:3072
	ds_read_b128 v[180:183], v224 offset:4096
	ds_read_b128 v[184:187], v224 offset:5120
	ds_read_b128 v[188:191], v224 offset:6144
	ds_read_b128 v[192:195], v224 offset:7168
	global_load_lds_dwordx4 v[2:3], off
	v_lshl_add_u64 v[2:3], s[48:49], 0, v[206:207]
	s_add_i32 m0, s35, 0xe000
	s_nop 0
	global_load_lds_dwordx4 v[2:3], off
	s_waitcnt vmcnt(8)
	s_waitcnt lgkmcnt(0)
	s_barrier
	s_setprio 1
	v_mfma_f32_16x16x32_bf16 v[124:127], v[148:151], v[164:167], v[124:127]
	v_mfma_f32_16x16x32_bf16 v[120:123], v[156:159], v[164:167], v[120:123]
	v_mfma_f32_16x16x32_bf16 v[104:107], v[148:151], v[172:175], v[104:107]
	v_mfma_f32_16x16x32_bf16 v[100:103], v[156:159], v[172:175], v[100:103]
	v_mfma_f32_16x16x32_bf16 v[88:91], v[148:151], v[180:183], v[88:91]
	v_mfma_f32_16x16x32_bf16 v[84:87], v[156:159], v[180:183], v[84:87]
	v_mfma_f32_16x16x32_bf16 v[76:79], v[148:151], v[188:191], v[76:79]
	v_mfma_f32_16x16x32_bf16 v[72:75], v[156:159], v[188:191], v[72:75]
	v_mfma_f32_16x16x32_bf16 v[124:127], v[152:155], v[168:171], v[124:127]
	v_mfma_f32_16x16x32_bf16 v[120:123], v[160:163], v[168:171], v[120:123]
	v_mfma_f32_16x16x32_bf16 v[104:107], v[152:155], v[176:179], v[104:107]
	v_mfma_f32_16x16x32_bf16 v[100:103], v[160:163], v[176:179], v[100:103]
	v_mfma_f32_16x16x32_bf16 v[88:91], v[152:155], v[184:187], v[88:91]
	v_mfma_f32_16x16x32_bf16 v[84:87], v[160:163], v[184:187], v[84:87]
	v_mfma_f32_16x16x32_bf16 v[76:79], v[152:155], v[192:195], v[76:79]
	v_mfma_f32_16x16x32_bf16 v[72:75], v[160:163], v[192:195], v[72:75]
	s_setprio 0
	s_setprio 1
	v_mfma_f32_16x16x32_bf16 v[128:131], v[132:135], v[164:167], v[128:131]
	v_mfma_f32_16x16x32_bf16 v[116:119], v[140:143], v[164:167], v[116:119]
	v_mfma_f32_16x16x32_bf16 v[112:115], v[132:135], v[172:175], v[112:115]
	v_mfma_f32_16x16x32_bf16 v[108:111], v[140:143], v[172:175], v[108:111]
	v_mfma_f32_16x16x32_bf16 v[96:99], v[132:135], v[180:183], v[96:99]
	v_mfma_f32_16x16x32_bf16 v[92:95], v[140:143], v[180:183], v[92:95]
	v_mfma_f32_16x16x32_bf16 v[80:83], v[132:135], v[188:191], v[80:83]
	v_mfma_f32_16x16x32_bf16 v[68:71], v[140:143], v[188:191], v[68:71]
	v_mfma_f32_16x16x32_bf16 v[128:131], v[136:139], v[168:171], v[128:131]
	v_mfma_f32_16x16x32_bf16 v[116:119], v[144:147], v[168:171], v[116:119]
	v_mfma_f32_16x16x32_bf16 v[112:115], v[136:139], v[176:179], v[112:115]
	v_mfma_f32_16x16x32_bf16 v[108:111], v[144:147], v[176:179], v[108:111]
	v_mfma_f32_16x16x32_bf16 v[96:99], v[136:139], v[184:187], v[96:99]
	v_mfma_f32_16x16x32_bf16 v[92:95], v[144:147], v[184:187], v[92:95]
	v_mfma_f32_16x16x32_bf16 v[80:83], v[136:139], v[192:195], v[80:83]
	v_mfma_f32_16x16x32_bf16 v[68:71], v[144:147], v[192:195], v[68:71]
	s_setprio 0
	s_barrier
	s_add_i32 s8, s65, s56
	v_lshl_add_u64 v[2:3], s[50:51], 0, v[198:199]
	s_mov_b32 m0, s8
	ds_read_b128 v[188:191], v224 offset:16384
	ds_read_b128 v[192:195], v224 offset:17408
	ds_read_b128 v[180:183], v224 offset:18432
	ds_read_b128 v[184:187], v224 offset:19456
	ds_read_b128 v[172:175], v224 offset:20480
	ds_read_b128 v[176:179], v224 offset:21504
	ds_read_b128 v[164:167], v224 offset:22528
	ds_read_b128 v[168:171], v224 offset:23552
	global_load_lds_dwordx4 v[2:3], off
	s_add_i32 m0, s8, 0x2000
	s_add_u32 s8, s50, 0x80000
	v_lshl_add_u64 v[212:213], s[50:51], 0, v[202:203]
	s_addc_u32 s9, s51, 0
	s_add_i32 s78, s66, s56
	global_load_lds_dwordx4 v[212:213], off
	v_lshl_add_u64 v[214:215], s[8:9], 0, v[198:199]
	s_mov_b32 m0, s78
	v_lshl_add_u64 v[216:217], s[52:53], 0, v[200:201]
	global_load_lds_dwordx4 v[214:215], off
	v_lshl_add_u64 v[214:215], s[8:9], 0, v[202:203]
	s_add_i32 m0, s78, 0x2000
	v_cmp_ne_u32_e64 s[8:9], 1, v227
	global_load_lds_dwordx4 v[214:215], off
	v_lshl_add_u64 v[214:215], s[52:53], 0, v[196:197]
	s_mov_b32 m0, s35
	s_andn2_b64 vcc, exec, s[36:37]
	global_load_lds_dwordx4 v[214:215], off
	s_mov_b32 m0, s58
	s_nop 0
	global_load_lds_dwordx4 v[216:217], off
	s_waitcnt vmcnt(8)
	s_waitcnt lgkmcnt(0)
	s_barrier
	s_cbranch_vccnz .LBB0_1051
	s_setprio 1
	v_mfma_f32_16x16x32_bf16 v[56:59], v[148:151], v[188:191], v[56:59]
	v_mfma_f32_16x16x32_bf16 v[52:55], v[156:159], v[188:191], v[52:55]
	v_mfma_f32_16x16x32_bf16 v[40:43], v[148:151], v[180:183], v[40:43]
	v_mfma_f32_16x16x32_bf16 v[36:39], v[156:159], v[180:183], v[36:39]
	v_mfma_f32_16x16x32_bf16 v[24:27], v[148:151], v[172:175], v[24:27]
	v_mfma_f32_16x16x32_bf16 v[20:23], v[156:159], v[172:175], v[20:23]
	v_mfma_f32_16x16x32_bf16 v[8:11], v[148:151], v[164:167], v[8:11]
	v_mfma_f32_16x16x32_bf16 v[4:7], v[156:159], v[164:167], v[4:7]
	v_mfma_f32_16x16x32_bf16 v[56:59], v[152:155], v[192:195], v[56:59]
	v_mfma_f32_16x16x32_bf16 v[52:55], v[160:163], v[192:195], v[52:55]
	v_mfma_f32_16x16x32_bf16 v[40:43], v[152:155], v[184:187], v[40:43]
	v_mfma_f32_16x16x32_bf16 v[36:39], v[160:163], v[184:187], v[36:39]
	v_mfma_f32_16x16x32_bf16 v[24:27], v[152:155], v[176:179], v[24:27]
	v_mfma_f32_16x16x32_bf16 v[20:23], v[160:163], v[176:179], v[20:23]
	v_mfma_f32_16x16x32_bf16 v[8:11], v[152:155], v[168:171], v[8:11]
	v_mfma_f32_16x16x32_bf16 v[4:7], v[160:163], v[168:171], v[4:7]
	s_setprio 0
	s_setprio 1
	v_mfma_f32_16x16x32_bf16 v[64:67], v[132:135], v[188:191], v[64:67]
	v_mfma_f32_16x16x32_bf16 v[60:63], v[140:143], v[188:191], v[60:63]
	v_mfma_f32_16x16x32_bf16 v[48:51], v[132:135], v[180:183], v[48:51]
	v_mfma_f32_16x16x32_bf16 v[44:47], v[140:143], v[180:183], v[44:47]
	v_mfma_f32_16x16x32_bf16 v[32:35], v[132:135], v[172:175], v[32:35]
	v_mfma_f32_16x16x32_bf16 v[28:31], v[140:143], v[172:175], v[28:31]
	v_mfma_f32_16x16x32_bf16 v[16:19], v[132:135], v[164:167], v[16:19]
	v_mfma_f32_16x16x32_bf16 v[12:15], v[140:143], v[164:167], v[12:15]
	v_mfma_f32_16x16x32_bf16 v[64:67], v[136:139], v[192:195], v[64:67]
	v_mfma_f32_16x16x32_bf16 v[60:63], v[144:147], v[192:195], v[60:63]
	v_mfma_f32_16x16x32_bf16 v[48:51], v[136:139], v[184:187], v[48:51]
	v_mfma_f32_16x16x32_bf16 v[44:47], v[144:147], v[184:187], v[44:47]
	v_mfma_f32_16x16x32_bf16 v[32:35], v[136:139], v[176:179], v[32:35]
	v_mfma_f32_16x16x32_bf16 v[28:31], v[144:147], v[176:179], v[28:31]
	v_mfma_f32_16x16x32_bf16 v[16:19], v[136:139], v[168:171], v[16:19]
	v_mfma_f32_16x16x32_bf16 v[12:15], v[144:147], v[168:171], v[12:15]
	s_setprio 0
.LBB0_1051:
	s_barrier
	s_add_i32 s78, 0, 0x18000
	v_add_u32_e32 v1, s78, v220
	s_add_i32 s82, 0, 0x1c000
	ds_read_b128 v[148:151], v1
	ds_read_b128 v[152:155], v1 offset:1024
	ds_read_b128 v[156:159], v1 offset:2048
	ds_read_b128 v[160:163], v1 offset:3072
	v_add_u32_e32 v1, s82, v220
	ds_read_b128 v[132:135], v1
	ds_read_b128 v[136:139], v1 offset:1024
	ds_read_b128 v[140:143], v1 offset:2048
	ds_read_b128 v[144:147], v1 offset:3072
	s_add_u32 s52, s52, 0x80000
	s_addc_u32 s53, s53, 0
	s_mov_b32 m0, s59
	v_lshl_add_u64 v[228:229], s[52:53], 0, v[196:197]
	s_waitcnt lgkmcnt(0)
	ds_read_b128 v[164:167], v224 offset:32768
	ds_read_b128 v[168:171], v224 offset:33792
	ds_read_b128 v[172:175], v224 offset:34816
	ds_read_b128 v[176:179], v224 offset:35840
	ds_read_b128 v[180:183], v224 offset:36864
	ds_read_b128 v[184:187], v224 offset:37888
	ds_read_b128 v[188:191], v224 offset:38912
	ds_read_b128 v[192:195], v224 offset:39936
	global_load_lds_dwordx4 v[228:229], off
	v_lshl_add_u64 v[228:229], s[52:53], 0, v[200:201]
	s_mov_b32 m0, s60
	s_nop 0
	global_load_lds_dwordx4 v[228:229], off
	s_waitcnt vmcnt(8)
	s_waitcnt lgkmcnt(0)
	s_barrier
	s_setprio 1
	v_mfma_f32_16x16x32_bf16 v[124:127], v[148:151], v[164:167], v[124:127]
	v_mfma_f32_16x16x32_bf16 v[120:123], v[156:159], v[164:167], v[120:123]
	v_mfma_f32_16x16x32_bf16 v[104:107], v[148:151], v[172:175], v[104:107]
	v_mfma_f32_16x16x32_bf16 v[100:103], v[156:159], v[172:175], v[100:103]
	v_mfma_f32_16x16x32_bf16 v[88:91], v[148:151], v[180:183], v[88:91]
	v_mfma_f32_16x16x32_bf16 v[84:87], v[156:159], v[180:183], v[84:87]
	v_mfma_f32_16x16x32_bf16 v[76:79], v[148:151], v[188:191], v[76:79]
	v_mfma_f32_16x16x32_bf16 v[72:75], v[156:159], v[188:191], v[72:75]
	v_mfma_f32_16x16x32_bf16 v[124:127], v[152:155], v[168:171], v[124:127]
	v_mfma_f32_16x16x32_bf16 v[120:123], v[160:163], v[168:171], v[120:123]
	v_mfma_f32_16x16x32_bf16 v[104:107], v[152:155], v[176:179], v[104:107]
	v_mfma_f32_16x16x32_bf16 v[100:103], v[160:163], v[176:179], v[100:103]
	v_mfma_f32_16x16x32_bf16 v[88:91], v[152:155], v[184:187], v[88:91]
	v_mfma_f32_16x16x32_bf16 v[84:87], v[160:163], v[184:187], v[84:87]
	v_mfma_f32_16x16x32_bf16 v[76:79], v[152:155], v[192:195], v[76:79]
	v_mfma_f32_16x16x32_bf16 v[72:75], v[160:163], v[192:195], v[72:75]
	s_setprio 0
	s_setprio 1
	v_mfma_f32_16x16x32_bf16 v[128:131], v[132:135], v[164:167], v[128:131]
	v_mfma_f32_16x16x32_bf16 v[116:119], v[140:143], v[164:167], v[116:119]
	v_mfma_f32_16x16x32_bf16 v[112:115], v[132:135], v[172:175], v[112:115]
	v_mfma_f32_16x16x32_bf16 v[108:111], v[140:143], v[172:175], v[108:111]
	v_mfma_f32_16x16x32_bf16 v[96:99], v[132:135], v[180:183], v[96:99]
	v_mfma_f32_16x16x32_bf16 v[92:95], v[140:143], v[180:183], v[92:95]
	v_mfma_f32_16x16x32_bf16 v[80:83], v[132:135], v[188:191], v[80:83]
	v_mfma_f32_16x16x32_bf16 v[68:71], v[140:143], v[188:191], v[68:71]
	v_mfma_f32_16x16x32_bf16 v[128:131], v[136:139], v[168:171], v[128:131]
	v_mfma_f32_16x16x32_bf16 v[116:119], v[144:147], v[168:171], v[116:119]
	v_mfma_f32_16x16x32_bf16 v[112:115], v[136:139], v[176:179], v[112:115]
	v_mfma_f32_16x16x32_bf16 v[108:111], v[144:147], v[176:179], v[108:111]
	v_mfma_f32_16x16x32_bf16 v[96:99], v[136:139], v[184:187], v[96:99]
	v_mfma_f32_16x16x32_bf16 v[92:95], v[144:147], v[184:187], v[92:95]
	v_mfma_f32_16x16x32_bf16 v[80:83], v[136:139], v[192:195], v[80:83]
	v_mfma_f32_16x16x32_bf16 v[68:71], v[144:147], v[192:195], v[68:71]
	s_setprio 0
	s_barrier
	s_add_i32 s52, s78, s56
	v_lshl_add_u64 v[2:3], v[2:3], 0, s[14:15]
	s_mov_b32 m0, s52
	ds_read_b128 v[188:191], v224 offset:49152
	ds_read_b128 v[192:195], v224 offset:50176
	ds_read_b128 v[180:183], v224 offset:51200
	ds_read_b128 v[184:187], v224 offset:52224
	ds_read_b128 v[172:175], v224 offset:53248
	ds_read_b128 v[176:179], v224 offset:54272
	ds_read_b128 v[164:167], v224 offset:55296
	ds_read_b128 v[168:171], v224 offset:56320
	global_load_lds_dwordx4 v[2:3], off
	s_add_i32 m0, s52, 0x2000
	s_add_u32 s50, s50, 0x80080
	v_lshl_add_u64 v[2:3], v[212:213], 0, s[14:15]
	s_addc_u32 s51, s51, 0
	s_add_i32 s52, s82, s56
	global_load_lds_dwordx4 v[2:3], off
	v_lshl_add_u64 v[2:3], s[50:51], 0, v[198:199]
	s_mov_b32 m0, s52
	s_and_b64 vcc, exec, s[8:9]
	global_load_lds_dwordx4 v[2:3], off
	v_lshl_add_u64 v[2:3], s[50:51], 0, v[202:203]
	s_add_i32 m0, s52, 0x2000
	s_nop 0
	global_load_lds_dwordx4 v[2:3], off
	v_lshl_add_u64 v[2:3], v[214:215], 0, s[14:15]
	s_mov_b32 m0, s61
	s_nop 0
	global_load_lds_dwordx4 v[2:3], off
	v_lshl_add_u64 v[2:3], v[216:217], 0, s[14:15]
	s_mov_b32 m0, s62
	s_nop 0
	global_load_lds_dwordx4 v[2:3], off
	s_waitcnt vmcnt(8)
	s_waitcnt lgkmcnt(0)
	s_barrier
	s_cbranch_vccnz .LBB0_1048
	s_setprio 1
	v_mfma_f32_16x16x32_bf16 v[56:59], v[148:151], v[188:191], v[56:59]
	v_mfma_f32_16x16x32_bf16 v[52:55], v[156:159], v[188:191], v[52:55]
	v_mfma_f32_16x16x32_bf16 v[40:43], v[148:151], v[180:183], v[40:43]
	v_mfma_f32_16x16x32_bf16 v[36:39], v[156:159], v[180:183], v[36:39]
	v_mfma_f32_16x16x32_bf16 v[24:27], v[148:151], v[172:175], v[24:27]
	v_mfma_f32_16x16x32_bf16 v[20:23], v[156:159], v[172:175], v[20:23]
	v_mfma_f32_16x16x32_bf16 v[8:11], v[148:151], v[164:167], v[8:11]
	v_mfma_f32_16x16x32_bf16 v[2:5], v[156:159], v[164:167], v[4:7]
	v_mfma_f32_16x16x32_bf16 v[56:59], v[152:155], v[192:195], v[56:59]
	v_mfma_f32_16x16x32_bf16 v[52:55], v[160:163], v[192:195], v[52:55]
	v_mfma_f32_16x16x32_bf16 v[40:43], v[152:155], v[184:187], v[40:43]
	v_mfma_f32_16x16x32_bf16 v[36:39], v[160:163], v[184:187], v[36:39]
	v_mfma_f32_16x16x32_bf16 v[24:27], v[152:155], v[176:179], v[24:27]
	v_mfma_f32_16x16x32_bf16 v[20:23], v[160:163], v[176:179], v[20:23]
	v_mfma_f32_16x16x32_bf16 v[8:11], v[152:155], v[168:171], v[8:11]
	v_mfma_f32_16x16x32_bf16 v[4:7], v[160:163], v[168:171], v[2:5]
	s_setprio 0
	s_setprio 1
	v_mfma_f32_16x16x32_bf16 v[64:67], v[132:135], v[188:191], v[64:67]
	v_mfma_f32_16x16x32_bf16 v[60:63], v[140:143], v[188:191], v[60:63]
	v_mfma_f32_16x16x32_bf16 v[48:51], v[132:135], v[180:183], v[48:51]
	v_mfma_f32_16x16x32_bf16 v[44:47], v[140:143], v[180:183], v[44:47]
	v_mfma_f32_16x16x32_bf16 v[32:35], v[132:135], v[172:175], v[32:35]
	v_mfma_f32_16x16x32_bf16 v[28:31], v[140:143], v[172:175], v[28:31]
	v_mfma_f32_16x16x32_bf16 v[16:19], v[132:135], v[164:167], v[16:19]
	v_mfma_f32_16x16x32_bf16 v[12:15], v[140:143], v[164:167], v[12:15]
	v_mfma_f32_16x16x32_bf16 v[64:67], v[136:139], v[192:195], v[64:67]
	v_mfma_f32_16x16x32_bf16 v[60:63], v[144:147], v[192:195], v[60:63]
	v_mfma_f32_16x16x32_bf16 v[48:51], v[136:139], v[184:187], v[48:51]
	v_mfma_f32_16x16x32_bf16 v[44:47], v[144:147], v[184:187], v[44:47]
	v_mfma_f32_16x16x32_bf16 v[32:35], v[136:139], v[176:179], v[32:35]
	v_mfma_f32_16x16x32_bf16 v[28:31], v[144:147], v[176:179], v[28:31]
	v_mfma_f32_16x16x32_bf16 v[16:19], v[136:139], v[168:171], v[16:19]
	v_mfma_f32_16x16x32_bf16 v[12:15], v[144:147], v[168:171], v[12:15]
	s_setprio 0
	s_branch .LBB0_1048

.LBB0_1137:
	ds_read_b128 v[144:147], v151
	ds_read_b128 v[156:159], v151 offset:1024
	ds_read_b128 v[160:163], v151 offset:2048
	ds_read_b128 v[164:167], v151 offset:3072
	ds_read_b128 v[168:171], v152
	ds_read_b128 v[172:175], v152 offset:1024
	ds_read_b128 v[176:179], v152 offset:2048
	ds_read_b128 v[180:183], v152 offset:3072
	s_add_u32 s34, s30, 0x100
	s_addc_u32 s35, s31, 0
	s_cmpk_eq_i32 s66, 0x54
	s_cselect_b32 s49, s11, s35
	s_cselect_b32 s48, s10, s34
	s_cselect_b32 s37, s27, s47
	s_cselect_b32 s36, s26, s46
	v_lshl_add_u64 v[216:217], s[30:31], 0, v[138:139]
	s_add_i32 m0, s53, 0xc000
	ds_read_b128 v[184:187], v153
	ds_read_b128 v[188:191], v153 offset:1024
	ds_read_b128 v[192:195], v153 offset:2048
	ds_read_b128 v[196:199], v153 offset:3072
	ds_read_b128 v[200:203], v153 offset:4096
	ds_read_b128 v[204:207], v153 offset:5120
	ds_read_b128 v[208:211], v153 offset:6144
	ds_read_b128 v[212:215], v153 offset:7168
	global_load_lds_dwordx4 v[216:217], off
	v_lshl_add_u64 v[216:217], s[30:31], 0, v[136:137]
	s_add_i32 m0, s53, 0xe000
	s_nop 0
	global_load_lds_dwordx4 v[216:217], off
	s_waitcnt vmcnt(8)
	s_waitcnt lgkmcnt(0)
	s_barrier
	s_setprio 1
	v_mfma_f32_16x16x32_bf16 v[124:127], v[144:147], v[184:187], v[124:127]
	v_mfma_f32_16x16x32_bf16 v[120:123], v[160:163], v[184:187], v[120:123]
	v_mfma_f32_16x16x32_bf16 v[108:111], v[144:147], v[192:195], v[108:111]
	v_mfma_f32_16x16x32_bf16 v[104:107], v[160:163], v[192:195], v[104:107]
	v_mfma_f32_16x16x32_bf16 v[92:95], v[144:147], v[200:203], v[92:95]
	v_mfma_f32_16x16x32_bf16 v[88:91], v[160:163], v[200:203], v[88:91]
	v_mfma_f32_16x16x32_bf16 v[76:79], v[144:147], v[208:211], v[76:79]
	v_mfma_f32_16x16x32_bf16 v[72:75], v[160:163], v[208:211], v[72:75]
	v_mfma_f32_16x16x32_bf16 v[124:127], v[156:159], v[188:191], v[124:127]
	v_mfma_f32_16x16x32_bf16 v[120:123], v[164:167], v[188:191], v[120:123]
	v_mfma_f32_16x16x32_bf16 v[108:111], v[156:159], v[196:199], v[108:111]
	v_mfma_f32_16x16x32_bf16 v[104:107], v[164:167], v[196:199], v[104:107]
	v_mfma_f32_16x16x32_bf16 v[92:95], v[156:159], v[204:207], v[92:95]
	v_mfma_f32_16x16x32_bf16 v[88:91], v[164:167], v[204:207], v[88:91]
	v_mfma_f32_16x16x32_bf16 v[76:79], v[156:159], v[212:215], v[76:79]
	v_mfma_f32_16x16x32_bf16 v[72:75], v[164:167], v[212:215], v[72:75]
	s_setprio 0
	s_setprio 1
	v_mfma_f32_16x16x32_bf16 v[116:119], v[168:171], v[184:187], v[116:119]
	v_mfma_f32_16x16x32_bf16 v[112:115], v[176:179], v[184:187], v[112:115]
	v_mfma_f32_16x16x32_bf16 v[100:103], v[168:171], v[192:195], v[100:103]
	v_mfma_f32_16x16x32_bf16 v[96:99], v[176:179], v[192:195], v[96:99]
	v_mfma_f32_16x16x32_bf16 v[84:87], v[168:171], v[200:203], v[84:87]
	v_mfma_f32_16x16x32_bf16 v[80:83], v[176:179], v[200:203], v[80:83]
	v_mfma_f32_16x16x32_bf16 v[68:71], v[168:171], v[208:211], v[68:71]
	v_mfma_f32_16x16x32_bf16 v[64:67], v[176:179], v[208:211], v[64:67]
	v_mfma_f32_16x16x32_bf16 v[116:119], v[172:175], v[188:191], v[116:119]
	v_mfma_f32_16x16x32_bf16 v[112:115], v[180:183], v[188:191], v[112:115]
	v_mfma_f32_16x16x32_bf16 v[100:103], v[172:175], v[196:199], v[100:103]
	v_mfma_f32_16x16x32_bf16 v[96:99], v[180:183], v[196:199], v[96:99]
	v_mfma_f32_16x16x32_bf16 v[84:87], v[172:175], v[204:207], v[84:87]
	v_mfma_f32_16x16x32_bf16 v[80:83], v[180:183], v[204:207], v[80:83]
	v_mfma_f32_16x16x32_bf16 v[68:71], v[172:175], v[212:215], v[68:71]
	v_mfma_f32_16x16x32_bf16 v[64:67], v[180:183], v[212:215], v[64:67]
	s_setprio 0
	s_barrier
	s_add_i32 s30, s60, s52
	v_lshl_add_u64 v[216:217], s[36:37], 0, v[130:131]
	s_mov_b32 m0, s30
	ds_read_b128 v[184:187], v153 offset:16384
	ds_read_b128 v[188:191], v153 offset:17408
	ds_read_b128 v[192:195], v153 offset:18432
	ds_read_b128 v[196:199], v153 offset:19456
	ds_read_b128 v[200:203], v153 offset:20480
	ds_read_b128 v[204:207], v153 offset:21504
	ds_read_b128 v[208:211], v153 offset:22528
	ds_read_b128 v[212:215], v153 offset:23552
	global_load_lds_dwordx4 v[216:217], off
	s_add_i32 m0, s30, 0x2000
	s_add_u32 s30, s36, 0x160000
	v_lshl_add_u64 v[218:219], s[36:37], 0, v[134:135]
	s_addc_u32 s31, s37, 0
	s_add_i32 s67, s61, s52
	global_load_lds_dwordx4 v[218:219], off
	v_lshl_add_u64 v[220:221], s[30:31], 0, v[130:131]
	s_mov_b32 m0, s67
	v_lshl_add_u64 v[222:223], s[48:49], 0, v[132:133]
	global_load_lds_dwordx4 v[220:221], off
	v_lshl_add_u64 v[220:221], s[30:31], 0, v[134:135]
	s_add_i32 m0, s67, 0x2000
	s_nop 0
	global_load_lds_dwordx4 v[220:221], off
	v_lshl_add_u64 v[220:221], s[48:49], 0, v[128:129]
	s_mov_b32 m0, s53
	s_nop 0
	global_load_lds_dwordx4 v[220:221], off
	s_mov_b32 m0, s54
	s_nop 0
	global_load_lds_dwordx4 v[222:223], off
	s_waitcnt vmcnt(8)
	s_waitcnt lgkmcnt(0)
	s_barrier
	s_setprio 1
	v_mfma_f32_16x16x32_bf16 v[60:63], v[144:147], v[184:187], v[60:63]
	v_mfma_f32_16x16x32_bf16 v[56:59], v[160:163], v[184:187], v[56:59]
	v_mfma_f32_16x16x32_bf16 v[44:47], v[144:147], v[192:195], v[44:47]
	v_mfma_f32_16x16x32_bf16 v[40:43], v[160:163], v[192:195], v[40:43]
	v_mfma_f32_16x16x32_bf16 v[28:31], v[144:147], v[200:203], v[28:31]
	v_mfma_f32_16x16x32_bf16 v[24:27], v[160:163], v[200:203], v[24:27]
	v_mfma_f32_16x16x32_bf16 v[12:15], v[144:147], v[208:211], v[12:15]
	v_mfma_f32_16x16x32_bf16 v[8:11], v[160:163], v[208:211], v[8:11]
	v_mfma_f32_16x16x32_bf16 v[60:63], v[156:159], v[188:191], v[60:63]
	v_mfma_f32_16x16x32_bf16 v[56:59], v[164:167], v[188:191], v[56:59]
	v_mfma_f32_16x16x32_bf16 v[44:47], v[156:159], v[196:199], v[44:47]
	v_mfma_f32_16x16x32_bf16 v[40:43], v[164:167], v[196:199], v[40:43]
	v_mfma_f32_16x16x32_bf16 v[28:31], v[156:159], v[204:207], v[28:31]
	v_mfma_f32_16x16x32_bf16 v[24:27], v[164:167], v[204:207], v[24:27]
	v_mfma_f32_16x16x32_bf16 v[12:15], v[156:159], v[212:215], v[12:15]
	v_mfma_f32_16x16x32_bf16 v[8:11], v[164:167], v[212:215], v[8:11]
	s_setprio 0
	s_setprio 1
	v_mfma_f32_16x16x32_bf16 v[52:55], v[168:171], v[184:187], v[52:55]
	v_mfma_f32_16x16x32_bf16 v[48:51], v[176:179], v[184:187], v[48:51]
	v_mfma_f32_16x16x32_bf16 v[36:39], v[168:171], v[192:195], v[36:39]
	v_mfma_f32_16x16x32_bf16 v[32:35], v[176:179], v[192:195], v[32:35]
	v_mfma_f32_16x16x32_bf16 v[20:23], v[168:171], v[200:203], v[20:23]
	v_mfma_f32_16x16x32_bf16 v[16:19], v[176:179], v[200:203], v[16:19]
	v_mfma_f32_16x16x32_bf16 v[4:7], v[168:171], v[208:211], v[4:7]
	v_mfma_f32_16x16x32_bf16 v[0:3], v[176:179], v[208:211], v[0:3]
	v_mfma_f32_16x16x32_bf16 v[52:55], v[172:175], v[188:191], v[52:55]
	v_mfma_f32_16x16x32_bf16 v[48:51], v[180:183], v[188:191], v[48:51]
	v_mfma_f32_16x16x32_bf16 v[36:39], v[172:175], v[196:199], v[36:39]
	v_mfma_f32_16x16x32_bf16 v[32:35], v[180:183], v[196:199], v[32:35]
	v_mfma_f32_16x16x32_bf16 v[20:23], v[172:175], v[204:207], v[20:23]
	v_mfma_f32_16x16x32_bf16 v[16:19], v[180:183], v[204:207], v[16:19]
	v_mfma_f32_16x16x32_bf16 v[4:7], v[172:175], v[212:215], v[4:7]
	v_mfma_f32_16x16x32_bf16 v[0:3], v[180:183], v[212:215], v[0:3]
	s_setprio 0
	s_barrier
	s_add_i32 s67, 0, 0x18000
	v_add_u32_e32 v155, s67, v149
	s_add_i32 s68, 0, 0x1c000
	ds_read_b128 v[144:147], v155
	ds_read_b128 v[156:159], v155 offset:1024
	ds_read_b128 v[160:163], v155 offset:2048
	ds_read_b128 v[164:167], v155 offset:3072
	v_add_u32_e32 v155, s68, v149
	ds_read_b128 v[168:171], v155
	ds_read_b128 v[172:175], v155 offset:1024
	ds_read_b128 v[176:179], v155 offset:2048
	ds_read_b128 v[180:183], v155 offset:3072
	s_add_u32 s30, s48, 0x160000
	s_addc_u32 s31, s49, 0
	s_mov_b32 m0, s55
	v_lshl_add_u64 v[224:225], s[30:31], 0, v[128:129]
	ds_read_b128 v[184:187], v153 offset:32768
	ds_read_b128 v[188:191], v153 offset:33792
	ds_read_b128 v[192:195], v153 offset:34816
	ds_read_b128 v[196:199], v153 offset:35840
	ds_read_b128 v[200:203], v153 offset:36864
	ds_read_b128 v[204:207], v153 offset:37888
	ds_read_b128 v[208:211], v153 offset:38912
	ds_read_b128 v[212:215], v153 offset:39936
	global_load_lds_dwordx4 v[224:225], off
	v_lshl_add_u64 v[224:225], s[30:31], 0, v[132:133]
	s_mov_b32 m0, s56
	s_nop 0
	global_load_lds_dwordx4 v[224:225], off
	s_waitcnt vmcnt(8)
	s_waitcnt lgkmcnt(0)
	s_barrier
	s_setprio 1
	v_mfma_f32_16x16x32_bf16 v[124:127], v[144:147], v[184:187], v[124:127]
	v_mfma_f32_16x16x32_bf16 v[120:123], v[160:163], v[184:187], v[120:123]
	v_mfma_f32_16x16x32_bf16 v[108:111], v[144:147], v[192:195], v[108:111]
	v_mfma_f32_16x16x32_bf16 v[104:107], v[160:163], v[192:195], v[104:107]
	v_mfma_f32_16x16x32_bf16 v[92:95], v[144:147], v[200:203], v[92:95]
	v_mfma_f32_16x16x32_bf16 v[88:91], v[160:163], v[200:203], v[88:91]
	v_mfma_f32_16x16x32_bf16 v[76:79], v[144:147], v[208:211], v[76:79]
	v_mfma_f32_16x16x32_bf16 v[72:75], v[160:163], v[208:211], v[72:75]
	v_mfma_f32_16x16x32_bf16 v[124:127], v[156:159], v[188:191], v[124:127]
	v_mfma_f32_16x16x32_bf16 v[120:123], v[164:167], v[188:191], v[120:123]
	v_mfma_f32_16x16x32_bf16 v[108:111], v[156:159], v[196:199], v[108:111]
	v_mfma_f32_16x16x32_bf16 v[104:107], v[164:167], v[196:199], v[104:107]
	v_mfma_f32_16x16x32_bf16 v[92:95], v[156:159], v[204:207], v[92:95]
	v_mfma_f32_16x16x32_bf16 v[88:91], v[164:167], v[204:207], v[88:91]
	v_mfma_f32_16x16x32_bf16 v[76:79], v[156:159], v[212:215], v[76:79]
	v_mfma_f32_16x16x32_bf16 v[72:75], v[164:167], v[212:215], v[72:75]
	s_setprio 0
	s_setprio 1
	v_mfma_f32_16x16x32_bf16 v[116:119], v[168:171], v[184:187], v[116:119]
	v_mfma_f32_16x16x32_bf16 v[112:115], v[176:179], v[184:187], v[112:115]
	v_mfma_f32_16x16x32_bf16 v[100:103], v[168:171], v[192:195], v[100:103]
	v_mfma_f32_16x16x32_bf16 v[96:99], v[176:179], v[192:195], v[96:99]
	v_mfma_f32_16x16x32_bf16 v[84:87], v[168:171], v[200:203], v[84:87]
	v_mfma_f32_16x16x32_bf16 v[80:83], v[176:179], v[200:203], v[80:83]
	v_mfma_f32_16x16x32_bf16 v[68:71], v[168:171], v[208:211], v[68:71]
	v_mfma_f32_16x16x32_bf16 v[64:67], v[176:179], v[208:211], v[64:67]
	v_mfma_f32_16x16x32_bf16 v[116:119], v[172:175], v[188:191], v[116:119]
	v_mfma_f32_16x16x32_bf16 v[112:115], v[180:183], v[188:191], v[112:115]
	v_mfma_f32_16x16x32_bf16 v[100:103], v[172:175], v[196:199], v[100:103]
	v_mfma_f32_16x16x32_bf16 v[96:99], v[180:183], v[196:199], v[96:99]
	v_mfma_f32_16x16x32_bf16 v[84:87], v[172:175], v[204:207], v[84:87]
	v_mfma_f32_16x16x32_bf16 v[80:83], v[180:183], v[204:207], v[80:83]
	v_mfma_f32_16x16x32_bf16 v[68:71], v[172:175], v[212:215], v[68:71]
	v_mfma_f32_16x16x32_bf16 v[64:67], v[180:183], v[212:215], v[64:67]
	s_setprio 0
	s_barrier
	s_add_i32 s30, s67, s52
	v_lshl_add_u64 v[216:217], v[216:217], 0, s[22:23]
	s_mov_b32 m0, s30
	ds_read_b128 v[184:187], v153 offset:49152
	ds_read_b128 v[188:191], v153 offset:50176
	ds_read_b128 v[192:195], v153 offset:51200
	ds_read_b128 v[196:199], v153 offset:52224
	ds_read_b128 v[200:203], v153 offset:53248
	ds_read_b128 v[204:207], v153 offset:54272
	ds_read_b128 v[208:211], v153 offset:55296
	ds_read_b128 v[212:215], v153 offset:56320
	global_load_lds_dwordx4 v[216:217], off
	s_add_i32 m0, s30, 0x2000
	s_add_u32 s30, s36, 0x160080
	v_lshl_add_u64 v[216:217], v[218:219], 0, s[22:23]
	s_addc_u32 s31, s37, 0
	s_add_i32 s36, s68, s52
	global_load_lds_dwordx4 v[216:217], off
	v_lshl_add_u64 v[216:217], s[30:31], 0, v[130:131]
	s_mov_b32 m0, s36
	s_nop 0
	global_load_lds_dwordx4 v[216:217], off
	v_lshl_add_u64 v[216:217], s[30:31], 0, v[134:135]
	s_add_i32 m0, s36, 0x2000
	s_nop 0
	global_load_lds_dwordx4 v[216:217], off
	v_lshl_add_u64 v[216:217], v[220:221], 0, s[22:23]
	s_mov_b32 m0, s58
	s_nop 0
	global_load_lds_dwordx4 v[216:217], off
	v_lshl_add_u64 v[216:217], v[222:223], 0, s[22:23]
	s_mov_b32 m0, s59
	s_nop 0
	global_load_lds_dwordx4 v[216:217], off
	s_waitcnt vmcnt(8)
	s_waitcnt lgkmcnt(0)
	s_barrier
	s_setprio 1
	v_mfma_f32_16x16x32_bf16 v[60:63], v[144:147], v[184:187], v[60:63]
	v_mfma_f32_16x16x32_bf16 v[56:59], v[160:163], v[184:187], v[56:59]
	v_mfma_f32_16x16x32_bf16 v[44:47], v[144:147], v[192:195], v[44:47]
	v_mfma_f32_16x16x32_bf16 v[40:43], v[160:163], v[192:195], v[40:43]
	v_mfma_f32_16x16x32_bf16 v[28:31], v[144:147], v[200:203], v[28:31]
	v_mfma_f32_16x16x32_bf16 v[24:27], v[160:163], v[200:203], v[24:27]
	v_mfma_f32_16x16x32_bf16 v[12:15], v[144:147], v[208:211], v[12:15]
	v_mfma_f32_16x16x32_bf16 v[8:11], v[160:163], v[208:211], v[8:11]
	v_mfma_f32_16x16x32_bf16 v[60:63], v[156:159], v[188:191], v[60:63]
	v_mfma_f32_16x16x32_bf16 v[56:59], v[164:167], v[188:191], v[56:59]
	v_mfma_f32_16x16x32_bf16 v[44:47], v[156:159], v[196:199], v[44:47]
	v_mfma_f32_16x16x32_bf16 v[40:43], v[164:167], v[196:199], v[40:43]
	v_mfma_f32_16x16x32_bf16 v[28:31], v[156:159], v[204:207], v[28:31]
	v_mfma_f32_16x16x32_bf16 v[24:27], v[164:167], v[204:207], v[24:27]
	v_mfma_f32_16x16x32_bf16 v[12:15], v[156:159], v[212:215], v[12:15]
	v_mfma_f32_16x16x32_bf16 v[8:11], v[164:167], v[212:215], v[8:11]
	s_setprio 0
	s_setprio 1
	v_mfma_f32_16x16x32_bf16 v[52:55], v[168:171], v[184:187], v[52:55]
	v_mfma_f32_16x16x32_bf16 v[48:51], v[176:179], v[184:187], v[48:51]
	v_mfma_f32_16x16x32_bf16 v[36:39], v[168:171], v[192:195], v[36:39]
	v_mfma_f32_16x16x32_bf16 v[32:35], v[176:179], v[192:195], v[32:35]
	v_mfma_f32_16x16x32_bf16 v[20:23], v[168:171], v[200:203], v[20:23]
	v_mfma_f32_16x16x32_bf16 v[16:19], v[176:179], v[200:203], v[16:19]
	v_mfma_f32_16x16x32_bf16 v[4:7], v[168:171], v[208:211], v[4:7]
	v_mfma_f32_16x16x32_bf16 v[0:3], v[176:179], v[208:211], v[0:3]
	v_mfma_f32_16x16x32_bf16 v[52:55], v[172:175], v[188:191], v[52:55]
	v_mfma_f32_16x16x32_bf16 v[48:51], v[180:183], v[188:191], v[48:51]
	v_mfma_f32_16x16x32_bf16 v[36:39], v[172:175], v[196:199], v[36:39]
	v_mfma_f32_16x16x32_bf16 v[32:35], v[180:183], v[196:199], v[32:35]
	v_mfma_f32_16x16x32_bf16 v[20:23], v[172:175], v[204:207], v[20:23]
	v_mfma_f32_16x16x32_bf16 v[16:19], v[180:183], v[204:207], v[16:19]
	v_mfma_f32_16x16x32_bf16 v[4:7], v[172:175], v[212:215], v[4:7]
	v_mfma_f32_16x16x32_bf16 v[0:3], v[180:183], v[212:215], v[0:3]
	s_setprio 0
	s_barrier
	s_add_i32 s66, s66, 2
	s_add_u32 s46, s46, 0x100
	s_addc_u32 s47, s47, 0
	s_cmpk_gt_u32 s66, 0x55
	s_mov_b64 s[30:31], s[34:35]
	s_cbranch_scc0 .LBB0_1137
	s_and_b64 vcc, exec, s[24:25]
	s_cbranch_vccz .LBB0_1140
	s_barrier

.LBB0_1227:
	v_add_u32_e32 v164, s56, v150
	v_add_u32_e32 v180, s57, v150
	s_add_u32 s34, s16, s30
	ds_read_b128 v[152:155], v164
	ds_read_b128 v[156:159], v164 offset:1024
	ds_read_b128 v[160:163], v164 offset:2048
	ds_read_b128 v[164:167], v164 offset:3072
	ds_read_b128 v[168:171], v180
	ds_read_b128 v[172:175], v180 offset:1024
	ds_read_b128 v[176:179], v180 offset:2048
	ds_read_b128 v[180:183], v180 offset:3072
	s_addc_u32 s35, s17, s31
	s_add_u32 s34, s34, 0x100
	s_addc_u32 s35, s35, 0
	s_add_u32 s64, s59, s30
	s_addc_u32 s65, s60, s31
	s_cmpk_eq_i32 s30, 0xf00
	s_cselect_b32 s37, s23, s35
	s_cselect_b32 s36, s61, s34
	s_cselect_b32 s35, s21, s65
	s_cselect_b32 s34, s62, s64
	v_lshl_add_u64 v[216:217], v[146:147], 0, s[30:31]
	s_add_i32 m0, s48, 0xc000
	ds_read_b128 v[184:187], v151
	ds_read_b128 v[188:191], v151 offset:1024
	ds_read_b128 v[192:195], v151 offset:2048
	ds_read_b128 v[196:199], v151 offset:3072
	ds_read_b128 v[200:203], v151 offset:4096
	ds_read_b128 v[204:207], v151 offset:5120
	ds_read_b128 v[208:211], v151 offset:6144
	ds_read_b128 v[212:215], v151 offset:7168
	global_load_lds_dwordx4 v[216:217], off
	v_lshl_add_u64 v[216:217], v[144:145], 0, s[30:31]
	s_add_i32 m0, s48, 0xe000
	s_nop 0
	global_load_lds_dwordx4 v[216:217], off
	s_waitcnt vmcnt(8)
	s_waitcnt lgkmcnt(0)
	s_barrier
	s_setprio 1
	v_mfma_f32_16x16x32_bf16 v[124:127], v[152:155], v[184:187], v[124:127]
	v_mfma_f32_16x16x32_bf16 v[120:123], v[160:163], v[184:187], v[120:123]
	v_mfma_f32_16x16x32_bf16 v[108:111], v[152:155], v[192:195], v[108:111]
	v_mfma_f32_16x16x32_bf16 v[104:107], v[160:163], v[192:195], v[104:107]
	v_mfma_f32_16x16x32_bf16 v[92:95], v[152:155], v[200:203], v[92:95]
	v_mfma_f32_16x16x32_bf16 v[88:91], v[160:163], v[200:203], v[88:91]
	v_mfma_f32_16x16x32_bf16 v[76:79], v[152:155], v[208:211], v[76:79]
	v_mfma_f32_16x16x32_bf16 v[72:75], v[160:163], v[208:211], v[72:75]
	v_mfma_f32_16x16x32_bf16 v[124:127], v[156:159], v[188:191], v[124:127]
	v_mfma_f32_16x16x32_bf16 v[120:123], v[164:167], v[188:191], v[120:123]
	v_mfma_f32_16x16x32_bf16 v[108:111], v[156:159], v[196:199], v[108:111]
	v_mfma_f32_16x16x32_bf16 v[104:107], v[164:167], v[196:199], v[104:107]
	v_mfma_f32_16x16x32_bf16 v[92:95], v[156:159], v[204:207], v[92:95]
	v_mfma_f32_16x16x32_bf16 v[88:91], v[164:167], v[204:207], v[88:91]
	v_mfma_f32_16x16x32_bf16 v[76:79], v[156:159], v[212:215], v[76:79]
	v_mfma_f32_16x16x32_bf16 v[72:75], v[164:167], v[212:215], v[72:75]
	s_setprio 0
	s_setprio 1
	v_mfma_f32_16x16x32_bf16 v[116:119], v[168:171], v[184:187], v[116:119]
	v_mfma_f32_16x16x32_bf16 v[112:115], v[176:179], v[184:187], v[112:115]
	v_mfma_f32_16x16x32_bf16 v[100:103], v[168:171], v[192:195], v[100:103]
	v_mfma_f32_16x16x32_bf16 v[96:99], v[176:179], v[192:195], v[96:99]
	v_mfma_f32_16x16x32_bf16 v[84:87], v[168:171], v[200:203], v[84:87]
	v_mfma_f32_16x16x32_bf16 v[80:83], v[176:179], v[200:203], v[80:83]
	v_mfma_f32_16x16x32_bf16 v[68:71], v[168:171], v[208:211], v[68:71]
	v_mfma_f32_16x16x32_bf16 v[64:67], v[176:179], v[208:211], v[64:67]
	v_mfma_f32_16x16x32_bf16 v[116:119], v[172:175], v[188:191], v[116:119]
	v_mfma_f32_16x16x32_bf16 v[112:115], v[180:183], v[188:191], v[112:115]
	v_mfma_f32_16x16x32_bf16 v[100:103], v[172:175], v[196:199], v[100:103]
	v_mfma_f32_16x16x32_bf16 v[96:99], v[180:183], v[196:199], v[96:99]
	v_mfma_f32_16x16x32_bf16 v[84:87], v[172:175], v[204:207], v[84:87]
	v_mfma_f32_16x16x32_bf16 v[80:83], v[180:183], v[204:207], v[80:83]
	v_mfma_f32_16x16x32_bf16 v[68:71], v[172:175], v[212:215], v[68:71]
	v_mfma_f32_16x16x32_bf16 v[64:67], v[180:183], v[212:215], v[64:67]
	s_setprio 0
	s_barrier
	s_add_i32 s64, s56, s47
	v_lshl_add_u64 v[216:217], s[34:35], 0, v[130:131]
	s_mov_b32 m0, s64
	ds_read_b128 v[184:187], v151 offset:16384
	ds_read_b128 v[188:191], v151 offset:17408
	ds_read_b128 v[192:195], v151 offset:18432
	ds_read_b128 v[196:199], v151 offset:19456
	ds_read_b128 v[200:203], v151 offset:20480
	ds_read_b128 v[204:207], v151 offset:21504
	ds_read_b128 v[208:211], v151 offset:22528
	ds_read_b128 v[212:215], v151 offset:23552
	global_load_lds_dwordx4 v[216:217], off
	s_add_i32 m0, s64, 0x2000
	s_add_u32 s64, s34, 0x80000
	v_lshl_add_u64 v[218:219], s[34:35], 0, v[134:135]
	s_addc_u32 s65, s35, 0
	s_add_i32 s66, s57, s47
	global_load_lds_dwordx4 v[218:219], off
	v_lshl_add_u64 v[220:221], s[64:65], 0, v[130:131]
	s_mov_b32 m0, s66
	v_lshl_add_u64 v[222:223], s[36:37], 0, v[132:133]
	global_load_lds_dwordx4 v[220:221], off
	v_lshl_add_u64 v[220:221], s[64:65], 0, v[134:135]
	s_add_i32 m0, s66, 0x2000
	s_nop 0
	global_load_lds_dwordx4 v[220:221], off
	v_lshl_add_u64 v[220:221], s[36:37], 0, v[128:129]
	s_mov_b32 m0, s48
	s_nop 0
	global_load_lds_dwordx4 v[220:221], off
	s_mov_b32 m0, s49
	s_nop 0
	global_load_lds_dwordx4 v[222:223], off
	s_waitcnt vmcnt(8)
	s_waitcnt lgkmcnt(0)
	s_barrier
	s_setprio 1
	v_mfma_f32_16x16x32_bf16 v[60:63], v[152:155], v[184:187], v[60:63]
	v_mfma_f32_16x16x32_bf16 v[56:59], v[160:163], v[184:187], v[56:59]
	v_mfma_f32_16x16x32_bf16 v[44:47], v[152:155], v[192:195], v[44:47]
	v_mfma_f32_16x16x32_bf16 v[40:43], v[160:163], v[192:195], v[40:43]
	v_mfma_f32_16x16x32_bf16 v[28:31], v[152:155], v[200:203], v[28:31]
	v_mfma_f32_16x16x32_bf16 v[24:27], v[160:163], v[200:203], v[24:27]
	v_mfma_f32_16x16x32_bf16 v[12:15], v[152:155], v[208:211], v[12:15]
	v_mfma_f32_16x16x32_bf16 v[8:11], v[160:163], v[208:211], v[8:11]
	v_mfma_f32_16x16x32_bf16 v[60:63], v[156:159], v[188:191], v[60:63]
	v_mfma_f32_16x16x32_bf16 v[56:59], v[164:167], v[188:191], v[56:59]
	v_mfma_f32_16x16x32_bf16 v[44:47], v[156:159], v[196:199], v[44:47]
	v_mfma_f32_16x16x32_bf16 v[40:43], v[164:167], v[196:199], v[40:43]
	v_mfma_f32_16x16x32_bf16 v[28:31], v[156:159], v[204:207], v[28:31]
	v_mfma_f32_16x16x32_bf16 v[24:27], v[164:167], v[204:207], v[24:27]
	v_mfma_f32_16x16x32_bf16 v[12:15], v[156:159], v[212:215], v[12:15]
	v_mfma_f32_16x16x32_bf16 v[8:11], v[164:167], v[212:215], v[8:11]
	s_setprio 0
	s_setprio 1
	v_mfma_f32_16x16x32_bf16 v[52:55], v[168:171], v[184:187], v[52:55]
	v_mfma_f32_16x16x32_bf16 v[48:51], v[176:179], v[184:187], v[48:51]
	v_mfma_f32_16x16x32_bf16 v[36:39], v[168:171], v[192:195], v[36:39]
	v_mfma_f32_16x16x32_bf16 v[32:35], v[176:179], v[192:195], v[32:35]
	v_mfma_f32_16x16x32_bf16 v[20:23], v[168:171], v[200:203], v[20:23]
	v_mfma_f32_16x16x32_bf16 v[16:19], v[176:179], v[200:203], v[16:19]
	v_mfma_f32_16x16x32_bf16 v[4:7], v[168:171], v[208:211], v[4:7]
	v_mfma_f32_16x16x32_bf16 v[0:3], v[176:179], v[208:211], v[0:3]
	v_mfma_f32_16x16x32_bf16 v[52:55], v[172:175], v[188:191], v[52:55]
	v_mfma_f32_16x16x32_bf16 v[48:51], v[180:183], v[188:191], v[48:51]
	v_mfma_f32_16x16x32_bf16 v[36:39], v[172:175], v[196:199], v[36:39]
	v_mfma_f32_16x16x32_bf16 v[32:35], v[180:183], v[196:199], v[32:35]
	v_mfma_f32_16x16x32_bf16 v[20:23], v[172:175], v[204:207], v[20:23]
	v_mfma_f32_16x16x32_bf16 v[16:19], v[180:183], v[204:207], v[16:19]
	v_mfma_f32_16x16x32_bf16 v[4:7], v[172:175], v[212:215], v[4:7]
	v_mfma_f32_16x16x32_bf16 v[0:3], v[180:183], v[212:215], v[0:3]
	s_setprio 0
	s_barrier
	s_add_i32 s64, 0, 0x18000
	s_add_i32 s65, 0, 0x1c000
	v_add_u32_e32 v164, s64, v150
	v_add_u32_e32 v180, s65, v150
	ds_read_b128 v[152:155], v164
	ds_read_b128 v[156:159], v164 offset:1024
	ds_read_b128 v[160:163], v164 offset:2048
	ds_read_b128 v[164:167], v164 offset:3072
	ds_read_b128 v[168:171], v180
	ds_read_b128 v[172:175], v180 offset:1024
	ds_read_b128 v[176:179], v180 offset:2048
	ds_read_b128 v[180:183], v180 offset:3072
	s_add_u32 s36, s36, 0x80000
	s_addc_u32 s37, s37, 0
	s_mov_b32 m0, s50
	v_lshl_add_u64 v[224:225], s[36:37], 0, v[128:129]
	ds_read_b128 v[184:187], v151 offset:32768
	ds_read_b128 v[188:191], v151 offset:33792
	ds_read_b128 v[192:195], v151 offset:34816
	ds_read_b128 v[196:199], v151 offset:35840
	ds_read_b128 v[200:203], v151 offset:36864
	ds_read_b128 v[204:207], v151 offset:37888
	ds_read_b128 v[208:211], v151 offset:38912
	ds_read_b128 v[212:215], v151 offset:39936
	global_load_lds_dwordx4 v[224:225], off
	v_lshl_add_u64 v[224:225], s[36:37], 0, v[132:133]
	s_mov_b32 m0, s51
	s_nop 0
	global_load_lds_dwordx4 v[224:225], off
	s_waitcnt vmcnt(8)
	s_waitcnt lgkmcnt(0)
	s_barrier
	s_setprio 1
	v_mfma_f32_16x16x32_bf16 v[124:127], v[152:155], v[184:187], v[124:127]
	v_mfma_f32_16x16x32_bf16 v[120:123], v[160:163], v[184:187], v[120:123]
	v_mfma_f32_16x16x32_bf16 v[108:111], v[152:155], v[192:195], v[108:111]
	v_mfma_f32_16x16x32_bf16 v[104:107], v[160:163], v[192:195], v[104:107]
	v_mfma_f32_16x16x32_bf16 v[92:95], v[152:155], v[200:203], v[92:95]
	v_mfma_f32_16x16x32_bf16 v[88:91], v[160:163], v[200:203], v[88:91]
	v_mfma_f32_16x16x32_bf16 v[76:79], v[152:155], v[208:211], v[76:79]
	v_mfma_f32_16x16x32_bf16 v[72:75], v[160:163], v[208:211], v[72:75]
	v_mfma_f32_16x16x32_bf16 v[124:127], v[156:159], v[188:191], v[124:127]
	v_mfma_f32_16x16x32_bf16 v[120:123], v[164:167], v[188:191], v[120:123]
	v_mfma_f32_16x16x32_bf16 v[108:111], v[156:159], v[196:199], v[108:111]
	v_mfma_f32_16x16x32_bf16 v[104:107], v[164:167], v[196:199], v[104:107]
	v_mfma_f32_16x16x32_bf16 v[92:95], v[156:159], v[204:207], v[92:95]
	v_mfma_f32_16x16x32_bf16 v[88:91], v[164:167], v[204:207], v[88:91]
	v_mfma_f32_16x16x32_bf16 v[76:79], v[156:159], v[212:215], v[76:79]
	v_mfma_f32_16x16x32_bf16 v[72:75], v[164:167], v[212:215], v[72:75]
	s_setprio 0
	s_setprio 1
	v_mfma_f32_16x16x32_bf16 v[116:119], v[168:171], v[184:187], v[116:119]
	v_mfma_f32_16x16x32_bf16 v[112:115], v[176:179], v[184:187], v[112:115]
	v_mfma_f32_16x16x32_bf16 v[100:103], v[168:171], v[192:195], v[100:103]
	v_mfma_f32_16x16x32_bf16 v[96:99], v[176:179], v[192:195], v[96:99]
	v_mfma_f32_16x16x32_bf16 v[84:87], v[168:171], v[200:203], v[84:87]
	v_mfma_f32_16x16x32_bf16 v[80:83], v[176:179], v[200:203], v[80:83]
	v_mfma_f32_16x16x32_bf16 v[68:71], v[168:171], v[208:211], v[68:71]
	v_mfma_f32_16x16x32_bf16 v[64:67], v[176:179], v[208:211], v[64:67]
	v_mfma_f32_16x16x32_bf16 v[116:119], v[172:175], v[188:191], v[116:119]
	v_mfma_f32_16x16x32_bf16 v[112:115], v[180:183], v[188:191], v[112:115]
	v_mfma_f32_16x16x32_bf16 v[100:103], v[172:175], v[196:199], v[100:103]
	v_mfma_f32_16x16x32_bf16 v[96:99], v[180:183], v[196:199], v[96:99]
	v_mfma_f32_16x16x32_bf16 v[84:87], v[172:175], v[204:207], v[84:87]
	v_mfma_f32_16x16x32_bf16 v[80:83], v[180:183], v[204:207], v[80:83]
	v_mfma_f32_16x16x32_bf16 v[68:71], v[172:175], v[212:215], v[68:71]
	v_mfma_f32_16x16x32_bf16 v[64:67], v[180:183], v[212:215], v[64:67]
	s_setprio 0
	s_barrier
	s_add_i32 s36, s64, s47
	v_lshl_add_u64 v[216:217], v[216:217], 0, s[18:19]
	s_mov_b32 m0, s36
	ds_read_b128 v[184:187], v151 offset:49152
	ds_read_b128 v[188:191], v151 offset:50176
	ds_read_b128 v[192:195], v151 offset:51200
	ds_read_b128 v[196:199], v151 offset:52224
	ds_read_b128 v[200:203], v151 offset:53248
	ds_read_b128 v[204:207], v151 offset:54272
	ds_read_b128 v[208:211], v151 offset:55296
	ds_read_b128 v[212:215], v151 offset:56320
	global_load_lds_dwordx4 v[216:217], off
	s_add_i32 m0, s36, 0x2000
	s_add_u32 s34, s34, 0x80080
	v_lshl_add_u64 v[216:217], v[218:219], 0, s[18:19]
	s_addc_u32 s35, s35, 0
	s_add_i32 s36, s65, s47
	global_load_lds_dwordx4 v[216:217], off
	v_lshl_add_u64 v[216:217], s[34:35], 0, v[130:131]
	s_mov_b32 m0, s36
	s_nop 0
	global_load_lds_dwordx4 v[216:217], off
	v_lshl_add_u64 v[216:217], s[34:35], 0, v[134:135]
	s_add_i32 m0, s36, 0x2000
	s_nop 0
	global_load_lds_dwordx4 v[216:217], off
	v_lshl_add_u64 v[216:217], v[220:221], 0, s[18:19]
	s_mov_b32 m0, s54
	s_nop 0
	global_load_lds_dwordx4 v[216:217], off
	v_lshl_add_u64 v[216:217], v[222:223], 0, s[18:19]
	s_mov_b32 m0, s55
	s_nop 0
	global_load_lds_dwordx4 v[216:217], off
	s_waitcnt vmcnt(8)
	s_waitcnt lgkmcnt(0)
	s_barrier
	s_setprio 1
	v_mfma_f32_16x16x32_bf16 v[60:63], v[152:155], v[184:187], v[60:63]
	v_mfma_f32_16x16x32_bf16 v[56:59], v[160:163], v[184:187], v[56:59]
	v_mfma_f32_16x16x32_bf16 v[44:47], v[152:155], v[192:195], v[44:47]
	v_mfma_f32_16x16x32_bf16 v[40:43], v[160:163], v[192:195], v[40:43]
	v_mfma_f32_16x16x32_bf16 v[28:31], v[152:155], v[200:203], v[28:31]
	v_mfma_f32_16x16x32_bf16 v[24:27], v[160:163], v[200:203], v[24:27]
	v_mfma_f32_16x16x32_bf16 v[12:15], v[152:155], v[208:211], v[12:15]
	v_mfma_f32_16x16x32_bf16 v[8:11], v[160:163], v[208:211], v[8:11]
	v_mfma_f32_16x16x32_bf16 v[60:63], v[156:159], v[188:191], v[60:63]
	v_mfma_f32_16x16x32_bf16 v[56:59], v[164:167], v[188:191], v[56:59]
	v_mfma_f32_16x16x32_bf16 v[44:47], v[156:159], v[196:199], v[44:47]
	v_mfma_f32_16x16x32_bf16 v[40:43], v[164:167], v[196:199], v[40:43]
	v_mfma_f32_16x16x32_bf16 v[28:31], v[156:159], v[204:207], v[28:31]
	v_mfma_f32_16x16x32_bf16 v[24:27], v[164:167], v[204:207], v[24:27]
	v_mfma_f32_16x16x32_bf16 v[12:15], v[156:159], v[212:215], v[12:15]
	v_mfma_f32_16x16x32_bf16 v[8:11], v[164:167], v[212:215], v[8:11]
	s_setprio 0
	s_setprio 1
	v_mfma_f32_16x16x32_bf16 v[52:55], v[168:171], v[184:187], v[52:55]
	v_mfma_f32_16x16x32_bf16 v[48:51], v[176:179], v[184:187], v[48:51]
	v_mfma_f32_16x16x32_bf16 v[36:39], v[168:171], v[192:195], v[36:39]
	v_mfma_f32_16x16x32_bf16 v[32:35], v[176:179], v[192:195], v[32:35]
	v_mfma_f32_16x16x32_bf16 v[20:23], v[168:171], v[200:203], v[20:23]
	v_mfma_f32_16x16x32_bf16 v[16:19], v[176:179], v[200:203], v[16:19]
	v_mfma_f32_16x16x32_bf16 v[4:7], v[168:171], v[208:211], v[4:7]
	v_mfma_f32_16x16x32_bf16 v[0:3], v[176:179], v[208:211], v[0:3]
	v_mfma_f32_16x16x32_bf16 v[52:55], v[172:175], v[188:191], v[52:55]
	v_mfma_f32_16x16x32_bf16 v[48:51], v[180:183], v[188:191], v[48:51]
	v_mfma_f32_16x16x32_bf16 v[36:39], v[172:175], v[196:199], v[36:39]
	v_mfma_f32_16x16x32_bf16 v[32:35], v[180:183], v[196:199], v[32:35]
	v_mfma_f32_16x16x32_bf16 v[20:23], v[172:175], v[204:207], v[20:23]
	v_mfma_f32_16x16x32_bf16 v[16:19], v[180:183], v[204:207], v[16:19]
	v_mfma_f32_16x16x32_bf16 v[4:7], v[172:175], v[212:215], v[4:7]
	v_mfma_f32_16x16x32_bf16 v[0:3], v[180:183], v[212:215], v[0:3]
	s_setprio 0
	s_barrier
	s_add_i32 s63, s63, 2
	s_add_u32 s30, s30, 0x100
	s_addc_u32 s31, s31, 0
	s_cmp_gt_u32 s63, 29
	s_cbranch_scc0 .LBB0_1227
	s_add_u32 s30, s59, 0xffffff00
	s_addc_u32 s31, s60, -1
	s_andn2_b64 vcc, exec, s[4:5]
	s_cbranch_vccnz .LBB0_1230
	v_mov_b32_e32 v0, 0
	s_mov_b32 s15, s20
	s_mov_b32 s14, s22
	s_mov_b64 s[16:17], s[26:27]
	s_mov_b32 s53, s58
	v_mov_b32_e32 v1, v0
	v_mov_b32_e32 v2, v0
	v_mov_b32_e32 v3, v0
	v_mov_b32_e32 v4, v0
	v_mov_b32_e32 v5, v0
	v_mov_b32_e32 v6, v0
	v_mov_b32_e32 v7, v0
	v_mov_b32_e32 v16, v0
	v_mov_b32_e32 v17, v0
	v_mov_b32_e32 v18, v0
	v_mov_b32_e32 v19, v0
	v_mov_b32_e32 v20, v0
	v_mov_b32_e32 v21, v0
	v_mov_b32_e32 v22, v0
	v_mov_b32_e32 v23, v0
	v_mov_b32_e32 v32, v0
	v_mov_b32_e32 v33, v0
	v_mov_b32_e32 v34, v0
	v_mov_b32_e32 v35, v0
	v_mov_b32_e32 v36, v0
	v_mov_b32_e32 v37, v0
	v_mov_b32_e32 v38, v0
	v_mov_b32_e32 v39, v0
	v_mov_b32_e32 v48, v0
	v_mov_b32_e32 v49, v0
	v_mov_b32_e32 v50, v0
	v_mov_b32_e32 v51, v0
	v_mov_b32_e32 v52, v0
	v_mov_b32_e32 v53, v0
	v_mov_b32_e32 v54, v0
	v_mov_b32_e32 v55, v0
	v_mov_b32_e32 v8, v0
	v_mov_b32_e32 v9, v0
	v_mov_b32_e32 v10, v0
	v_mov_b32_e32 v11, v0
	v_mov_b32_e32 v12, v0
	v_mov_b32_e32 v13, v0
	v_mov_b32_e32 v14, v0
	v_mov_b32_e32 v15, v0
	v_mov_b32_e32 v24, v0
	v_mov_b32_e32 v25, v0
	v_mov_b32_e32 v26, v0
	v_mov_b32_e32 v27, v0
	v_mov_b32_e32 v28, v0
	v_mov_b32_e32 v29, v0
	v_mov_b32_e32 v30, v0
	v_mov_b32_e32 v31, v0
	v_mov_b32_e32 v40, v0
	v_mov_b32_e32 v41, v0
	v_mov_b32_e32 v42, v0
	v_mov_b32_e32 v43, v0
	v_mov_b32_e32 v44, v0
	v_mov_b32_e32 v45, v0
	v_mov_b32_e32 v46, v0
	v_mov_b32_e32 v47, v0
	v_mov_b32_e32 v56, v0
	v_mov_b32_e32 v57, v0
	v_mov_b32_e32 v58, v0
	v_mov_b32_e32 v59, v0
	v_mov_b32_e32 v60, v0
	v_mov_b32_e32 v61, v0
	v_mov_b32_e32 v62, v0
	v_mov_b32_e32 v63, v0
	v_mov_b32_e32 v64, v0
	v_mov_b32_e32 v65, v0
	v_mov_b32_e32 v66, v0
	v_mov_b32_e32 v67, v0
	v_mov_b32_e32 v68, v0
	v_mov_b32_e32 v69, v0
	v_mov_b32_e32 v70, v0
	v_mov_b32_e32 v71, v0
	v_mov_b32_e32 v80, v0
	v_mov_b32_e32 v81, v0
	v_mov_b32_e32 v82, v0
	v_mov_b32_e32 v83, v0
	v_mov_b32_e32 v84, v0
	v_mov_b32_e32 v85, v0
	v_mov_b32_e32 v86, v0
	v_mov_b32_e32 v87, v0
	v_mov_b32_e32 v96, v0
	v_mov_b32_e32 v97, v0
	v_mov_b32_e32 v98, v0
	v_mov_b32_e32 v99, v0
	v_mov_b32_e32 v100, v0
	v_mov_b32_e32 v101, v0
	v_mov_b32_e32 v102, v0
	v_mov_b32_e32 v103, v0
	v_mov_b32_e32 v112, v0
	v_mov_b32_e32 v113, v0
	v_mov_b32_e32 v114, v0
	v_mov_b32_e32 v115, v0
	v_mov_b32_e32 v116, v0
	v_mov_b32_e32 v117, v0
	v_mov_b32_e32 v118, v0
	v_mov_b32_e32 v119, v0
	v_mov_b32_e32 v72, v0
	v_mov_b32_e32 v73, v0
	v_mov_b32_e32 v74, v0
	v_mov_b32_e32 v75, v0
	v_mov_b32_e32 v76, v0
	v_mov_b32_e32 v77, v0
	v_mov_b32_e32 v78, v0
	v_mov_b32_e32 v79, v0
	v_mov_b32_e32 v88, v0
	v_mov_b32_e32 v89, v0
	v_mov_b32_e32 v90, v0
	v_mov_b32_e32 v91, v0
	v_mov_b32_e32 v92, v0
	v_mov_b32_e32 v93, v0
	v_mov_b32_e32 v94, v0
	v_mov_b32_e32 v95, v0
	v_mov_b32_e32 v104, v0
	v_mov_b32_e32 v105, v0
	v_mov_b32_e32 v106, v0
	v_mov_b32_e32 v107, v0
	v_mov_b32_e32 v108, v0
	v_mov_b32_e32 v109, v0
	v_mov_b32_e32 v110, v0
	v_mov_b32_e32 v111, v0
	v_mov_b32_e32 v120, v0
	v_mov_b32_e32 v121, v0
	v_mov_b32_e32 v122, v0
	v_mov_b32_e32 v123, v0
	v_mov_b32_e32 v124, v0
	v_mov_b32_e32 v125, v0
	v_mov_b32_e32 v126, v0
	v_mov_b32_e32 v127, v0
	s_andn2_b64 vcc, exec, s[0:1]
	s_cbranch_vccnz .LBB0_1231
	s_branch .LBB0_1232
